# PH9: tile-1 DMA issued with tile 0, last MFMA group deferred past the buffer-release barrier; PH2/6/8 tile-1 DMA issued with tile 0
# speedup vs baseline: 1.0369x; 1.0109x over previous
.LBB0_232:
	s_mul_hi_i32 s2, s8, 0x66666667
	s_lshr_b32 s3, s2, 31
	s_ashr_i32 s2, s2, 3
	s_add_i32 s34, s2, s3
	s_ashr_i32 s35, s34, 31
	v_readlane_b32 s36, v210, 50
	v_mov_b32_e32 v36, v133
	s_lshl_b64 s[2:3], s[34:35], 18
	v_readlane_b32 s38, v210, 52
	v_readlane_b32 s39, v210, 53
	v_ashrrev_i32_e32 v34, 3, v36
	s_add_u32 s2, s38, s2
	v_ashrrev_i32_e32 v35, 31, v34
	s_addc_u32 s3, s39, s3
	v_lshlrev_b64 v[2:3], 11, v[34:35]
	s_waitcnt vmcnt(0)
	v_lshlrev_b32_e32 v0, 4, v36
	v_lshl_add_u64 v[2:3], s[2:3], 0, v[2:3]
	v_and_b32_e32 v0, 0x70, v0
	s_mul_i32 s2, s34, 0xa00
	v_lshl_add_u64 v[66:67], v[2:3], 0, v[0:1]
	v_subrev_u32_e32 v2, s2, v34
	v_add_u32_e32 v2, s7, v2
	v_ashrrev_i32_e32 v3, 31, v2
	v_lshlrev_b64 v[2:3], 11, v[2:3]
	v_lshl_add_u64 v[2:3], s[0:1], 0, v[2:3]
	v_add_co_u32_e32 v70, vcc, s56, v66
	v_lshl_add_u64 v[68:69], v[2:3], 0, v[0:1]
	s_nop 0
	v_addc_co_u32_e32 v71, vcc, 0, v67, vcc
	v_add_co_u32_e32 v72, vcc, s56, v68
	v_addc_co_u32_e32 v73, vcc, 0, v69, vcc
	v_add_co_u32_e32 v74, vcc, s57, v66
	s_nop 0
	v_addc_co_u32_e32 v75, vcc, 0, v67, vcc
	v_add_co_u32_e32 v76, vcc, s57, v68
	s_nop 0
	v_addc_co_u32_e32 v77, vcc, 0, v69, vcc
	v_add_co_u32_e32 v78, vcc, s58, v66
	s_nop 0
	v_addc_co_u32_e32 v79, vcc, 0, v67, vcc
	v_add_co_u32_e32 v80, vcc, s58, v68
	v_lshlrev_b32_e32 v0, 7, v34
	s_nop 0
	v_addc_co_u32_e32 v81, vcc, 0, v69, vcc
	v_lshrrev_b32_e32 v216, 4, v133
	v_xor_b32_e32 v216, v216, v133
	v_and_b32_e32 v216, 7, v216
	v_lshlrev_b32_e32 v216, 4, v216
	v_mov_b32_e32 v217, 0x70
	v_lshrrev_b32_e32 v218, 6, v133
	v_lshlrev_b32_e32 v218, 10, v218
	s_nop 0
	v_readfirstlane_b32 s32, v218
	v_bfi_b32 v66, v217, v216, v66
	v_bfi_b32 v70, v217, v216, v70
	v_bfi_b32 v74, v217, v216, v74
	v_bfi_b32 v78, v217, v216, v78
	v_bfi_b32 v68, v217, v216, v68
	v_bfi_b32 v72, v217, v216, v72
	v_bfi_b32 v76, v217, v216, v76
	v_bfi_b32 v80, v217, v216, v80
	s_mov_b64 s[98:99], 0x80
	s_add_u32 m0, s32, 0x0
	s_nop 0
	global_load_lds_dwordx4 v[66:67], off
	s_add_u32 m0, s32, 0x1000
	s_nop 0
	global_load_lds_dwordx4 v[70:71], off
	s_add_u32 m0, s32, 0x2000
	s_nop 0
	global_load_lds_dwordx4 v[74:75], off
	s_add_u32 m0, s32, 0x3000
	s_nop 0
	global_load_lds_dwordx4 v[78:79], off
	s_add_u32 m0, s32, 0x8000
	s_nop 0
	global_load_lds_dwordx4 v[68:69], off
	s_add_u32 m0, s32, 0x9000
	s_nop 0
	global_load_lds_dwordx4 v[72:73], off
	s_add_u32 m0, s32, 0xa000
	s_nop 0
	global_load_lds_dwordx4 v[76:77], off
	s_add_u32 m0, s32, 0xb000
	s_nop 0
	global_load_lds_dwordx4 v[80:81], off
	v_lshl_add_u64 v[66:67], v[66:67], 0, s[98:99]
	v_lshl_add_u64 v[70:71], v[70:71], 0, s[98:99]
	v_lshl_add_u64 v[74:75], v[74:75], 0, s[98:99]
	v_lshl_add_u64 v[78:79], v[78:79], 0, s[98:99]
	v_lshl_add_u64 v[68:69], v[68:69], 0, s[98:99]
	v_lshl_add_u64 v[72:73], v[72:73], 0, s[98:99]
	v_lshl_add_u64 v[76:77], v[76:77], 0, s[98:99]
	v_lshl_add_u64 v[80:81], v[80:81], 0, s[98:99]
	s_add_u32 m0, s32, 0x4000
	s_nop 0
	global_load_lds_dwordx4 v[66:67], off
	s_add_u32 m0, s32, 0x5000
	s_nop 0
	global_load_lds_dwordx4 v[70:71], off
	s_add_u32 m0, s32, 0x6000
	s_nop 0
	global_load_lds_dwordx4 v[74:75], off
	s_add_u32 m0, s32, 0x7000
	s_nop 0
	global_load_lds_dwordx4 v[78:79], off
	s_add_u32 m0, s32, 0xc000
	s_nop 0
	global_load_lds_dwordx4 v[68:69], off
	s_add_u32 m0, s32, 0xd000
	s_nop 0
	global_load_lds_dwordx4 v[72:73], off
	s_add_u32 m0, s32, 0xe000
	s_nop 0
	global_load_lds_dwordx4 v[76:77], off
	s_add_u32 m0, s32, 0xf000
	s_nop 0
	global_load_lds_dwordx4 v[80:81], off
	v_lshrrev_b32_e32 v34, 1, v34
	v_xor_b32_e32 v34, v34, v36
	v_lshlrev_b32_e32 v34, 4, v34
	v_and_or_b32 v0, v34, s59, v0
	v_and_b32_e32 v84, 31, v36
	v_bfe_u32 v82, v36, 5, 1
	v_ashrrev_i32_e32 v83, 7, v36
	v_bfe_u32 v85, v36, 6, 1
	v_readlane_b32 s40, v210, 54
	v_readlane_b32 s41, v210, 55
	v_readlane_b32 s37, v210, 51
	v_readlane_b32 s42, v210, 56
	v_readlane_b32 s43, v210, 57
	v_readlane_b32 s44, v210, 58
	v_readlane_b32 s45, v210, 59
	v_readlane_b32 s46, v210, 60
	v_readlane_b32 s47, v210, 61
	v_readlane_b32 s48, v210, 62
	v_readlane_b32 s49, v210, 63
	v_readlane_b32 s50, v209, 0
	v_readlane_b32 s51, v209, 1
	v_lshl_add_u64 v[66:67], v[66:67], 0, s[98:99]
	v_lshl_add_u64 v[70:71], v[70:71], 0, s[98:99]
	v_lshl_add_u64 v[74:75], v[74:75], 0, s[98:99]
	v_lshl_add_u64 v[78:79], v[78:79], 0, s[98:99]
	v_lshl_add_u64 v[68:69], v[68:69], 0, s[98:99]
	v_lshl_add_u64 v[72:73], v[72:73], 0, s[98:99]
	v_lshl_add_u64 v[76:77], v[76:77], 0, s[98:99]
	v_lshl_add_u64 v[80:81], v[80:81], 0, s[98:99]
	s_waitcnt vmcnt(8)
	s_waitcnt lgkmcnt(0)
	s_barrier
	v_lshrrev_b32_e32 v4, 1, v36
	v_lshlrev_b32_e32 v2, 7, v84
	v_bitop3_b32 v4, v4, v82, 7 bitop3:0x6c
	v_lshl_or_b32 v3, v83, 13, v2
	v_bfe_u32 v5, v36, 1, 3
	v_lshlrev_b32_e32 v4, 4, v4
	v_lshl_or_b32 v2, v85, 13, v2
	v_or_b32_e32 v91, v3, v4
	v_or_b32_e32 v92, v2, v4
	v_bitop3_b32 v4, v82, v5, 2 bitop3:0x36
	v_lshlrev_b32_e32 v4, 4, v4
	v_or_b32_e32 v93, v3, v4
	v_or_b32_e32 v90, v2, v4
	v_bitop3_b32 v4, v82, v5, 4 bitop3:0x36
	v_lshlrev_b32_e32 v4, 4, v4
	v_or_b32_e32 v89, v3, v4
	v_or_b32_e32 v88, v2, v4
	v_bitop3_b32 v4, v82, v5, 6 bitop3:0x36
	v_lshlrev_b32_e32 v4, 4, v4
	v_or_b32_e32 v87, v3, v4
	v_or_b32_e32 v86, v2, v4
	ds_read_b128 v[2:5], v91
	ds_read_b128 v[6:9], v92 offset:32768
	ds_read_b128 v[10:13], v91 offset:4096
	ds_read_b128 v[14:17], v92 offset:36864
	ds_read_b128 v[162:165], v93
	ds_read_b128 v[166:169], v90 offset:32768
	ds_read_b128 v[182:185], v93 offset:4096
	ds_read_b128 v[186:189], v90 offset:36864
	s_waitcnt lgkmcnt(6)
	v_mfma_f32_32x32x16_bf16 v[50:65], v[2:5], v[6:9], 0
	s_waitcnt lgkmcnt(4)
	v_mfma_f32_32x32x16_bf16 v[34:49], v[2:5], v[14:17], 0
	v_mfma_f32_32x32x16_bf16 v[18:33], v[10:13], v[6:9], 0
	v_mfma_f32_32x32x16_bf16 v[2:17], v[10:13], v[14:17], 0
	ds_read_b128 v[190:193], v89
	ds_read_b128 v[194:197], v89 offset:4096
	ds_read_b128 v[198:201], v88 offset:32768
	ds_read_b128 v[202:205], v88 offset:36864
	s_waitcnt lgkmcnt(6)
	v_mfma_f32_32x32x16_bf16 v[50:65], v[162:165], v[166:169], v[50:65]
	s_waitcnt lgkmcnt(4)
	v_mfma_f32_32x32x16_bf16 v[34:49], v[162:165], v[186:189], v[34:49]
	v_mfma_f32_32x32x16_bf16 v[18:33], v[182:185], v[166:169], v[18:33]
	v_mfma_f32_32x32x16_bf16 v[2:17], v[182:185], v[186:189], v[2:17]
	ds_read_b128 v[162:165], v87
	ds_read_b128 v[166:169], v87 offset:4096
	ds_read_b128 v[182:185], v86 offset:32768
	ds_read_b128 v[186:189], v86 offset:36864
	s_waitcnt lgkmcnt(0)
	s_barrier
	s_add_u32 m0, s32, 0x0
	v_mfma_f32_32x32x16_bf16 v[50:65], v[190:193], v[198:201], v[50:65]
	global_load_lds_dwordx4 v[66:67], off
	s_add_u32 m0, s32, 0x1000
	v_mfma_f32_32x32x16_bf16 v[34:49], v[190:193], v[202:205], v[34:49]
	global_load_lds_dwordx4 v[70:71], off
	s_add_u32 m0, s32, 0x2000
	v_mfma_f32_32x32x16_bf16 v[18:33], v[194:197], v[198:201], v[18:33]
	global_load_lds_dwordx4 v[74:75], off
	s_add_u32 m0, s32, 0x3000
	v_mfma_f32_32x32x16_bf16 v[2:17], v[194:197], v[202:205], v[2:17]
	global_load_lds_dwordx4 v[78:79], off
	s_add_u32 m0, s32, 0x8000
	v_mfma_f32_32x32x16_bf16 v[50:65], v[162:165], v[182:185], v[50:65]
	global_load_lds_dwordx4 v[68:69], off
	s_add_u32 m0, s32, 0x9000
	v_mfma_f32_32x32x16_bf16 v[34:49], v[162:165], v[186:189], v[34:49]
	global_load_lds_dwordx4 v[72:73], off
	s_add_u32 m0, s32, 0xa000
	v_mfma_f32_32x32x16_bf16 v[18:33], v[166:169], v[182:185], v[18:33]
	global_load_lds_dwordx4 v[76:77], off
	s_add_u32 m0, s32, 0xb000
	v_mfma_f32_32x32x16_bf16 v[2:17], v[166:169], v[186:189], v[2:17]
	global_load_lds_dwordx4 v[80:81], off
	s_waitcnt vmcnt(8)
	s_barrier
	ds_read_b128 v[162:165], v91 offset:16384
	ds_read_b128 v[166:169], v92 offset:49152
	ds_read_b128 v[182:185], v91 offset:20480
	ds_read_b128 v[186:189], v92 offset:53248
	ds_read_b128 v[190:193], v93 offset:16384
	ds_read_b128 v[194:197], v90 offset:49152
	ds_read_b128 v[198:201], v93 offset:20480
	ds_read_b128 v[202:205], v90 offset:53248
	s_waitcnt lgkmcnt(6)
	v_mfma_f32_32x32x16_bf16 v[50:65], v[162:165], v[166:169], v[50:65]
	s_waitcnt lgkmcnt(4)
	v_mfma_f32_32x32x16_bf16 v[34:49], v[162:165], v[186:189], v[34:49]
	v_mfma_f32_32x32x16_bf16 v[18:33], v[182:185], v[166:169], v[18:33]
	v_mfma_f32_32x32x16_bf16 v[2:17], v[182:185], v[186:189], v[2:17]
	ds_read_b128 v[162:165], v89 offset:16384
	ds_read_b128 v[166:169], v89 offset:20480
	ds_read_b128 v[182:185], v88 offset:49152
	ds_read_b128 v[186:189], v88 offset:53248
	s_waitcnt lgkmcnt(6)
	v_mfma_f32_32x32x16_bf16 v[50:65], v[190:193], v[194:197], v[50:65]
	s_waitcnt lgkmcnt(4)
	v_mfma_f32_32x32x16_bf16 v[34:49], v[190:193], v[202:205], v[34:49]
	v_mfma_f32_32x32x16_bf16 v[18:33], v[198:201], v[194:197], v[18:33]
	v_mfma_f32_32x32x16_bf16 v[2:17], v[198:201], v[202:205], v[2:17]
	ds_read_b128 v[190:193], v87 offset:16384
	ds_read_b128 v[194:197], v87 offset:20480
	ds_read_b128 v[198:201], v86 offset:49152
	ds_read_b128 v[202:205], v86 offset:53248
	v_lshl_add_u64 v[66:67], v[66:67], 0, s[98:99]
	v_lshl_add_u64 v[70:71], v[70:71], 0, s[98:99]
	v_lshl_add_u64 v[74:75], v[74:75], 0, s[98:99]
	v_lshl_add_u64 v[78:79], v[78:79], 0, s[98:99]
	v_lshl_add_u64 v[68:69], v[68:69], 0, s[98:99]
	v_lshl_add_u64 v[72:73], v[72:73], 0, s[98:99]
	v_lshl_add_u64 v[76:77], v[76:77], 0, s[98:99]
	v_lshl_add_u64 v[80:81], v[80:81], 0, s[98:99]
	s_waitcnt lgkmcnt(0)
	s_barrier
	s_add_u32 m0, s32, 0x4000
	v_mfma_f32_32x32x16_bf16 v[50:65], v[162:165], v[182:185], v[50:65]
	global_load_lds_dwordx4 v[66:67], off
	s_add_u32 m0, s32, 0x5000
	v_mfma_f32_32x32x16_bf16 v[34:49], v[162:165], v[186:189], v[34:49]
	global_load_lds_dwordx4 v[70:71], off
	s_add_u32 m0, s32, 0x6000
	v_mfma_f32_32x32x16_bf16 v[18:33], v[166:169], v[182:185], v[18:33]
	global_load_lds_dwordx4 v[74:75], off
	s_add_u32 m0, s32, 0x7000
	v_mfma_f32_32x32x16_bf16 v[2:17], v[166:169], v[186:189], v[2:17]
	global_load_lds_dwordx4 v[78:79], off
	s_add_u32 m0, s32, 0xc000
	v_mfma_f32_32x32x16_bf16 v[50:65], v[190:193], v[198:201], v[50:65]
	global_load_lds_dwordx4 v[68:69], off
	s_add_u32 m0, s32, 0xd000
	v_mfma_f32_32x32x16_bf16 v[34:49], v[190:193], v[202:205], v[34:49]
	global_load_lds_dwordx4 v[72:73], off
	s_add_u32 m0, s32, 0xe000
	v_mfma_f32_32x32x16_bf16 v[18:33], v[194:197], v[198:201], v[18:33]
	global_load_lds_dwordx4 v[76:77], off
	s_add_u32 m0, s32, 0xf000
	v_mfma_f32_32x32x16_bf16 v[2:17], v[194:197], v[202:205], v[2:17]
	global_load_lds_dwordx4 v[80:81], off
	s_waitcnt vmcnt(8)
	s_barrier
	ds_read_b128 v[162:165], v91
	ds_read_b128 v[166:169], v92 offset:32768
	ds_read_b128 v[182:185], v91 offset:4096
	ds_read_b128 v[186:189], v92 offset:36864
	ds_read_b128 v[190:193], v93
	ds_read_b128 v[194:197], v90 offset:32768
	ds_read_b128 v[198:201], v93 offset:4096
	ds_read_b128 v[202:205], v90 offset:36864
	s_waitcnt lgkmcnt(6)
	v_mfma_f32_32x32x16_bf16 v[50:65], v[162:165], v[166:169], v[50:65]
	s_waitcnt lgkmcnt(4)
	v_mfma_f32_32x32x16_bf16 v[34:49], v[162:165], v[186:189], v[34:49]
	v_mfma_f32_32x32x16_bf16 v[18:33], v[182:185], v[166:169], v[18:33]
	v_mfma_f32_32x32x16_bf16 v[2:17], v[182:185], v[186:189], v[2:17]
	ds_read_b128 v[162:165], v89
	ds_read_b128 v[166:169], v89 offset:4096
	ds_read_b128 v[182:185], v88 offset:32768
	ds_read_b128 v[186:189], v88 offset:36864
	s_waitcnt lgkmcnt(6)
	v_mfma_f32_32x32x16_bf16 v[50:65], v[190:193], v[194:197], v[50:65]
	s_waitcnt lgkmcnt(4)
	v_mfma_f32_32x32x16_bf16 v[34:49], v[190:193], v[202:205], v[34:49]
	v_mfma_f32_32x32x16_bf16 v[18:33], v[198:201], v[194:197], v[18:33]
	v_mfma_f32_32x32x16_bf16 v[2:17], v[198:201], v[202:205], v[2:17]
	ds_read_b128 v[190:193], v87
	ds_read_b128 v[194:197], v87 offset:4096
	ds_read_b128 v[198:201], v86 offset:32768
	ds_read_b128 v[202:205], v86 offset:36864
	v_lshl_add_u64 v[66:67], v[66:67], 0, s[98:99]
	v_lshl_add_u64 v[70:71], v[70:71], 0, s[98:99]
	v_lshl_add_u64 v[74:75], v[74:75], 0, s[98:99]
	v_lshl_add_u64 v[78:79], v[78:79], 0, s[98:99]
	v_lshl_add_u64 v[68:69], v[68:69], 0, s[98:99]
	v_lshl_add_u64 v[72:73], v[72:73], 0, s[98:99]
	v_lshl_add_u64 v[76:77], v[76:77], 0, s[98:99]
	v_lshl_add_u64 v[80:81], v[80:81], 0, s[98:99]
	s_waitcnt lgkmcnt(0)
	s_barrier
	s_add_u32 m0, s32, 0x0
	v_mfma_f32_32x32x16_bf16 v[50:65], v[162:165], v[182:185], v[50:65]
	global_load_lds_dwordx4 v[66:67], off
	s_add_u32 m0, s32, 0x1000
	v_mfma_f32_32x32x16_bf16 v[34:49], v[162:165], v[186:189], v[34:49]
	global_load_lds_dwordx4 v[70:71], off
	s_add_u32 m0, s32, 0x2000
	v_mfma_f32_32x32x16_bf16 v[18:33], v[166:169], v[182:185], v[18:33]
	global_load_lds_dwordx4 v[74:75], off
	s_add_u32 m0, s32, 0x3000
	v_mfma_f32_32x32x16_bf16 v[2:17], v[166:169], v[186:189], v[2:17]
	global_load_lds_dwordx4 v[78:79], off
	s_add_u32 m0, s32, 0x8000
	v_mfma_f32_32x32x16_bf16 v[50:65], v[190:193], v[198:201], v[50:65]
	global_load_lds_dwordx4 v[68:69], off
	s_add_u32 m0, s32, 0x9000
	v_mfma_f32_32x32x16_bf16 v[34:49], v[190:193], v[202:205], v[34:49]
	global_load_lds_dwordx4 v[72:73], off
	s_add_u32 m0, s32, 0xa000
	v_mfma_f32_32x32x16_bf16 v[18:33], v[194:197], v[198:201], v[18:33]
	global_load_lds_dwordx4 v[76:77], off
	s_add_u32 m0, s32, 0xb000
	v_mfma_f32_32x32x16_bf16 v[2:17], v[194:197], v[202:205], v[2:17]
	global_load_lds_dwordx4 v[80:81], off
	s_waitcnt vmcnt(8)
	s_barrier
	ds_read_b128 v[162:165], v91 offset:16384
	ds_read_b128 v[166:169], v92 offset:49152
	ds_read_b128 v[182:185], v91 offset:20480
	ds_read_b128 v[186:189], v92 offset:53248
	ds_read_b128 v[190:193], v93 offset:16384
	ds_read_b128 v[194:197], v90 offset:49152
	ds_read_b128 v[198:201], v93 offset:20480
	ds_read_b128 v[202:205], v90 offset:53248
	s_waitcnt lgkmcnt(6)
	v_mfma_f32_32x32x16_bf16 v[50:65], v[162:165], v[166:169], v[50:65]
	s_waitcnt lgkmcnt(4)
	v_mfma_f32_32x32x16_bf16 v[34:49], v[162:165], v[186:189], v[34:49]
	v_mfma_f32_32x32x16_bf16 v[18:33], v[182:185], v[166:169], v[18:33]
	v_mfma_f32_32x32x16_bf16 v[2:17], v[182:185], v[186:189], v[2:17]
	ds_read_b128 v[162:165], v89 offset:16384
	ds_read_b128 v[166:169], v89 offset:20480
	ds_read_b128 v[182:185], v88 offset:49152
	ds_read_b128 v[186:189], v88 offset:53248
	s_waitcnt lgkmcnt(6)
	v_mfma_f32_32x32x16_bf16 v[50:65], v[190:193], v[194:197], v[50:65]
	s_waitcnt lgkmcnt(4)
	v_mfma_f32_32x32x16_bf16 v[34:49], v[190:193], v[202:205], v[34:49]
	v_mfma_f32_32x32x16_bf16 v[18:33], v[198:201], v[194:197], v[18:33]
	v_mfma_f32_32x32x16_bf16 v[2:17], v[198:201], v[202:205], v[2:17]
	ds_read_b128 v[190:193], v87 offset:16384
	ds_read_b128 v[194:197], v87 offset:20480
	ds_read_b128 v[198:201], v86 offset:49152
	ds_read_b128 v[202:205], v86 offset:53248
	v_lshl_add_u64 v[66:67], v[66:67], 0, s[98:99]
	v_lshl_add_u64 v[70:71], v[70:71], 0, s[98:99]
	v_lshl_add_u64 v[74:75], v[74:75], 0, s[98:99]
	v_lshl_add_u64 v[78:79], v[78:79], 0, s[98:99]
	v_lshl_add_u64 v[68:69], v[68:69], 0, s[98:99]
	v_lshl_add_u64 v[72:73], v[72:73], 0, s[98:99]
	v_lshl_add_u64 v[76:77], v[76:77], 0, s[98:99]
	v_lshl_add_u64 v[80:81], v[80:81], 0, s[98:99]
	s_waitcnt lgkmcnt(0)
	s_barrier
	s_add_u32 m0, s32, 0x4000
	v_mfma_f32_32x32x16_bf16 v[50:65], v[162:165], v[182:185], v[50:65]
	global_load_lds_dwordx4 v[66:67], off
	s_add_u32 m0, s32, 0x5000
	v_mfma_f32_32x32x16_bf16 v[34:49], v[162:165], v[186:189], v[34:49]
	global_load_lds_dwordx4 v[70:71], off
	s_add_u32 m0, s32, 0x6000
	v_mfma_f32_32x32x16_bf16 v[18:33], v[166:169], v[182:185], v[18:33]
	global_load_lds_dwordx4 v[74:75], off
	s_add_u32 m0, s32, 0x7000
	v_mfma_f32_32x32x16_bf16 v[2:17], v[166:169], v[186:189], v[2:17]
	global_load_lds_dwordx4 v[78:79], off
	s_add_u32 m0, s32, 0xc000
	v_mfma_f32_32x32x16_bf16 v[50:65], v[190:193], v[198:201], v[50:65]
	global_load_lds_dwordx4 v[68:69], off
	s_add_u32 m0, s32, 0xd000
	v_mfma_f32_32x32x16_bf16 v[34:49], v[190:193], v[202:205], v[34:49]
	global_load_lds_dwordx4 v[72:73], off
	s_add_u32 m0, s32, 0xe000
	v_mfma_f32_32x32x16_bf16 v[18:33], v[194:197], v[198:201], v[18:33]
	global_load_lds_dwordx4 v[76:77], off
	s_add_u32 m0, s32, 0xf000
	v_mfma_f32_32x32x16_bf16 v[2:17], v[194:197], v[202:205], v[2:17]
	global_load_lds_dwordx4 v[80:81], off
	s_waitcnt vmcnt(8)
	s_barrier
	ds_read_b128 v[162:165], v91
	ds_read_b128 v[166:169], v92 offset:32768
	ds_read_b128 v[182:185], v91 offset:4096
	ds_read_b128 v[186:189], v92 offset:36864
	ds_read_b128 v[190:193], v93
	ds_read_b128 v[194:197], v90 offset:32768
	ds_read_b128 v[198:201], v93 offset:4096
	ds_read_b128 v[202:205], v90 offset:36864
	s_waitcnt lgkmcnt(6)
	v_mfma_f32_32x32x16_bf16 v[50:65], v[162:165], v[166:169], v[50:65]
	s_waitcnt lgkmcnt(4)
	v_mfma_f32_32x32x16_bf16 v[34:49], v[162:165], v[186:189], v[34:49]
	v_mfma_f32_32x32x16_bf16 v[18:33], v[182:185], v[166:169], v[18:33]
	v_mfma_f32_32x32x16_bf16 v[2:17], v[182:185], v[186:189], v[2:17]
	ds_read_b128 v[162:165], v89
	ds_read_b128 v[166:169], v89 offset:4096
	ds_read_b128 v[182:185], v88 offset:32768
	ds_read_b128 v[186:189], v88 offset:36864
	s_waitcnt lgkmcnt(6)
	v_mfma_f32_32x32x16_bf16 v[50:65], v[190:193], v[194:197], v[50:65]
	s_waitcnt lgkmcnt(4)
	v_mfma_f32_32x32x16_bf16 v[34:49], v[190:193], v[202:205], v[34:49]
	v_mfma_f32_32x32x16_bf16 v[18:33], v[198:201], v[194:197], v[18:33]
	v_mfma_f32_32x32x16_bf16 v[2:17], v[198:201], v[202:205], v[2:17]
	ds_read_b128 v[190:193], v87
	ds_read_b128 v[194:197], v87 offset:4096
	ds_read_b128 v[198:201], v86 offset:32768
	ds_read_b128 v[202:205], v86 offset:36864
	v_lshl_add_u64 v[66:67], v[66:67], 0, s[98:99]
	v_lshl_add_u64 v[70:71], v[70:71], 0, s[98:99]
	v_lshl_add_u64 v[74:75], v[74:75], 0, s[98:99]
	v_lshl_add_u64 v[78:79], v[78:79], 0, s[98:99]
	v_lshl_add_u64 v[68:69], v[68:69], 0, s[98:99]
	v_lshl_add_u64 v[72:73], v[72:73], 0, s[98:99]
	v_lshl_add_u64 v[76:77], v[76:77], 0, s[98:99]
	v_lshl_add_u64 v[80:81], v[80:81], 0, s[98:99]
	s_waitcnt lgkmcnt(0)
	s_barrier
	s_add_u32 m0, s32, 0x0
	v_mfma_f32_32x32x16_bf16 v[50:65], v[162:165], v[182:185], v[50:65]
	global_load_lds_dwordx4 v[66:67], off
	s_add_u32 m0, s32, 0x1000
	v_mfma_f32_32x32x16_bf16 v[34:49], v[162:165], v[186:189], v[34:49]
	global_load_lds_dwordx4 v[70:71], off
	s_add_u32 m0, s32, 0x2000
	v_mfma_f32_32x32x16_bf16 v[18:33], v[166:169], v[182:185], v[18:33]
	global_load_lds_dwordx4 v[74:75], off
	s_add_u32 m0, s32, 0x3000
	v_mfma_f32_32x32x16_bf16 v[2:17], v[166:169], v[186:189], v[2:17]
	global_load_lds_dwordx4 v[78:79], off
	s_add_u32 m0, s32, 0x8000
	v_mfma_f32_32x32x16_bf16 v[50:65], v[190:193], v[198:201], v[50:65]
	global_load_lds_dwordx4 v[68:69], off
	s_add_u32 m0, s32, 0x9000
	v_mfma_f32_32x32x16_bf16 v[34:49], v[190:193], v[202:205], v[34:49]
	global_load_lds_dwordx4 v[72:73], off
	s_add_u32 m0, s32, 0xa000
	v_mfma_f32_32x32x16_bf16 v[18:33], v[194:197], v[198:201], v[18:33]
	global_load_lds_dwordx4 v[76:77], off
	s_add_u32 m0, s32, 0xb000
	v_mfma_f32_32x32x16_bf16 v[2:17], v[194:197], v[202:205], v[2:17]
	global_load_lds_dwordx4 v[80:81], off
	s_waitcnt vmcnt(8)
	s_barrier
	ds_read_b128 v[162:165], v91 offset:16384
	ds_read_b128 v[166:169], v92 offset:49152
	ds_read_b128 v[182:185], v91 offset:20480
	ds_read_b128 v[186:189], v92 offset:53248
	ds_read_b128 v[190:193], v93 offset:16384
	ds_read_b128 v[194:197], v90 offset:49152
	ds_read_b128 v[198:201], v93 offset:20480
	ds_read_b128 v[202:205], v90 offset:53248
	s_waitcnt lgkmcnt(6)
	v_mfma_f32_32x32x16_bf16 v[50:65], v[162:165], v[166:169], v[50:65]
	s_waitcnt lgkmcnt(4)
	v_mfma_f32_32x32x16_bf16 v[34:49], v[162:165], v[186:189], v[34:49]
	v_mfma_f32_32x32x16_bf16 v[18:33], v[182:185], v[166:169], v[18:33]
	v_mfma_f32_32x32x16_bf16 v[2:17], v[182:185], v[186:189], v[2:17]
	ds_read_b128 v[162:165], v89 offset:16384
	ds_read_b128 v[166:169], v89 offset:20480
	ds_read_b128 v[182:185], v88 offset:49152
	ds_read_b128 v[186:189], v88 offset:53248
	s_waitcnt lgkmcnt(6)
	v_mfma_f32_32x32x16_bf16 v[50:65], v[190:193], v[194:197], v[50:65]
	s_waitcnt lgkmcnt(4)
	v_mfma_f32_32x32x16_bf16 v[34:49], v[190:193], v[202:205], v[34:49]
	v_mfma_f32_32x32x16_bf16 v[18:33], v[198:201], v[194:197], v[18:33]
	v_mfma_f32_32x32x16_bf16 v[2:17], v[198:201], v[202:205], v[2:17]
	ds_read_b128 v[190:193], v87 offset:16384
	ds_read_b128 v[194:197], v87 offset:20480
	ds_read_b128 v[198:201], v86 offset:49152
	ds_read_b128 v[202:205], v86 offset:53248
	v_lshl_add_u64 v[66:67], v[66:67], 0, s[98:99]
	v_lshl_add_u64 v[70:71], v[70:71], 0, s[98:99]
	v_lshl_add_u64 v[74:75], v[74:75], 0, s[98:99]
	v_lshl_add_u64 v[78:79], v[78:79], 0, s[98:99]
	v_lshl_add_u64 v[68:69], v[68:69], 0, s[98:99]
	v_lshl_add_u64 v[72:73], v[72:73], 0, s[98:99]
	v_lshl_add_u64 v[76:77], v[76:77], 0, s[98:99]
	v_lshl_add_u64 v[80:81], v[80:81], 0, s[98:99]
	s_waitcnt lgkmcnt(0)
	s_barrier
	s_add_u32 m0, s32, 0x4000
	v_mfma_f32_32x32x16_bf16 v[50:65], v[162:165], v[182:185], v[50:65]
	global_load_lds_dwordx4 v[66:67], off
	s_add_u32 m0, s32, 0x5000
	v_mfma_f32_32x32x16_bf16 v[34:49], v[162:165], v[186:189], v[34:49]
	global_load_lds_dwordx4 v[70:71], off
	s_add_u32 m0, s32, 0x6000
	v_mfma_f32_32x32x16_bf16 v[18:33], v[166:169], v[182:185], v[18:33]
	global_load_lds_dwordx4 v[74:75], off
	s_add_u32 m0, s32, 0x7000
	v_mfma_f32_32x32x16_bf16 v[2:17], v[166:169], v[186:189], v[2:17]
	global_load_lds_dwordx4 v[78:79], off
	s_add_u32 m0, s32, 0xc000
	v_mfma_f32_32x32x16_bf16 v[50:65], v[190:193], v[198:201], v[50:65]
	global_load_lds_dwordx4 v[68:69], off
	s_add_u32 m0, s32, 0xd000
	v_mfma_f32_32x32x16_bf16 v[34:49], v[190:193], v[202:205], v[34:49]
	global_load_lds_dwordx4 v[72:73], off
	s_add_u32 m0, s32, 0xe000
	v_mfma_f32_32x32x16_bf16 v[18:33], v[194:197], v[198:201], v[18:33]
	global_load_lds_dwordx4 v[76:77], off
	s_add_u32 m0, s32, 0xf000
	v_mfma_f32_32x32x16_bf16 v[2:17], v[194:197], v[202:205], v[2:17]
	global_load_lds_dwordx4 v[80:81], off
	s_waitcnt vmcnt(8)
	s_barrier
	ds_read_b128 v[162:165], v91
	ds_read_b128 v[166:169], v92 offset:32768
	ds_read_b128 v[182:185], v91 offset:4096
	ds_read_b128 v[186:189], v92 offset:36864
	ds_read_b128 v[190:193], v93
	ds_read_b128 v[194:197], v90 offset:32768
	ds_read_b128 v[198:201], v93 offset:4096
	ds_read_b128 v[202:205], v90 offset:36864
	s_waitcnt lgkmcnt(6)
	v_mfma_f32_32x32x16_bf16 v[50:65], v[162:165], v[166:169], v[50:65]
	s_waitcnt lgkmcnt(4)
	v_mfma_f32_32x32x16_bf16 v[34:49], v[162:165], v[186:189], v[34:49]
	v_mfma_f32_32x32x16_bf16 v[18:33], v[182:185], v[166:169], v[18:33]
	v_mfma_f32_32x32x16_bf16 v[2:17], v[182:185], v[186:189], v[2:17]
	ds_read_b128 v[162:165], v89
	ds_read_b128 v[166:169], v89 offset:4096
	ds_read_b128 v[182:185], v88 offset:32768
	ds_read_b128 v[186:189], v88 offset:36864
	s_waitcnt lgkmcnt(6)
	v_mfma_f32_32x32x16_bf16 v[50:65], v[190:193], v[194:197], v[50:65]
	s_waitcnt lgkmcnt(4)
	v_mfma_f32_32x32x16_bf16 v[34:49], v[190:193], v[202:205], v[34:49]
	v_mfma_f32_32x32x16_bf16 v[18:33], v[198:201], v[194:197], v[18:33]
	v_mfma_f32_32x32x16_bf16 v[2:17], v[198:201], v[202:205], v[2:17]
	ds_read_b128 v[190:193], v87
	ds_read_b128 v[194:197], v87 offset:4096
	ds_read_b128 v[198:201], v86 offset:32768
	ds_read_b128 v[202:205], v86 offset:36864
	v_lshl_add_u64 v[66:67], v[66:67], 0, s[98:99]
	v_lshl_add_u64 v[70:71], v[70:71], 0, s[98:99]
	v_lshl_add_u64 v[74:75], v[74:75], 0, s[98:99]
	v_lshl_add_u64 v[78:79], v[78:79], 0, s[98:99]
	v_lshl_add_u64 v[68:69], v[68:69], 0, s[98:99]
	v_lshl_add_u64 v[72:73], v[72:73], 0, s[98:99]
	v_lshl_add_u64 v[76:77], v[76:77], 0, s[98:99]
	v_lshl_add_u64 v[80:81], v[80:81], 0, s[98:99]
	s_waitcnt lgkmcnt(0)
	s_barrier
	s_add_u32 m0, s32, 0x0
	v_mfma_f32_32x32x16_bf16 v[50:65], v[162:165], v[182:185], v[50:65]
	global_load_lds_dwordx4 v[66:67], off
	s_add_u32 m0, s32, 0x1000
	v_mfma_f32_32x32x16_bf16 v[34:49], v[162:165], v[186:189], v[34:49]
	global_load_lds_dwordx4 v[70:71], off
	s_add_u32 m0, s32, 0x2000
	v_mfma_f32_32x32x16_bf16 v[18:33], v[166:169], v[182:185], v[18:33]
	global_load_lds_dwordx4 v[74:75], off
	s_add_u32 m0, s32, 0x3000
	v_mfma_f32_32x32x16_bf16 v[2:17], v[166:169], v[186:189], v[2:17]
	global_load_lds_dwordx4 v[78:79], off
	s_add_u32 m0, s32, 0x8000
	v_mfma_f32_32x32x16_bf16 v[50:65], v[190:193], v[198:201], v[50:65]
	global_load_lds_dwordx4 v[68:69], off
	s_add_u32 m0, s32, 0x9000
	v_mfma_f32_32x32x16_bf16 v[34:49], v[190:193], v[202:205], v[34:49]
	global_load_lds_dwordx4 v[72:73], off
	s_add_u32 m0, s32, 0xa000
	v_mfma_f32_32x32x16_bf16 v[18:33], v[194:197], v[198:201], v[18:33]
	global_load_lds_dwordx4 v[76:77], off
	s_add_u32 m0, s32, 0xb000
	v_mfma_f32_32x32x16_bf16 v[2:17], v[194:197], v[202:205], v[2:17]
	global_load_lds_dwordx4 v[80:81], off
	s_waitcnt vmcnt(8)
	s_barrier
	ds_read_b128 v[162:165], v91 offset:16384
	ds_read_b128 v[166:169], v92 offset:49152
	ds_read_b128 v[182:185], v91 offset:20480
	ds_read_b128 v[186:189], v92 offset:53248
	ds_read_b128 v[190:193], v93 offset:16384
	ds_read_b128 v[194:197], v90 offset:49152
	ds_read_b128 v[198:201], v93 offset:20480
	ds_read_b128 v[202:205], v90 offset:53248
	s_waitcnt lgkmcnt(6)
	v_mfma_f32_32x32x16_bf16 v[50:65], v[162:165], v[166:169], v[50:65]
	s_waitcnt lgkmcnt(4)
	v_mfma_f32_32x32x16_bf16 v[34:49], v[162:165], v[186:189], v[34:49]
	v_mfma_f32_32x32x16_bf16 v[18:33], v[182:185], v[166:169], v[18:33]
	v_mfma_f32_32x32x16_bf16 v[2:17], v[182:185], v[186:189], v[2:17]
	ds_read_b128 v[162:165], v89 offset:16384
	ds_read_b128 v[166:169], v89 offset:20480
	ds_read_b128 v[182:185], v88 offset:49152
	ds_read_b128 v[186:189], v88 offset:53248
	s_waitcnt lgkmcnt(6)
	v_mfma_f32_32x32x16_bf16 v[50:65], v[190:193], v[194:197], v[50:65]
	s_waitcnt lgkmcnt(4)
	v_mfma_f32_32x32x16_bf16 v[34:49], v[190:193], v[202:205], v[34:49]
	v_mfma_f32_32x32x16_bf16 v[18:33], v[198:201], v[194:197], v[18:33]
	v_mfma_f32_32x32x16_bf16 v[2:17], v[198:201], v[202:205], v[2:17]
	ds_read_b128 v[190:193], v87 offset:16384
	ds_read_b128 v[194:197], v87 offset:20480
	ds_read_b128 v[198:201], v86 offset:49152
	ds_read_b128 v[202:205], v86 offset:53248
	v_lshl_add_u64 v[66:67], v[66:67], 0, s[98:99]
	v_lshl_add_u64 v[70:71], v[70:71], 0, s[98:99]
	v_lshl_add_u64 v[74:75], v[74:75], 0, s[98:99]
	v_lshl_add_u64 v[78:79], v[78:79], 0, s[98:99]
	v_lshl_add_u64 v[68:69], v[68:69], 0, s[98:99]
	v_lshl_add_u64 v[72:73], v[72:73], 0, s[98:99]
	v_lshl_add_u64 v[76:77], v[76:77], 0, s[98:99]
	v_lshl_add_u64 v[80:81], v[80:81], 0, s[98:99]
	s_waitcnt lgkmcnt(0)
	s_barrier
	s_add_u32 m0, s32, 0x4000
	v_mfma_f32_32x32x16_bf16 v[50:65], v[162:165], v[182:185], v[50:65]
	global_load_lds_dwordx4 v[66:67], off
	s_add_u32 m0, s32, 0x5000
	v_mfma_f32_32x32x16_bf16 v[34:49], v[162:165], v[186:189], v[34:49]
	global_load_lds_dwordx4 v[70:71], off
	s_add_u32 m0, s32, 0x6000
	v_mfma_f32_32x32x16_bf16 v[18:33], v[166:169], v[182:185], v[18:33]
	global_load_lds_dwordx4 v[74:75], off
	s_add_u32 m0, s32, 0x7000
	v_mfma_f32_32x32x16_bf16 v[2:17], v[166:169], v[186:189], v[2:17]
	global_load_lds_dwordx4 v[78:79], off
	s_add_u32 m0, s32, 0xc000
	v_mfma_f32_32x32x16_bf16 v[50:65], v[190:193], v[198:201], v[50:65]
	global_load_lds_dwordx4 v[68:69], off
	s_add_u32 m0, s32, 0xd000
	v_mfma_f32_32x32x16_bf16 v[34:49], v[190:193], v[202:205], v[34:49]
	global_load_lds_dwordx4 v[72:73], off
	s_add_u32 m0, s32, 0xe000
	v_mfma_f32_32x32x16_bf16 v[18:33], v[194:197], v[198:201], v[18:33]
	global_load_lds_dwordx4 v[76:77], off
	s_add_u32 m0, s32, 0xf000
	v_mfma_f32_32x32x16_bf16 v[2:17], v[194:197], v[202:205], v[2:17]
	global_load_lds_dwordx4 v[80:81], off
	s_waitcnt vmcnt(8)
	s_barrier
	ds_read_b128 v[162:165], v91
	ds_read_b128 v[166:169], v92 offset:32768
	ds_read_b128 v[182:185], v91 offset:4096
	ds_read_b128 v[186:189], v92 offset:36864
	ds_read_b128 v[190:193], v93
	ds_read_b128 v[194:197], v90 offset:32768
	ds_read_b128 v[198:201], v93 offset:4096
	ds_read_b128 v[202:205], v90 offset:36864
	s_waitcnt lgkmcnt(6)
	v_mfma_f32_32x32x16_bf16 v[50:65], v[162:165], v[166:169], v[50:65]
	s_waitcnt lgkmcnt(4)
	v_mfma_f32_32x32x16_bf16 v[34:49], v[162:165], v[186:189], v[34:49]
	v_mfma_f32_32x32x16_bf16 v[18:33], v[182:185], v[166:169], v[18:33]
	v_mfma_f32_32x32x16_bf16 v[2:17], v[182:185], v[186:189], v[2:17]
	ds_read_b128 v[162:165], v89
	ds_read_b128 v[166:169], v89 offset:4096
	ds_read_b128 v[182:185], v88 offset:32768
	ds_read_b128 v[186:189], v88 offset:36864
	s_waitcnt lgkmcnt(6)
	v_mfma_f32_32x32x16_bf16 v[50:65], v[190:193], v[194:197], v[50:65]
	s_waitcnt lgkmcnt(4)
	v_mfma_f32_32x32x16_bf16 v[34:49], v[190:193], v[202:205], v[34:49]
	v_mfma_f32_32x32x16_bf16 v[18:33], v[198:201], v[194:197], v[18:33]
	v_mfma_f32_32x32x16_bf16 v[2:17], v[198:201], v[202:205], v[2:17]
	ds_read_b128 v[190:193], v87
	ds_read_b128 v[194:197], v87 offset:4096
	ds_read_b128 v[198:201], v86 offset:32768
	ds_read_b128 v[202:205], v86 offset:36864
	v_lshl_add_u64 v[66:67], v[66:67], 0, s[98:99]
	v_lshl_add_u64 v[70:71], v[70:71], 0, s[98:99]
	v_lshl_add_u64 v[74:75], v[74:75], 0, s[98:99]
	v_lshl_add_u64 v[78:79], v[78:79], 0, s[98:99]
	v_lshl_add_u64 v[68:69], v[68:69], 0, s[98:99]
	v_lshl_add_u64 v[72:73], v[72:73], 0, s[98:99]
	v_lshl_add_u64 v[76:77], v[76:77], 0, s[98:99]
	v_lshl_add_u64 v[80:81], v[80:81], 0, s[98:99]
	s_waitcnt lgkmcnt(0)
	s_barrier
	s_add_u32 m0, s32, 0x0
	v_mfma_f32_32x32x16_bf16 v[50:65], v[162:165], v[182:185], v[50:65]
	global_load_lds_dwordx4 v[66:67], off
	s_add_u32 m0, s32, 0x1000
	v_mfma_f32_32x32x16_bf16 v[34:49], v[162:165], v[186:189], v[34:49]
	global_load_lds_dwordx4 v[70:71], off
	s_add_u32 m0, s32, 0x2000
	v_mfma_f32_32x32x16_bf16 v[18:33], v[166:169], v[182:185], v[18:33]
	global_load_lds_dwordx4 v[74:75], off
	s_add_u32 m0, s32, 0x3000
	v_mfma_f32_32x32x16_bf16 v[2:17], v[166:169], v[186:189], v[2:17]
	global_load_lds_dwordx4 v[78:79], off
	s_add_u32 m0, s32, 0x8000
	v_mfma_f32_32x32x16_bf16 v[50:65], v[190:193], v[198:201], v[50:65]
	global_load_lds_dwordx4 v[68:69], off
	s_add_u32 m0, s32, 0x9000
	v_mfma_f32_32x32x16_bf16 v[34:49], v[190:193], v[202:205], v[34:49]
	global_load_lds_dwordx4 v[72:73], off
	s_add_u32 m0, s32, 0xa000
	v_mfma_f32_32x32x16_bf16 v[18:33], v[194:197], v[198:201], v[18:33]
	global_load_lds_dwordx4 v[76:77], off
	s_add_u32 m0, s32, 0xb000
	v_mfma_f32_32x32x16_bf16 v[2:17], v[194:197], v[202:205], v[2:17]
	global_load_lds_dwordx4 v[80:81], off
	s_waitcnt vmcnt(8)
	s_barrier
	ds_read_b128 v[162:165], v91 offset:16384
	ds_read_b128 v[166:169], v92 offset:49152
	ds_read_b128 v[182:185], v91 offset:20480
	ds_read_b128 v[186:189], v92 offset:53248
	ds_read_b128 v[190:193], v93 offset:16384
	ds_read_b128 v[194:197], v90 offset:49152
	ds_read_b128 v[198:201], v93 offset:20480
	ds_read_b128 v[202:205], v90 offset:53248
	s_waitcnt lgkmcnt(6)
	v_mfma_f32_32x32x16_bf16 v[50:65], v[162:165], v[166:169], v[50:65]
	s_waitcnt lgkmcnt(4)
	v_mfma_f32_32x32x16_bf16 v[34:49], v[162:165], v[186:189], v[34:49]
	v_mfma_f32_32x32x16_bf16 v[18:33], v[182:185], v[166:169], v[18:33]
	v_mfma_f32_32x32x16_bf16 v[2:17], v[182:185], v[186:189], v[2:17]
	ds_read_b128 v[162:165], v89 offset:16384
	ds_read_b128 v[166:169], v89 offset:20480
	ds_read_b128 v[182:185], v88 offset:49152
	ds_read_b128 v[186:189], v88 offset:53248
	s_waitcnt lgkmcnt(6)
	v_mfma_f32_32x32x16_bf16 v[50:65], v[190:193], v[194:197], v[50:65]
	s_waitcnt lgkmcnt(4)
	v_mfma_f32_32x32x16_bf16 v[34:49], v[190:193], v[202:205], v[34:49]
	v_mfma_f32_32x32x16_bf16 v[18:33], v[198:201], v[194:197], v[18:33]
	v_mfma_f32_32x32x16_bf16 v[2:17], v[198:201], v[202:205], v[2:17]
	ds_read_b128 v[190:193], v87 offset:16384
	ds_read_b128 v[194:197], v87 offset:20480
	ds_read_b128 v[198:201], v86 offset:49152
	ds_read_b128 v[202:205], v86 offset:53248
	v_lshl_add_u64 v[66:67], v[66:67], 0, s[98:99]
	v_lshl_add_u64 v[70:71], v[70:71], 0, s[98:99]
	v_lshl_add_u64 v[74:75], v[74:75], 0, s[98:99]
	v_lshl_add_u64 v[78:79], v[78:79], 0, s[98:99]
	v_lshl_add_u64 v[68:69], v[68:69], 0, s[98:99]
	v_lshl_add_u64 v[72:73], v[72:73], 0, s[98:99]
	v_lshl_add_u64 v[76:77], v[76:77], 0, s[98:99]
	v_lshl_add_u64 v[80:81], v[80:81], 0, s[98:99]
	s_waitcnt lgkmcnt(0)
	s_barrier
	s_add_u32 m0, s32, 0x4000
	v_mfma_f32_32x32x16_bf16 v[50:65], v[162:165], v[182:185], v[50:65]
	global_load_lds_dwordx4 v[66:67], off
	s_add_u32 m0, s32, 0x5000
	v_mfma_f32_32x32x16_bf16 v[34:49], v[162:165], v[186:189], v[34:49]
	global_load_lds_dwordx4 v[70:71], off
	s_add_u32 m0, s32, 0x6000
	v_mfma_f32_32x32x16_bf16 v[18:33], v[166:169], v[182:185], v[18:33]
	global_load_lds_dwordx4 v[74:75], off
	s_add_u32 m0, s32, 0x7000
	v_mfma_f32_32x32x16_bf16 v[2:17], v[166:169], v[186:189], v[2:17]
	global_load_lds_dwordx4 v[78:79], off
	s_add_u32 m0, s32, 0xc000
	v_mfma_f32_32x32x16_bf16 v[50:65], v[190:193], v[198:201], v[50:65]
	global_load_lds_dwordx4 v[68:69], off
	s_add_u32 m0, s32, 0xd000
	v_mfma_f32_32x32x16_bf16 v[34:49], v[190:193], v[202:205], v[34:49]
	global_load_lds_dwordx4 v[72:73], off
	s_add_u32 m0, s32, 0xe000
	v_mfma_f32_32x32x16_bf16 v[18:33], v[194:197], v[198:201], v[18:33]
	global_load_lds_dwordx4 v[76:77], off
	s_add_u32 m0, s32, 0xf000
	v_mfma_f32_32x32x16_bf16 v[2:17], v[194:197], v[202:205], v[2:17]
	global_load_lds_dwordx4 v[80:81], off
	s_waitcnt vmcnt(8)
	s_barrier
	ds_read_b128 v[162:165], v91
	ds_read_b128 v[166:169], v92 offset:32768
	ds_read_b128 v[182:185], v91 offset:4096
	ds_read_b128 v[186:189], v92 offset:36864
	ds_read_b128 v[190:193], v93
	ds_read_b128 v[194:197], v90 offset:32768
	ds_read_b128 v[198:201], v93 offset:4096
	ds_read_b128 v[202:205], v90 offset:36864
	s_waitcnt lgkmcnt(6)
	v_mfma_f32_32x32x16_bf16 v[50:65], v[162:165], v[166:169], v[50:65]
	s_waitcnt lgkmcnt(4)
	v_mfma_f32_32x32x16_bf16 v[34:49], v[162:165], v[186:189], v[34:49]
	v_mfma_f32_32x32x16_bf16 v[18:33], v[182:185], v[166:169], v[18:33]
	v_mfma_f32_32x32x16_bf16 v[2:17], v[182:185], v[186:189], v[2:17]
	ds_read_b128 v[162:165], v89
	ds_read_b128 v[166:169], v89 offset:4096
	ds_read_b128 v[182:185], v88 offset:32768
	ds_read_b128 v[186:189], v88 offset:36864
	s_waitcnt lgkmcnt(6)
	v_mfma_f32_32x32x16_bf16 v[50:65], v[190:193], v[194:197], v[50:65]
	s_waitcnt lgkmcnt(4)
	v_mfma_f32_32x32x16_bf16 v[34:49], v[190:193], v[202:205], v[34:49]
	v_mfma_f32_32x32x16_bf16 v[18:33], v[198:201], v[194:197], v[18:33]
	v_mfma_f32_32x32x16_bf16 v[2:17], v[198:201], v[202:205], v[2:17]
	ds_read_b128 v[190:193], v87
	ds_read_b128 v[194:197], v87 offset:4096
	ds_read_b128 v[198:201], v86 offset:32768
	ds_read_b128 v[202:205], v86 offset:36864
	v_lshl_add_u64 v[66:67], v[66:67], 0, s[98:99]
	v_lshl_add_u64 v[70:71], v[70:71], 0, s[98:99]
	v_lshl_add_u64 v[74:75], v[74:75], 0, s[98:99]
	v_lshl_add_u64 v[78:79], v[78:79], 0, s[98:99]
	v_lshl_add_u64 v[68:69], v[68:69], 0, s[98:99]
	v_lshl_add_u64 v[72:73], v[72:73], 0, s[98:99]
	v_lshl_add_u64 v[76:77], v[76:77], 0, s[98:99]
	v_lshl_add_u64 v[80:81], v[80:81], 0, s[98:99]
	s_waitcnt lgkmcnt(0)
	s_barrier
	s_add_u32 m0, s32, 0x0
	v_mfma_f32_32x32x16_bf16 v[50:65], v[162:165], v[182:185], v[50:65]
	global_load_lds_dwordx4 v[66:67], off
	s_add_u32 m0, s32, 0x1000
	v_mfma_f32_32x32x16_bf16 v[34:49], v[162:165], v[186:189], v[34:49]
	global_load_lds_dwordx4 v[70:71], off
	s_add_u32 m0, s32, 0x2000
	v_mfma_f32_32x32x16_bf16 v[18:33], v[166:169], v[182:185], v[18:33]
	global_load_lds_dwordx4 v[74:75], off
	s_add_u32 m0, s32, 0x3000
	v_mfma_f32_32x32x16_bf16 v[2:17], v[166:169], v[186:189], v[2:17]
	global_load_lds_dwordx4 v[78:79], off
	s_add_u32 m0, s32, 0x8000
	v_mfma_f32_32x32x16_bf16 v[50:65], v[190:193], v[198:201], v[50:65]
	global_load_lds_dwordx4 v[68:69], off
	s_add_u32 m0, s32, 0x9000
	v_mfma_f32_32x32x16_bf16 v[34:49], v[190:193], v[202:205], v[34:49]
	global_load_lds_dwordx4 v[72:73], off
	s_add_u32 m0, s32, 0xa000
	v_mfma_f32_32x32x16_bf16 v[18:33], v[194:197], v[198:201], v[18:33]
	global_load_lds_dwordx4 v[76:77], off
	s_add_u32 m0, s32, 0xb000
	v_mfma_f32_32x32x16_bf16 v[2:17], v[194:197], v[202:205], v[2:17]
	global_load_lds_dwordx4 v[80:81], off
	s_waitcnt vmcnt(8)
	s_barrier
	ds_read_b128 v[162:165], v91 offset:16384
	ds_read_b128 v[166:169], v92 offset:49152
	ds_read_b128 v[182:185], v91 offset:20480
	ds_read_b128 v[186:189], v92 offset:53248
	ds_read_b128 v[190:193], v93 offset:16384
	ds_read_b128 v[194:197], v90 offset:49152
	ds_read_b128 v[198:201], v93 offset:20480
	ds_read_b128 v[202:205], v90 offset:53248
	s_waitcnt lgkmcnt(6)
	v_mfma_f32_32x32x16_bf16 v[50:65], v[162:165], v[166:169], v[50:65]
	s_waitcnt lgkmcnt(4)
	v_mfma_f32_32x32x16_bf16 v[34:49], v[162:165], v[186:189], v[34:49]
	v_mfma_f32_32x32x16_bf16 v[18:33], v[182:185], v[166:169], v[18:33]
	v_mfma_f32_32x32x16_bf16 v[2:17], v[182:185], v[186:189], v[2:17]
	ds_read_b128 v[162:165], v89 offset:16384
	ds_read_b128 v[166:169], v89 offset:20480
	ds_read_b128 v[182:185], v88 offset:49152
	ds_read_b128 v[186:189], v88 offset:53248
	s_waitcnt lgkmcnt(6)
	v_mfma_f32_32x32x16_bf16 v[50:65], v[190:193], v[194:197], v[50:65]
	s_waitcnt lgkmcnt(4)
	v_mfma_f32_32x32x16_bf16 v[34:49], v[190:193], v[202:205], v[34:49]
	v_mfma_f32_32x32x16_bf16 v[18:33], v[198:201], v[194:197], v[18:33]
	v_mfma_f32_32x32x16_bf16 v[2:17], v[198:201], v[202:205], v[2:17]
	ds_read_b128 v[190:193], v87 offset:16384
	ds_read_b128 v[194:197], v87 offset:20480
	ds_read_b128 v[198:201], v86 offset:49152
	ds_read_b128 v[202:205], v86 offset:53248
	v_lshl_add_u64 v[66:67], v[66:67], 0, s[98:99]
	v_lshl_add_u64 v[70:71], v[70:71], 0, s[98:99]
	v_lshl_add_u64 v[74:75], v[74:75], 0, s[98:99]
	v_lshl_add_u64 v[78:79], v[78:79], 0, s[98:99]
	v_lshl_add_u64 v[68:69], v[68:69], 0, s[98:99]
	v_lshl_add_u64 v[72:73], v[72:73], 0, s[98:99]
	v_lshl_add_u64 v[76:77], v[76:77], 0, s[98:99]
	v_lshl_add_u64 v[80:81], v[80:81], 0, s[98:99]
	s_waitcnt lgkmcnt(0)
	s_barrier
	s_add_u32 m0, s32, 0x4000
	v_mfma_f32_32x32x16_bf16 v[50:65], v[162:165], v[182:185], v[50:65]
	global_load_lds_dwordx4 v[66:67], off
	s_add_u32 m0, s32, 0x5000
	v_mfma_f32_32x32x16_bf16 v[34:49], v[162:165], v[186:189], v[34:49]
	global_load_lds_dwordx4 v[70:71], off
	s_add_u32 m0, s32, 0x6000
	v_mfma_f32_32x32x16_bf16 v[18:33], v[166:169], v[182:185], v[18:33]
	global_load_lds_dwordx4 v[74:75], off
	s_add_u32 m0, s32, 0x7000
	v_mfma_f32_32x32x16_bf16 v[2:17], v[166:169], v[186:189], v[2:17]
	global_load_lds_dwordx4 v[78:79], off
	s_add_u32 m0, s32, 0xc000
	v_mfma_f32_32x32x16_bf16 v[50:65], v[190:193], v[198:201], v[50:65]
	global_load_lds_dwordx4 v[68:69], off
	s_add_u32 m0, s32, 0xd000
	v_mfma_f32_32x32x16_bf16 v[34:49], v[190:193], v[202:205], v[34:49]
	global_load_lds_dwordx4 v[72:73], off
	s_add_u32 m0, s32, 0xe000
	v_mfma_f32_32x32x16_bf16 v[18:33], v[194:197], v[198:201], v[18:33]
	global_load_lds_dwordx4 v[76:77], off
	s_add_u32 m0, s32, 0xf000
	v_mfma_f32_32x32x16_bf16 v[2:17], v[194:197], v[202:205], v[2:17]
	global_load_lds_dwordx4 v[80:81], off
	s_waitcnt vmcnt(8)
	s_barrier
	ds_read_b128 v[162:165], v91
	ds_read_b128 v[166:169], v92 offset:32768
	ds_read_b128 v[182:185], v91 offset:4096
	ds_read_b128 v[186:189], v92 offset:36864
	ds_read_b128 v[190:193], v93
	ds_read_b128 v[194:197], v90 offset:32768
	ds_read_b128 v[198:201], v93 offset:4096
	ds_read_b128 v[202:205], v90 offset:36864
	s_waitcnt lgkmcnt(6)
	v_mfma_f32_32x32x16_bf16 v[50:65], v[162:165], v[166:169], v[50:65]
	s_waitcnt lgkmcnt(4)
	v_mfma_f32_32x32x16_bf16 v[34:49], v[162:165], v[186:189], v[34:49]
	v_mfma_f32_32x32x16_bf16 v[18:33], v[182:185], v[166:169], v[18:33]
	v_mfma_f32_32x32x16_bf16 v[2:17], v[182:185], v[186:189], v[2:17]
	ds_read_b128 v[162:165], v89
	ds_read_b128 v[166:169], v89 offset:4096
	ds_read_b128 v[182:185], v88 offset:32768
	ds_read_b128 v[186:189], v88 offset:36864
	s_waitcnt lgkmcnt(6)
	v_mfma_f32_32x32x16_bf16 v[50:65], v[190:193], v[194:197], v[50:65]
	s_waitcnt lgkmcnt(4)
	v_mfma_f32_32x32x16_bf16 v[34:49], v[190:193], v[202:205], v[34:49]
	v_mfma_f32_32x32x16_bf16 v[18:33], v[198:201], v[194:197], v[18:33]
	v_mfma_f32_32x32x16_bf16 v[2:17], v[198:201], v[202:205], v[2:17]
	ds_read_b128 v[190:193], v87
	ds_read_b128 v[194:197], v87 offset:4096
	ds_read_b128 v[198:201], v86 offset:32768
	ds_read_b128 v[202:205], v86 offset:36864
	v_lshl_add_u64 v[66:67], v[66:67], 0, s[98:99]
	v_lshl_add_u64 v[70:71], v[70:71], 0, s[98:99]
	v_lshl_add_u64 v[74:75], v[74:75], 0, s[98:99]
	v_lshl_add_u64 v[78:79], v[78:79], 0, s[98:99]
	v_lshl_add_u64 v[68:69], v[68:69], 0, s[98:99]
	v_lshl_add_u64 v[72:73], v[72:73], 0, s[98:99]
	v_lshl_add_u64 v[76:77], v[76:77], 0, s[98:99]
	v_lshl_add_u64 v[80:81], v[80:81], 0, s[98:99]
	s_waitcnt lgkmcnt(0)
	s_barrier
	s_add_u32 m0, s32, 0x0
	s_nop 0
	global_load_lds_dwordx4 v[66:67], off
	s_add_u32 m0, s32, 0x1000
	s_nop 0
	global_load_lds_dwordx4 v[70:71], off
	s_add_u32 m0, s32, 0x2000
	s_nop 0
	global_load_lds_dwordx4 v[74:75], off
	s_add_u32 m0, s32, 0x3000
	s_nop 0
	global_load_lds_dwordx4 v[78:79], off
	s_add_u32 m0, s32, 0x8000
	s_nop 0
	global_load_lds_dwordx4 v[68:69], off
	s_add_u32 m0, s32, 0x9000
	s_nop 0
	global_load_lds_dwordx4 v[72:73], off
	s_add_u32 m0, s32, 0xa000
	s_nop 0
	global_load_lds_dwordx4 v[76:77], off
	s_add_u32 m0, s32, 0xb000
	s_nop 0
	global_load_lds_dwordx4 v[80:81], off
	s_waitcnt vmcnt(8)
	s_barrier
	s_nop 0
	s_nop 0
	s_nop 0
	s_nop 0
	s_nop 0
	s_nop 0
	s_nop 0
	v_mfma_f32_32x32x16_bf16 v[50:65], v[162:165], v[182:185], v[50:65]
	v_mfma_f32_32x32x16_bf16 v[34:49], v[162:165], v[186:189], v[34:49]
	v_mfma_f32_32x32x16_bf16 v[18:33], v[166:169], v[182:185], v[18:33]
	v_mfma_f32_32x32x16_bf16 v[2:17], v[166:169], v[186:189], v[2:17]
	ds_read_b128 v[110:113], v91 offset:16384
	ds_read_b128 v[114:117], v91 offset:20480
	ds_read_b128 v[118:121], v92 offset:49152
	ds_read_b128 v[122:125], v92 offset:53248
	ds_read_b128 v[162:165], v93 offset:16384
	ds_read_b128 v[166:169], v93 offset:20480
	ds_read_b128 v[182:185], v90 offset:49152
	ds_read_b128 v[186:189], v90 offset:53248
	v_mfma_f32_32x32x16_bf16 v[50:65], v[190:193], v[198:201], v[50:65]
	v_mfma_f32_32x32x16_bf16 v[34:49], v[190:193], v[202:205], v[34:49]
	v_mfma_f32_32x32x16_bf16 v[18:33], v[194:197], v[198:201], v[18:33]
	v_mfma_f32_32x32x16_bf16 v[2:17], v[194:197], v[202:205], v[2:17]
	s_waitcnt lgkmcnt(5)
	v_mfma_f32_32x32x16_bf16 v[50:65], v[110:113], v[118:121], v[50:65]
	s_waitcnt lgkmcnt(4)
	v_mfma_f32_32x32x16_bf16 v[34:49], v[110:113], v[122:125], v[34:49]
	v_mfma_f32_32x32x16_bf16 v[18:33], v[114:117], v[118:121], v[18:33]
	v_mfma_f32_32x32x16_bf16 v[2:17], v[114:117], v[122:125], v[2:17]
	ds_read_b128 v[110:113], v89 offset:16384
	ds_read_b128 v[114:117], v89 offset:20480
	ds_read_b128 v[118:121], v88 offset:49152
	ds_read_b128 v[122:125], v88 offset:53248
	s_waitcnt lgkmcnt(5)
	v_mfma_f32_32x32x16_bf16 v[50:65], v[162:165], v[182:185], v[50:65]
	s_waitcnt lgkmcnt(4)
	v_mfma_f32_32x32x16_bf16 v[34:49], v[162:165], v[186:189], v[34:49]
	v_mfma_f32_32x32x16_bf16 v[18:33], v[166:169], v[182:185], v[18:33]
	v_mfma_f32_32x32x16_bf16 v[2:17], v[166:169], v[186:189], v[2:17]
	ds_read_b128 v[162:165], v87 offset:16384
	ds_read_b128 v[166:169], v87 offset:20480
	ds_read_b128 v[182:185], v86 offset:49152
	ds_read_b128 v[186:189], v86 offset:53248
	s_waitcnt lgkmcnt(5)
	v_mfma_f32_32x32x16_bf16 v[50:65], v[110:113], v[118:121], v[50:65]
	v_lshl_add_u64 v[66:67], v[66:67], 0, s[98:99]
	v_lshl_add_u64 v[70:71], v[70:71], 0, s[98:99]
	v_lshl_add_u64 v[74:75], v[74:75], 0, s[98:99]
	v_lshl_add_u64 v[78:79], v[78:79], 0, s[98:99]
	v_lshl_add_u64 v[68:69], v[68:69], 0, s[98:99]
	v_lshl_add_u64 v[72:73], v[72:73], 0, s[98:99]
	v_lshl_add_u64 v[76:77], v[76:77], 0, s[98:99]
	v_lshl_add_u64 v[80:81], v[80:81], 0, s[98:99]
	s_waitcnt lgkmcnt(0)
	s_barrier
	s_add_u32 m0, s32, 0x4000
	s_nop 0
	global_load_lds_dwordx4 v[66:67], off
	s_add_u32 m0, s32, 0x5000
	s_nop 0
	global_load_lds_dwordx4 v[70:71], off
	s_add_u32 m0, s32, 0x6000
	s_nop 0
	global_load_lds_dwordx4 v[74:75], off
	s_add_u32 m0, s32, 0x7000
	s_nop 0
	global_load_lds_dwordx4 v[78:79], off
	s_add_u32 m0, s32, 0xc000
	s_nop 0
	global_load_lds_dwordx4 v[68:69], off
	s_add_u32 m0, s32, 0xd000
	s_nop 0
	global_load_lds_dwordx4 v[72:73], off
	s_add_u32 m0, s32, 0xe000
	s_nop 0
	global_load_lds_dwordx4 v[76:77], off
	s_add_u32 m0, s32, 0xf000
	s_nop 0
	global_load_lds_dwordx4 v[80:81], off
	s_waitcnt vmcnt(8)
	s_barrier
	v_mfma_f32_32x32x16_bf16 v[34:49], v[110:113], v[122:125], v[34:49]
	v_mfma_f32_32x32x16_bf16 v[18:33], v[114:117], v[118:121], v[18:33]
	v_mfma_f32_32x32x16_bf16 v[2:17], v[114:117], v[122:125], v[2:17]
	ds_read_b128 v[110:113], v91
	ds_read_b128 v[114:117], v91 offset:4096
	ds_read_b128 v[118:121], v92 offset:32768
	ds_read_b128 v[122:125], v92 offset:36864
	ds_read_b128 v[126:129], v93
	ds_read_b128 v[134:137], v93 offset:4096
	ds_read_b128 v[138:141], v90 offset:32768
	ds_read_b128 v[142:145], v90 offset:36864
	v_mfma_f32_32x32x16_bf16 v[50:65], v[162:165], v[182:185], v[50:65]
	v_mfma_f32_32x32x16_bf16 v[34:49], v[162:165], v[186:189], v[34:49]
	v_mfma_f32_32x32x16_bf16 v[18:33], v[166:169], v[182:185], v[18:33]
	v_mfma_f32_32x32x16_bf16 v[2:17], v[166:169], v[186:189], v[2:17]
	s_waitcnt lgkmcnt(5)
	v_mfma_f32_32x32x16_bf16 v[50:65], v[110:113], v[118:121], v[50:65]
	s_waitcnt lgkmcnt(4)
	v_mfma_f32_32x32x16_bf16 v[34:49], v[110:113], v[122:125], v[34:49]
	v_mfma_f32_32x32x16_bf16 v[18:33], v[114:117], v[118:121], v[18:33]
	v_mfma_f32_32x32x16_bf16 v[2:17], v[114:117], v[122:125], v[2:17]
	ds_read_b128 v[110:113], v89
	ds_read_b128 v[114:117], v89 offset:4096
	ds_read_b128 v[118:121], v88 offset:32768
	ds_read_b128 v[122:125], v88 offset:36864
	s_waitcnt lgkmcnt(5)
	v_mfma_f32_32x32x16_bf16 v[50:65], v[126:129], v[138:141], v[50:65]
	s_waitcnt lgkmcnt(4)
	v_mfma_f32_32x32x16_bf16 v[34:49], v[126:129], v[142:145], v[34:49]
	v_mfma_f32_32x32x16_bf16 v[18:33], v[134:137], v[138:141], v[18:33]
	v_mfma_f32_32x32x16_bf16 v[2:17], v[134:137], v[142:145], v[2:17]
	ds_read_b128 v[126:129], v87
	ds_read_b128 v[134:137], v87 offset:4096
	ds_read_b128 v[138:141], v86 offset:32768
	ds_read_b128 v[142:145], v86 offset:36864
	s_waitcnt lgkmcnt(5)
	v_mfma_f32_32x32x16_bf16 v[50:65], v[110:113], v[118:121], v[50:65]
	s_waitcnt vmcnt(0)
	s_waitcnt lgkmcnt(0)
	s_barrier
	ds_read_b128 v[66:69], v91 offset:16384
	ds_read_b128 v[70:73], v91 offset:20480
	ds_read_b128 v[74:77], v92 offset:49152
	ds_read_b128 v[78:81], v92 offset:53248
	ds_read_b128 v[94:97], v93 offset:16384
	ds_read_b128 v[98:101], v93 offset:20480
	ds_read_b128 v[102:105], v90 offset:49152
	ds_read_b128 v[90:93], v90 offset:53248
	v_mfma_f32_32x32x16_bf16 v[34:49], v[110:113], v[122:125], v[34:49]
	v_mfma_f32_32x32x16_bf16 v[18:33], v[114:117], v[118:121], v[18:33]
	v_mfma_f32_32x32x16_bf16 v[2:17], v[114:117], v[122:125], v[2:17]
	v_mfma_f32_32x32x16_bf16 v[50:65], v[126:129], v[138:141], v[50:65]
	v_mfma_f32_32x32x16_bf16 v[34:49], v[126:129], v[142:145], v[34:49]
	v_mfma_f32_32x32x16_bf16 v[18:33], v[134:137], v[138:141], v[18:33]
	v_mfma_f32_32x32x16_bf16 v[2:17], v[134:137], v[142:145], v[2:17]
	s_waitcnt lgkmcnt(5)
	v_mfma_f32_32x32x16_bf16 v[50:65], v[66:69], v[74:77], v[50:65]
	s_waitcnt lgkmcnt(4)
	v_mfma_f32_32x32x16_bf16 v[34:49], v[66:69], v[78:81], v[34:49]
	v_mfma_f32_32x32x16_bf16 v[18:33], v[70:73], v[74:77], v[18:33]
	v_mfma_f32_32x32x16_bf16 v[2:17], v[70:73], v[78:81], v[2:17]
	ds_read_b128 v[66:69], v89 offset:16384
	ds_read_b128 v[70:73], v89 offset:20480
	ds_read_b128 v[74:77], v88 offset:49152
	ds_read_b128 v[78:81], v88 offset:53248
	s_waitcnt lgkmcnt(5)
	v_mfma_f32_32x32x16_bf16 v[50:65], v[94:97], v[102:105], v[50:65]
	s_waitcnt lgkmcnt(4)
	v_mfma_f32_32x32x16_bf16 v[34:49], v[94:97], v[90:93], v[34:49]
	v_mfma_f32_32x32x16_bf16 v[18:33], v[98:101], v[102:105], v[18:33]
	v_mfma_f32_32x32x16_bf16 v[2:17], v[98:101], v[90:93], v[2:17]
	ds_read_b128 v[88:91], v87 offset:16384
	ds_read_b128 v[92:95], v87 offset:20480
	ds_read_b128 v[96:99], v86 offset:49152
	ds_read_b128 v[100:103], v86 offset:53248
	s_waitcnt lgkmcnt(5)
	v_mfma_f32_32x32x16_bf16 v[50:65], v[66:69], v[74:77], v[50:65]
	v_lshlrev_b32_e32 v0, 6, v85
	v_subrev_u32_e32 v0, s2, v0
	s_lshl_b32 s3, s34, 7
	s_movk_i32 s2, 0x9c0
	s_waitcnt lgkmcnt(0)
	s_barrier
	v_mfma_f32_32x32x16_bf16 v[34:49], v[66:69], v[78:81], v[34:49]
	v_add_u32_e32 v66, s7, v0
	v_lshl_add_u32 v68, v83, 6, s3
	v_add_u32_e32 v0, v66, v84
	v_cmp_lt_i32_e64 s[40:41], s63, v0
	v_cmp_gt_u32_e32 vcc, s2, v66
	v_lshl_add_u64 v[66:67], v[0:1], 1, s[48:49]
	v_mfma_f32_32x32x16_bf16 v[18:33], v[70:73], v[74:77], v[18:33]
	v_mfma_f32_32x32x16_bf16 v[2:17], v[70:73], v[78:81], v[2:17]
	v_lshl_or_b32 v70, v82, 2, v68
	v_mfma_f32_32x32x16_bf16 v[50:65], v[88:91], v[96:99], v[50:65]
	v_mfma_f32_32x32x16_bf16 v[34:49], v[88:91], v[100:103], v[34:49]
	v_mfma_f32_32x32x16_bf16 v[18:33], v[92:95], v[96:99], v[18:33]
	v_mfma_f32_32x32x16_bf16 v[2:17], v[92:95], v[100:103], v[2:17]
	s_and_saveexec_b64 s[2:3], s[40:41]
	s_xor_b64 s[2:3], exec, s[2:3]
	s_cbranch_execz .LBB0_236
	s_and_saveexec_b64 s[4:5], vcc
	s_cbranch_execz .LBB0_235
	s_nop 3
	v_cvt_pk_bf16_f32 v71, v50, s0
	v_mad_i64_i32 v[68:69], s[34:35], v70, s68, v[66:67]
	global_store_short v[68:69], v71, off offset:-1920

.LBB0_1186:
	s_ashr_i32 s5, s4, 31
	s_lshr_b32 s5, s5, 29
	s_add_i32 s5, s4, s5
	s_ashr_i32 s34, s5, 3
	s_ashr_i32 s35, s34, 31
	v_readlane_b32 s36, v210, 50
	v_mov_b32_e32 v36, v133
	s_lshl_b64 s[6:7], s[34:35], 18
	v_readlane_b32 s38, v210, 52
	v_readlane_b32 s39, v210, 53
	v_ashrrev_i32_e32 v34, 3, v36
	s_add_u32 s6, s38, s6
	v_ashrrev_i32_e32 v35, 31, v34
	s_addc_u32 s7, s39, s7
	v_lshlrev_b64 v[2:3], 11, v[34:35]
	v_lshlrev_b32_e32 v0, 4, v36
	v_lshl_add_u64 v[2:3], s[6:7], 0, v[2:3]
	v_and_b32_e32 v0, 0x70, v0
	s_lshl_b32 s5, s34, 10
	v_lshl_add_u64 v[66:67], v[2:3], 0, v[0:1]
	v_subrev_u32_e32 v2, s5, v34
	v_add_u32_e32 v2, s3, v2
	v_ashrrev_i32_e32 v3, 31, v2
	v_lshlrev_b64 v[2:3], 11, v[2:3]
	v_lshl_add_u64 v[2:3], s[0:1], 0, v[2:3]
	v_add_co_u32_e32 v70, vcc, s10, v66
	v_lshl_add_u64 v[68:69], v[2:3], 0, v[0:1]
	s_nop 0
	v_addc_co_u32_e32 v71, vcc, 0, v67, vcc
	v_add_co_u32_e32 v72, vcc, s10, v68
	v_addc_co_u32_e32 v73, vcc, 0, v69, vcc
	v_add_co_u32_e32 v74, vcc, s63, v66
	s_nop 0
	v_addc_co_u32_e32 v75, vcc, 0, v67, vcc
	v_add_co_u32_e32 v76, vcc, s63, v68
	s_nop 0
	v_addc_co_u32_e32 v77, vcc, 0, v69, vcc
	v_add_co_u32_e32 v78, vcc, s61, v66
	s_nop 0
	v_addc_co_u32_e32 v79, vcc, 0, v67, vcc
	v_add_co_u32_e32 v80, vcc, s61, v68
	v_lshlrev_b32_e32 v0, 7, v34
	s_nop 0
	v_addc_co_u32_e32 v81, vcc, 0, v69, vcc
	v_lshrrev_b32_e32 v216, 4, v133
	v_xor_b32_e32 v216, v216, v133
	v_and_b32_e32 v216, 7, v216
	v_lshlrev_b32_e32 v216, 4, v216
	v_mov_b32_e32 v217, 0x70
	v_lshrrev_b32_e32 v218, 6, v133
	v_lshlrev_b32_e32 v218, 10, v218
	s_nop 0
	v_readfirstlane_b32 s32, v218
	v_bfi_b32 v66, v217, v216, v66
	v_bfi_b32 v70, v217, v216, v70
	v_bfi_b32 v74, v217, v216, v74
	v_bfi_b32 v78, v217, v216, v78
	v_bfi_b32 v68, v217, v216, v68
	v_bfi_b32 v72, v217, v216, v72
	v_bfi_b32 v76, v217, v216, v76
	v_bfi_b32 v80, v217, v216, v80
	s_mov_b64 s[98:99], 0x80
	s_add_u32 m0, s32, 0x0
	s_nop 0
	global_load_lds_dwordx4 v[66:67], off
	s_add_u32 m0, s32, 0x1000
	s_nop 0
	global_load_lds_dwordx4 v[70:71], off
	s_add_u32 m0, s32, 0x2000
	s_nop 0
	global_load_lds_dwordx4 v[74:75], off
	s_add_u32 m0, s32, 0x3000
	s_nop 0
	global_load_lds_dwordx4 v[78:79], off
	s_add_u32 m0, s32, 0x8000
	s_nop 0
	global_load_lds_dwordx4 v[68:69], off
	s_add_u32 m0, s32, 0x9000
	s_nop 0
	global_load_lds_dwordx4 v[72:73], off
	s_add_u32 m0, s32, 0xa000
	s_nop 0
	global_load_lds_dwordx4 v[76:77], off
	s_add_u32 m0, s32, 0xb000
	s_nop 0
	global_load_lds_dwordx4 v[80:81], off
	v_lshl_add_u64 v[66:67], v[66:67], 0, s[98:99]
	v_lshl_add_u64 v[70:71], v[70:71], 0, s[98:99]
	v_lshl_add_u64 v[74:75], v[74:75], 0, s[98:99]
	v_lshl_add_u64 v[78:79], v[78:79], 0, s[98:99]
	v_lshl_add_u64 v[68:69], v[68:69], 0, s[98:99]
	v_lshl_add_u64 v[72:73], v[72:73], 0, s[98:99]
	v_lshl_add_u64 v[76:77], v[76:77], 0, s[98:99]
	v_lshl_add_u64 v[80:81], v[80:81], 0, s[98:99]
	s_add_u32 m0, s32, 0x4000
	s_nop 0
	global_load_lds_dwordx4 v[66:67], off
	s_add_u32 m0, s32, 0x5000
	s_nop 0
	global_load_lds_dwordx4 v[70:71], off
	s_add_u32 m0, s32, 0x6000
	s_nop 0
	global_load_lds_dwordx4 v[74:75], off
	s_add_u32 m0, s32, 0x7000
	s_nop 0
	global_load_lds_dwordx4 v[78:79], off
	s_add_u32 m0, s32, 0xc000
	s_nop 0
	global_load_lds_dwordx4 v[68:69], off
	s_add_u32 m0, s32, 0xd000
	s_nop 0
	global_load_lds_dwordx4 v[72:73], off
	s_add_u32 m0, s32, 0xe000
	s_nop 0
	global_load_lds_dwordx4 v[76:77], off
	s_add_u32 m0, s32, 0xf000
	s_nop 0
	global_load_lds_dwordx4 v[80:81], off
	v_lshrrev_b32_e32 v34, 1, v34
	v_xor_b32_e32 v34, v34, v36
	v_lshlrev_b32_e32 v34, 4, v34
	s_movk_i32 s6, 0x70
	v_and_or_b32 v0, v34, s6, v0
	s_waitcnt vmcnt(26)
	v_and_b32_e32 v82, 31, v36
	v_bfe_u32 v85, v36, 5, 1
	v_ashrrev_i32_e32 v84, 7, v36
	v_bfe_u32 v83, v36, 6, 1
	v_readlane_b32 s37, v210, 51
	v_readlane_b32 s40, v210, 54
	v_readlane_b32 s41, v210, 55
	v_readlane_b32 s42, v210, 56
	v_readlane_b32 s43, v210, 57
	v_readlane_b32 s44, v210, 58
	v_readlane_b32 s45, v210, 59
	v_readlane_b32 s46, v210, 60
	v_readlane_b32 s47, v210, 61
	v_readlane_b32 s48, v210, 62
	v_readlane_b32 s49, v210, 63
	v_readlane_b32 s50, v209, 0
	v_readlane_b32 s51, v209, 1
	v_lshl_add_u64 v[66:67], v[66:67], 0, s[98:99]
	v_lshl_add_u64 v[70:71], v[70:71], 0, s[98:99]
	v_lshl_add_u64 v[74:75], v[74:75], 0, s[98:99]
	v_lshl_add_u64 v[78:79], v[78:79], 0, s[98:99]
	v_lshl_add_u64 v[68:69], v[68:69], 0, s[98:99]
	v_lshl_add_u64 v[72:73], v[72:73], 0, s[98:99]
	v_lshl_add_u64 v[76:77], v[76:77], 0, s[98:99]
	v_lshl_add_u64 v[80:81], v[80:81], 0, s[98:99]
	s_waitcnt vmcnt(8)
	s_waitcnt lgkmcnt(0)
	s_barrier
	v_lshrrev_b32_e32 v4, 1, v36
	v_lshlrev_b32_e32 v2, 7, v82
	v_bitop3_b32 v4, v4, v85, 7 bitop3:0x6c
	v_lshl_or_b32 v3, v84, 13, v2
	v_bfe_u32 v5, v36, 1, 3
	v_lshlrev_b32_e32 v4, 4, v4
	v_lshl_or_b32 v2, v83, 13, v2
	v_or_b32_e32 v91, v3, v4
	v_or_b32_e32 v92, v2, v4
	v_bitop3_b32 v4, v85, v5, 2 bitop3:0x36
	v_lshlrev_b32_e32 v4, 4, v4
	v_or_b32_e32 v93, v3, v4
	v_or_b32_e32 v90, v2, v4
	v_bitop3_b32 v4, v85, v5, 4 bitop3:0x36
	v_lshlrev_b32_e32 v4, 4, v4
	v_or_b32_e32 v89, v3, v4
	v_or_b32_e32 v88, v2, v4
	v_bitop3_b32 v4, v85, v5, 6 bitop3:0x36
	v_lshlrev_b32_e32 v4, 4, v4
	v_or_b32_e32 v87, v3, v4
	v_or_b32_e32 v86, v2, v4
	ds_read_b128 v[2:5], v91
	ds_read_b128 v[6:9], v92 offset:32768
	ds_read_b128 v[10:13], v91 offset:4096
	ds_read_b128 v[14:17], v92 offset:36864
	ds_read_b128 v[162:165], v93
	ds_read_b128 v[166:169], v90 offset:32768
	ds_read_b128 v[182:185], v93 offset:4096
	ds_read_b128 v[186:189], v90 offset:36864
	s_waitcnt lgkmcnt(6)
	v_mfma_f32_32x32x16_bf16 v[50:65], v[2:5], v[6:9], 0
	s_waitcnt lgkmcnt(4)
	v_mfma_f32_32x32x16_bf16 v[18:33], v[2:5], v[14:17], 0
	v_mfma_f32_32x32x16_bf16 v[34:49], v[10:13], v[6:9], 0
	v_mfma_f32_32x32x16_bf16 v[2:17], v[10:13], v[14:17], 0
	ds_read_b128 v[190:193], v89
	ds_read_b128 v[194:197], v89 offset:4096
	ds_read_b128 v[198:201], v88 offset:32768
	ds_read_b128 v[202:205], v88 offset:36864
	s_waitcnt lgkmcnt(6)
	v_mfma_f32_32x32x16_bf16 v[50:65], v[162:165], v[166:169], v[50:65]
	s_waitcnt lgkmcnt(4)
	v_mfma_f32_32x32x16_bf16 v[18:33], v[162:165], v[186:189], v[18:33]
	v_mfma_f32_32x32x16_bf16 v[34:49], v[182:185], v[166:169], v[34:49]
	v_mfma_f32_32x32x16_bf16 v[2:17], v[182:185], v[186:189], v[2:17]
	ds_read_b128 v[162:165], v87
	ds_read_b128 v[166:169], v87 offset:4096
	ds_read_b128 v[182:185], v86 offset:32768
	ds_read_b128 v[186:189], v86 offset:36864
	s_waitcnt lgkmcnt(0)
	s_barrier
	s_add_u32 m0, s32, 0x0
	v_mfma_f32_32x32x16_bf16 v[50:65], v[190:193], v[198:201], v[50:65]
	global_load_lds_dwordx4 v[66:67], off
	s_add_u32 m0, s32, 0x1000
	v_mfma_f32_32x32x16_bf16 v[18:33], v[190:193], v[202:205], v[18:33]
	global_load_lds_dwordx4 v[70:71], off
	s_add_u32 m0, s32, 0x2000
	v_mfma_f32_32x32x16_bf16 v[34:49], v[194:197], v[198:201], v[34:49]
	global_load_lds_dwordx4 v[74:75], off
	s_add_u32 m0, s32, 0x3000
	v_mfma_f32_32x32x16_bf16 v[2:17], v[194:197], v[202:205], v[2:17]
	global_load_lds_dwordx4 v[78:79], off
	s_add_u32 m0, s32, 0x8000
	v_mfma_f32_32x32x16_bf16 v[50:65], v[162:165], v[182:185], v[50:65]
	global_load_lds_dwordx4 v[68:69], off
	s_add_u32 m0, s32, 0x9000
	v_mfma_f32_32x32x16_bf16 v[18:33], v[162:165], v[186:189], v[18:33]
	global_load_lds_dwordx4 v[72:73], off
	s_add_u32 m0, s32, 0xa000
	v_mfma_f32_32x32x16_bf16 v[34:49], v[166:169], v[182:185], v[34:49]
	global_load_lds_dwordx4 v[76:77], off
	s_add_u32 m0, s32, 0xb000
	v_mfma_f32_32x32x16_bf16 v[2:17], v[166:169], v[186:189], v[2:17]
	global_load_lds_dwordx4 v[80:81], off
	s_waitcnt vmcnt(8)
	s_barrier
	ds_read_b128 v[162:165], v91 offset:16384
	ds_read_b128 v[166:169], v92 offset:49152
	ds_read_b128 v[182:185], v91 offset:20480
	ds_read_b128 v[186:189], v92 offset:53248
	ds_read_b128 v[190:193], v93 offset:16384
	ds_read_b128 v[194:197], v90 offset:49152
	ds_read_b128 v[198:201], v93 offset:20480
	ds_read_b128 v[202:205], v90 offset:53248
	s_waitcnt lgkmcnt(6)
	v_mfma_f32_32x32x16_bf16 v[50:65], v[162:165], v[166:169], v[50:65]
	s_waitcnt lgkmcnt(4)
	v_mfma_f32_32x32x16_bf16 v[18:33], v[162:165], v[186:189], v[18:33]
	v_mfma_f32_32x32x16_bf16 v[34:49], v[182:185], v[166:169], v[34:49]
	v_mfma_f32_32x32x16_bf16 v[2:17], v[182:185], v[186:189], v[2:17]
	ds_read_b128 v[162:165], v89 offset:16384
	ds_read_b128 v[166:169], v89 offset:20480
	ds_read_b128 v[182:185], v88 offset:49152
	ds_read_b128 v[186:189], v88 offset:53248
	s_waitcnt lgkmcnt(6)
	v_mfma_f32_32x32x16_bf16 v[50:65], v[190:193], v[194:197], v[50:65]
	s_waitcnt lgkmcnt(4)
	v_mfma_f32_32x32x16_bf16 v[18:33], v[190:193], v[202:205], v[18:33]
	v_mfma_f32_32x32x16_bf16 v[34:49], v[198:201], v[194:197], v[34:49]
	v_mfma_f32_32x32x16_bf16 v[2:17], v[198:201], v[202:205], v[2:17]
	ds_read_b128 v[190:193], v87 offset:16384
	ds_read_b128 v[194:197], v87 offset:20480
	ds_read_b128 v[198:201], v86 offset:49152
	ds_read_b128 v[202:205], v86 offset:53248
	v_lshl_add_u64 v[66:67], v[66:67], 0, s[98:99]
	v_lshl_add_u64 v[70:71], v[70:71], 0, s[98:99]
	v_lshl_add_u64 v[74:75], v[74:75], 0, s[98:99]
	v_lshl_add_u64 v[78:79], v[78:79], 0, s[98:99]
	v_lshl_add_u64 v[68:69], v[68:69], 0, s[98:99]
	v_lshl_add_u64 v[72:73], v[72:73], 0, s[98:99]
	v_lshl_add_u64 v[76:77], v[76:77], 0, s[98:99]
	v_lshl_add_u64 v[80:81], v[80:81], 0, s[98:99]
	s_waitcnt lgkmcnt(0)
	s_barrier
	s_add_u32 m0, s32, 0x4000
	v_mfma_f32_32x32x16_bf16 v[50:65], v[162:165], v[182:185], v[50:65]
	global_load_lds_dwordx4 v[66:67], off
	s_add_u32 m0, s32, 0x5000
	v_mfma_f32_32x32x16_bf16 v[18:33], v[162:165], v[186:189], v[18:33]
	global_load_lds_dwordx4 v[70:71], off
	s_add_u32 m0, s32, 0x6000
	v_mfma_f32_32x32x16_bf16 v[34:49], v[166:169], v[182:185], v[34:49]
	global_load_lds_dwordx4 v[74:75], off
	s_add_u32 m0, s32, 0x7000
	v_mfma_f32_32x32x16_bf16 v[2:17], v[166:169], v[186:189], v[2:17]
	global_load_lds_dwordx4 v[78:79], off
	s_add_u32 m0, s32, 0xc000
	v_mfma_f32_32x32x16_bf16 v[50:65], v[190:193], v[198:201], v[50:65]
	global_load_lds_dwordx4 v[68:69], off
	s_add_u32 m0, s32, 0xd000
	v_mfma_f32_32x32x16_bf16 v[18:33], v[190:193], v[202:205], v[18:33]
	global_load_lds_dwordx4 v[72:73], off
	s_add_u32 m0, s32, 0xe000
	v_mfma_f32_32x32x16_bf16 v[34:49], v[194:197], v[198:201], v[34:49]
	global_load_lds_dwordx4 v[76:77], off
	s_add_u32 m0, s32, 0xf000
	v_mfma_f32_32x32x16_bf16 v[2:17], v[194:197], v[202:205], v[2:17]
	global_load_lds_dwordx4 v[80:81], off
	s_waitcnt vmcnt(8)
	s_barrier
	ds_read_b128 v[162:165], v91
	ds_read_b128 v[166:169], v92 offset:32768
	ds_read_b128 v[182:185], v91 offset:4096
	ds_read_b128 v[186:189], v92 offset:36864
	ds_read_b128 v[190:193], v93
	ds_read_b128 v[194:197], v90 offset:32768
	ds_read_b128 v[198:201], v93 offset:4096
	ds_read_b128 v[202:205], v90 offset:36864
	s_waitcnt lgkmcnt(6)
	v_mfma_f32_32x32x16_bf16 v[50:65], v[162:165], v[166:169], v[50:65]
	s_waitcnt lgkmcnt(4)
	v_mfma_f32_32x32x16_bf16 v[18:33], v[162:165], v[186:189], v[18:33]
	v_mfma_f32_32x32x16_bf16 v[34:49], v[182:185], v[166:169], v[34:49]
	v_mfma_f32_32x32x16_bf16 v[2:17], v[182:185], v[186:189], v[2:17]
	ds_read_b128 v[162:165], v89
	ds_read_b128 v[166:169], v89 offset:4096
	ds_read_b128 v[182:185], v88 offset:32768
	ds_read_b128 v[186:189], v88 offset:36864
	s_waitcnt lgkmcnt(6)
	v_mfma_f32_32x32x16_bf16 v[50:65], v[190:193], v[194:197], v[50:65]
	s_waitcnt lgkmcnt(4)
	v_mfma_f32_32x32x16_bf16 v[18:33], v[190:193], v[202:205], v[18:33]
	v_mfma_f32_32x32x16_bf16 v[34:49], v[198:201], v[194:197], v[34:49]
	v_mfma_f32_32x32x16_bf16 v[2:17], v[198:201], v[202:205], v[2:17]
	ds_read_b128 v[190:193], v87
	ds_read_b128 v[194:197], v87 offset:4096
	ds_read_b128 v[198:201], v86 offset:32768
	ds_read_b128 v[202:205], v86 offset:36864
	v_lshl_add_u64 v[66:67], v[66:67], 0, s[98:99]
	v_lshl_add_u64 v[70:71], v[70:71], 0, s[98:99]
	v_lshl_add_u64 v[74:75], v[74:75], 0, s[98:99]
	v_lshl_add_u64 v[78:79], v[78:79], 0, s[98:99]
	v_lshl_add_u64 v[68:69], v[68:69], 0, s[98:99]
	v_lshl_add_u64 v[72:73], v[72:73], 0, s[98:99]
	v_lshl_add_u64 v[76:77], v[76:77], 0, s[98:99]
	v_lshl_add_u64 v[80:81], v[80:81], 0, s[98:99]
	s_waitcnt lgkmcnt(0)
	s_barrier
	s_add_u32 m0, s32, 0x0
	v_mfma_f32_32x32x16_bf16 v[50:65], v[162:165], v[182:185], v[50:65]
	global_load_lds_dwordx4 v[66:67], off
	s_add_u32 m0, s32, 0x1000
	v_mfma_f32_32x32x16_bf16 v[18:33], v[162:165], v[186:189], v[18:33]
	global_load_lds_dwordx4 v[70:71], off
	s_add_u32 m0, s32, 0x2000
	v_mfma_f32_32x32x16_bf16 v[34:49], v[166:169], v[182:185], v[34:49]
	global_load_lds_dwordx4 v[74:75], off
	s_add_u32 m0, s32, 0x3000
	v_mfma_f32_32x32x16_bf16 v[2:17], v[166:169], v[186:189], v[2:17]
	global_load_lds_dwordx4 v[78:79], off
	s_add_u32 m0, s32, 0x8000
	v_mfma_f32_32x32x16_bf16 v[50:65], v[190:193], v[198:201], v[50:65]
	global_load_lds_dwordx4 v[68:69], off
	s_add_u32 m0, s32, 0x9000
	v_mfma_f32_32x32x16_bf16 v[18:33], v[190:193], v[202:205], v[18:33]
	global_load_lds_dwordx4 v[72:73], off
	s_add_u32 m0, s32, 0xa000
	v_mfma_f32_32x32x16_bf16 v[34:49], v[194:197], v[198:201], v[34:49]
	global_load_lds_dwordx4 v[76:77], off
	s_add_u32 m0, s32, 0xb000
	v_mfma_f32_32x32x16_bf16 v[2:17], v[194:197], v[202:205], v[2:17]
	global_load_lds_dwordx4 v[80:81], off
	s_waitcnt vmcnt(8)
	s_barrier
	ds_read_b128 v[162:165], v91 offset:16384
	ds_read_b128 v[166:169], v92 offset:49152
	ds_read_b128 v[182:185], v91 offset:20480
	ds_read_b128 v[186:189], v92 offset:53248
	ds_read_b128 v[190:193], v93 offset:16384
	ds_read_b128 v[194:197], v90 offset:49152
	ds_read_b128 v[198:201], v93 offset:20480
	ds_read_b128 v[202:205], v90 offset:53248
	s_waitcnt lgkmcnt(6)
	v_mfma_f32_32x32x16_bf16 v[50:65], v[162:165], v[166:169], v[50:65]
	s_waitcnt lgkmcnt(4)
	v_mfma_f32_32x32x16_bf16 v[18:33], v[162:165], v[186:189], v[18:33]
	v_mfma_f32_32x32x16_bf16 v[34:49], v[182:185], v[166:169], v[34:49]
	v_mfma_f32_32x32x16_bf16 v[2:17], v[182:185], v[186:189], v[2:17]
	ds_read_b128 v[162:165], v89 offset:16384
	ds_read_b128 v[166:169], v89 offset:20480
	ds_read_b128 v[182:185], v88 offset:49152
	ds_read_b128 v[186:189], v88 offset:53248
	s_waitcnt lgkmcnt(6)
	v_mfma_f32_32x32x16_bf16 v[50:65], v[190:193], v[194:197], v[50:65]
	s_waitcnt lgkmcnt(4)
	v_mfma_f32_32x32x16_bf16 v[18:33], v[190:193], v[202:205], v[18:33]
	v_mfma_f32_32x32x16_bf16 v[34:49], v[198:201], v[194:197], v[34:49]
	v_mfma_f32_32x32x16_bf16 v[2:17], v[198:201], v[202:205], v[2:17]
	ds_read_b128 v[190:193], v87 offset:16384
	ds_read_b128 v[194:197], v87 offset:20480
	ds_read_b128 v[198:201], v86 offset:49152
	ds_read_b128 v[202:205], v86 offset:53248
	v_lshl_add_u64 v[66:67], v[66:67], 0, s[98:99]
	v_lshl_add_u64 v[70:71], v[70:71], 0, s[98:99]
	v_lshl_add_u64 v[74:75], v[74:75], 0, s[98:99]
	v_lshl_add_u64 v[78:79], v[78:79], 0, s[98:99]
	v_lshl_add_u64 v[68:69], v[68:69], 0, s[98:99]
	v_lshl_add_u64 v[72:73], v[72:73], 0, s[98:99]
	v_lshl_add_u64 v[76:77], v[76:77], 0, s[98:99]
	v_lshl_add_u64 v[80:81], v[80:81], 0, s[98:99]
	s_waitcnt lgkmcnt(0)
	s_barrier
	s_add_u32 m0, s32, 0x4000
	v_mfma_f32_32x32x16_bf16 v[50:65], v[162:165], v[182:185], v[50:65]
	global_load_lds_dwordx4 v[66:67], off
	s_add_u32 m0, s32, 0x5000
	v_mfma_f32_32x32x16_bf16 v[18:33], v[162:165], v[186:189], v[18:33]
	global_load_lds_dwordx4 v[70:71], off
	s_add_u32 m0, s32, 0x6000
	v_mfma_f32_32x32x16_bf16 v[34:49], v[166:169], v[182:185], v[34:49]
	global_load_lds_dwordx4 v[74:75], off
	s_add_u32 m0, s32, 0x7000
	v_mfma_f32_32x32x16_bf16 v[2:17], v[166:169], v[186:189], v[2:17]
	global_load_lds_dwordx4 v[78:79], off
	s_add_u32 m0, s32, 0xc000
	v_mfma_f32_32x32x16_bf16 v[50:65], v[190:193], v[198:201], v[50:65]
	global_load_lds_dwordx4 v[68:69], off
	s_add_u32 m0, s32, 0xd000
	v_mfma_f32_32x32x16_bf16 v[18:33], v[190:193], v[202:205], v[18:33]
	global_load_lds_dwordx4 v[72:73], off
	s_add_u32 m0, s32, 0xe000
	v_mfma_f32_32x32x16_bf16 v[34:49], v[194:197], v[198:201], v[34:49]
	global_load_lds_dwordx4 v[76:77], off
	s_add_u32 m0, s32, 0xf000
	v_mfma_f32_32x32x16_bf16 v[2:17], v[194:197], v[202:205], v[2:17]
	global_load_lds_dwordx4 v[80:81], off
	s_waitcnt vmcnt(8)
	s_barrier
	ds_read_b128 v[162:165], v91
	ds_read_b128 v[166:169], v92 offset:32768
	ds_read_b128 v[182:185], v91 offset:4096
	ds_read_b128 v[186:189], v92 offset:36864
	ds_read_b128 v[190:193], v93
	ds_read_b128 v[194:197], v90 offset:32768
	ds_read_b128 v[198:201], v93 offset:4096
	ds_read_b128 v[202:205], v90 offset:36864
	s_waitcnt lgkmcnt(6)
	v_mfma_f32_32x32x16_bf16 v[50:65], v[162:165], v[166:169], v[50:65]
	s_waitcnt lgkmcnt(4)
	v_mfma_f32_32x32x16_bf16 v[18:33], v[162:165], v[186:189], v[18:33]
	v_mfma_f32_32x32x16_bf16 v[34:49], v[182:185], v[166:169], v[34:49]
	v_mfma_f32_32x32x16_bf16 v[2:17], v[182:185], v[186:189], v[2:17]
	ds_read_b128 v[162:165], v89
	ds_read_b128 v[166:169], v89 offset:4096
	ds_read_b128 v[182:185], v88 offset:32768
	ds_read_b128 v[186:189], v88 offset:36864
	s_waitcnt lgkmcnt(6)
	v_mfma_f32_32x32x16_bf16 v[50:65], v[190:193], v[194:197], v[50:65]
	s_waitcnt lgkmcnt(4)
	v_mfma_f32_32x32x16_bf16 v[18:33], v[190:193], v[202:205], v[18:33]
	v_mfma_f32_32x32x16_bf16 v[34:49], v[198:201], v[194:197], v[34:49]
	v_mfma_f32_32x32x16_bf16 v[2:17], v[198:201], v[202:205], v[2:17]
	ds_read_b128 v[190:193], v87
	ds_read_b128 v[194:197], v87 offset:4096
	ds_read_b128 v[198:201], v86 offset:32768
	ds_read_b128 v[202:205], v86 offset:36864
	v_lshl_add_u64 v[66:67], v[66:67], 0, s[98:99]
	v_lshl_add_u64 v[70:71], v[70:71], 0, s[98:99]
	v_lshl_add_u64 v[74:75], v[74:75], 0, s[98:99]
	v_lshl_add_u64 v[78:79], v[78:79], 0, s[98:99]
	v_lshl_add_u64 v[68:69], v[68:69], 0, s[98:99]
	v_lshl_add_u64 v[72:73], v[72:73], 0, s[98:99]
	v_lshl_add_u64 v[76:77], v[76:77], 0, s[98:99]
	v_lshl_add_u64 v[80:81], v[80:81], 0, s[98:99]
	s_waitcnt lgkmcnt(0)
	s_barrier
	s_add_u32 m0, s32, 0x0
	v_mfma_f32_32x32x16_bf16 v[50:65], v[162:165], v[182:185], v[50:65]
	global_load_lds_dwordx4 v[66:67], off
	s_add_u32 m0, s32, 0x1000
	v_mfma_f32_32x32x16_bf16 v[18:33], v[162:165], v[186:189], v[18:33]
	global_load_lds_dwordx4 v[70:71], off
	s_add_u32 m0, s32, 0x2000
	v_mfma_f32_32x32x16_bf16 v[34:49], v[166:169], v[182:185], v[34:49]
	global_load_lds_dwordx4 v[74:75], off
	s_add_u32 m0, s32, 0x3000
	v_mfma_f32_32x32x16_bf16 v[2:17], v[166:169], v[186:189], v[2:17]
	global_load_lds_dwordx4 v[78:79], off
	s_add_u32 m0, s32, 0x8000
	v_mfma_f32_32x32x16_bf16 v[50:65], v[190:193], v[198:201], v[50:65]
	global_load_lds_dwordx4 v[68:69], off
	s_add_u32 m0, s32, 0x9000
	v_mfma_f32_32x32x16_bf16 v[18:33], v[190:193], v[202:205], v[18:33]
	global_load_lds_dwordx4 v[72:73], off
	s_add_u32 m0, s32, 0xa000
	v_mfma_f32_32x32x16_bf16 v[34:49], v[194:197], v[198:201], v[34:49]
	global_load_lds_dwordx4 v[76:77], off
	s_add_u32 m0, s32, 0xb000
	v_mfma_f32_32x32x16_bf16 v[2:17], v[194:197], v[202:205], v[2:17]
	global_load_lds_dwordx4 v[80:81], off
	s_waitcnt vmcnt(8)
	s_barrier
	ds_read_b128 v[162:165], v91 offset:16384
	ds_read_b128 v[166:169], v92 offset:49152
	ds_read_b128 v[182:185], v91 offset:20480
	ds_read_b128 v[186:189], v92 offset:53248
	ds_read_b128 v[190:193], v93 offset:16384
	ds_read_b128 v[194:197], v90 offset:49152
	ds_read_b128 v[198:201], v93 offset:20480
	ds_read_b128 v[202:205], v90 offset:53248
	s_waitcnt lgkmcnt(6)
	v_mfma_f32_32x32x16_bf16 v[50:65], v[162:165], v[166:169], v[50:65]
	s_waitcnt lgkmcnt(4)
	v_mfma_f32_32x32x16_bf16 v[18:33], v[162:165], v[186:189], v[18:33]
	v_mfma_f32_32x32x16_bf16 v[34:49], v[182:185], v[166:169], v[34:49]
	v_mfma_f32_32x32x16_bf16 v[2:17], v[182:185], v[186:189], v[2:17]
	ds_read_b128 v[162:165], v89 offset:16384
	ds_read_b128 v[166:169], v89 offset:20480
	ds_read_b128 v[182:185], v88 offset:49152
	ds_read_b128 v[186:189], v88 offset:53248
	s_waitcnt lgkmcnt(6)
	v_mfma_f32_32x32x16_bf16 v[50:65], v[190:193], v[194:197], v[50:65]
	s_waitcnt lgkmcnt(4)
	v_mfma_f32_32x32x16_bf16 v[18:33], v[190:193], v[202:205], v[18:33]
	v_mfma_f32_32x32x16_bf16 v[34:49], v[198:201], v[194:197], v[34:49]
	v_mfma_f32_32x32x16_bf16 v[2:17], v[198:201], v[202:205], v[2:17]
	ds_read_b128 v[190:193], v87 offset:16384
	ds_read_b128 v[194:197], v87 offset:20480
	ds_read_b128 v[198:201], v86 offset:49152
	ds_read_b128 v[202:205], v86 offset:53248
	v_lshl_add_u64 v[66:67], v[66:67], 0, s[98:99]
	v_lshl_add_u64 v[70:71], v[70:71], 0, s[98:99]
	v_lshl_add_u64 v[74:75], v[74:75], 0, s[98:99]
	v_lshl_add_u64 v[78:79], v[78:79], 0, s[98:99]
	v_lshl_add_u64 v[68:69], v[68:69], 0, s[98:99]
	v_lshl_add_u64 v[72:73], v[72:73], 0, s[98:99]
	v_lshl_add_u64 v[76:77], v[76:77], 0, s[98:99]
	v_lshl_add_u64 v[80:81], v[80:81], 0, s[98:99]
	s_waitcnt lgkmcnt(0)
	s_barrier
	s_add_u32 m0, s32, 0x4000
	v_mfma_f32_32x32x16_bf16 v[50:65], v[162:165], v[182:185], v[50:65]
	global_load_lds_dwordx4 v[66:67], off
	s_add_u32 m0, s32, 0x5000
	v_mfma_f32_32x32x16_bf16 v[18:33], v[162:165], v[186:189], v[18:33]
	global_load_lds_dwordx4 v[70:71], off
	s_add_u32 m0, s32, 0x6000
	v_mfma_f32_32x32x16_bf16 v[34:49], v[166:169], v[182:185], v[34:49]
	global_load_lds_dwordx4 v[74:75], off
	s_add_u32 m0, s32, 0x7000
	v_mfma_f32_32x32x16_bf16 v[2:17], v[166:169], v[186:189], v[2:17]
	global_load_lds_dwordx4 v[78:79], off
	s_add_u32 m0, s32, 0xc000
	v_mfma_f32_32x32x16_bf16 v[50:65], v[190:193], v[198:201], v[50:65]
	global_load_lds_dwordx4 v[68:69], off
	s_add_u32 m0, s32, 0xd000
	v_mfma_f32_32x32x16_bf16 v[18:33], v[190:193], v[202:205], v[18:33]
	global_load_lds_dwordx4 v[72:73], off
	s_add_u32 m0, s32, 0xe000
	v_mfma_f32_32x32x16_bf16 v[34:49], v[194:197], v[198:201], v[34:49]
	global_load_lds_dwordx4 v[76:77], off
	s_add_u32 m0, s32, 0xf000
	v_mfma_f32_32x32x16_bf16 v[2:17], v[194:197], v[202:205], v[2:17]
	global_load_lds_dwordx4 v[80:81], off
	s_waitcnt vmcnt(8)
	s_barrier
	ds_read_b128 v[162:165], v91
	ds_read_b128 v[166:169], v92 offset:32768
	ds_read_b128 v[182:185], v91 offset:4096
	ds_read_b128 v[186:189], v92 offset:36864
	ds_read_b128 v[190:193], v93
	ds_read_b128 v[194:197], v90 offset:32768
	ds_read_b128 v[198:201], v93 offset:4096
	ds_read_b128 v[202:205], v90 offset:36864
	s_waitcnt lgkmcnt(6)
	v_mfma_f32_32x32x16_bf16 v[50:65], v[162:165], v[166:169], v[50:65]
	s_waitcnt lgkmcnt(4)
	v_mfma_f32_32x32x16_bf16 v[18:33], v[162:165], v[186:189], v[18:33]
	v_mfma_f32_32x32x16_bf16 v[34:49], v[182:185], v[166:169], v[34:49]
	v_mfma_f32_32x32x16_bf16 v[2:17], v[182:185], v[186:189], v[2:17]
	ds_read_b128 v[162:165], v89
	ds_read_b128 v[166:169], v89 offset:4096
	ds_read_b128 v[182:185], v88 offset:32768
	ds_read_b128 v[186:189], v88 offset:36864
	s_waitcnt lgkmcnt(6)
	v_mfma_f32_32x32x16_bf16 v[50:65], v[190:193], v[194:197], v[50:65]
	s_waitcnt lgkmcnt(4)
	v_mfma_f32_32x32x16_bf16 v[18:33], v[190:193], v[202:205], v[18:33]
	v_mfma_f32_32x32x16_bf16 v[34:49], v[198:201], v[194:197], v[34:49]
	v_mfma_f32_32x32x16_bf16 v[2:17], v[198:201], v[202:205], v[2:17]
	ds_read_b128 v[190:193], v87
	ds_read_b128 v[194:197], v87 offset:4096
	ds_read_b128 v[198:201], v86 offset:32768
	ds_read_b128 v[202:205], v86 offset:36864
	v_lshl_add_u64 v[66:67], v[66:67], 0, s[98:99]
	v_lshl_add_u64 v[70:71], v[70:71], 0, s[98:99]
	v_lshl_add_u64 v[74:75], v[74:75], 0, s[98:99]
	v_lshl_add_u64 v[78:79], v[78:79], 0, s[98:99]
	v_lshl_add_u64 v[68:69], v[68:69], 0, s[98:99]
	v_lshl_add_u64 v[72:73], v[72:73], 0, s[98:99]
	v_lshl_add_u64 v[76:77], v[76:77], 0, s[98:99]
	v_lshl_add_u64 v[80:81], v[80:81], 0, s[98:99]
	s_waitcnt lgkmcnt(0)
	s_barrier
	s_add_u32 m0, s32, 0x0
	v_mfma_f32_32x32x16_bf16 v[50:65], v[162:165], v[182:185], v[50:65]
	global_load_lds_dwordx4 v[66:67], off
	s_add_u32 m0, s32, 0x1000
	v_mfma_f32_32x32x16_bf16 v[18:33], v[162:165], v[186:189], v[18:33]
	global_load_lds_dwordx4 v[70:71], off
	s_add_u32 m0, s32, 0x2000
	v_mfma_f32_32x32x16_bf16 v[34:49], v[166:169], v[182:185], v[34:49]
	global_load_lds_dwordx4 v[74:75], off
	s_add_u32 m0, s32, 0x3000
	v_mfma_f32_32x32x16_bf16 v[2:17], v[166:169], v[186:189], v[2:17]
	global_load_lds_dwordx4 v[78:79], off
	s_add_u32 m0, s32, 0x8000
	v_mfma_f32_32x32x16_bf16 v[50:65], v[190:193], v[198:201], v[50:65]
	global_load_lds_dwordx4 v[68:69], off
	s_add_u32 m0, s32, 0x9000
	v_mfma_f32_32x32x16_bf16 v[18:33], v[190:193], v[202:205], v[18:33]
	global_load_lds_dwordx4 v[72:73], off
	s_add_u32 m0, s32, 0xa000
	v_mfma_f32_32x32x16_bf16 v[34:49], v[194:197], v[198:201], v[34:49]
	global_load_lds_dwordx4 v[76:77], off
	s_add_u32 m0, s32, 0xb000
	v_mfma_f32_32x32x16_bf16 v[2:17], v[194:197], v[202:205], v[2:17]
	global_load_lds_dwordx4 v[80:81], off
	s_waitcnt vmcnt(8)
	s_barrier
	ds_read_b128 v[162:165], v91 offset:16384
	ds_read_b128 v[166:169], v92 offset:49152
	ds_read_b128 v[182:185], v91 offset:20480
	ds_read_b128 v[186:189], v92 offset:53248
	ds_read_b128 v[190:193], v93 offset:16384
	ds_read_b128 v[194:197], v90 offset:49152
	ds_read_b128 v[198:201], v93 offset:20480
	ds_read_b128 v[202:205], v90 offset:53248
	s_waitcnt lgkmcnt(6)
	v_mfma_f32_32x32x16_bf16 v[50:65], v[162:165], v[166:169], v[50:65]
	s_waitcnt lgkmcnt(4)
	v_mfma_f32_32x32x16_bf16 v[18:33], v[162:165], v[186:189], v[18:33]
	v_mfma_f32_32x32x16_bf16 v[34:49], v[182:185], v[166:169], v[34:49]
	v_mfma_f32_32x32x16_bf16 v[2:17], v[182:185], v[186:189], v[2:17]
	ds_read_b128 v[162:165], v89 offset:16384
	ds_read_b128 v[166:169], v89 offset:20480
	ds_read_b128 v[182:185], v88 offset:49152
	ds_read_b128 v[186:189], v88 offset:53248
	s_waitcnt lgkmcnt(6)
	v_mfma_f32_32x32x16_bf16 v[50:65], v[190:193], v[194:197], v[50:65]
	s_waitcnt lgkmcnt(4)
	v_mfma_f32_32x32x16_bf16 v[18:33], v[190:193], v[202:205], v[18:33]
	v_mfma_f32_32x32x16_bf16 v[34:49], v[198:201], v[194:197], v[34:49]
	v_mfma_f32_32x32x16_bf16 v[2:17], v[198:201], v[202:205], v[2:17]
	ds_read_b128 v[190:193], v87 offset:16384
	ds_read_b128 v[194:197], v87 offset:20480
	ds_read_b128 v[198:201], v86 offset:49152
	ds_read_b128 v[202:205], v86 offset:53248
	v_lshl_add_u64 v[66:67], v[66:67], 0, s[98:99]
	v_lshl_add_u64 v[70:71], v[70:71], 0, s[98:99]
	v_lshl_add_u64 v[74:75], v[74:75], 0, s[98:99]
	v_lshl_add_u64 v[78:79], v[78:79], 0, s[98:99]
	v_lshl_add_u64 v[68:69], v[68:69], 0, s[98:99]
	v_lshl_add_u64 v[72:73], v[72:73], 0, s[98:99]
	v_lshl_add_u64 v[76:77], v[76:77], 0, s[98:99]
	v_lshl_add_u64 v[80:81], v[80:81], 0, s[98:99]
	s_waitcnt lgkmcnt(0)
	s_barrier
	s_add_u32 m0, s32, 0x4000
	v_mfma_f32_32x32x16_bf16 v[50:65], v[162:165], v[182:185], v[50:65]
	global_load_lds_dwordx4 v[66:67], off
	s_add_u32 m0, s32, 0x5000
	v_mfma_f32_32x32x16_bf16 v[18:33], v[162:165], v[186:189], v[18:33]
	global_load_lds_dwordx4 v[70:71], off
	s_add_u32 m0, s32, 0x6000
	v_mfma_f32_32x32x16_bf16 v[34:49], v[166:169], v[182:185], v[34:49]
	global_load_lds_dwordx4 v[74:75], off
	s_add_u32 m0, s32, 0x7000
	v_mfma_f32_32x32x16_bf16 v[2:17], v[166:169], v[186:189], v[2:17]
	global_load_lds_dwordx4 v[78:79], off
	s_add_u32 m0, s32, 0xc000
	v_mfma_f32_32x32x16_bf16 v[50:65], v[190:193], v[198:201], v[50:65]
	global_load_lds_dwordx4 v[68:69], off
	s_add_u32 m0, s32, 0xd000
	v_mfma_f32_32x32x16_bf16 v[18:33], v[190:193], v[202:205], v[18:33]
	global_load_lds_dwordx4 v[72:73], off
	s_add_u32 m0, s32, 0xe000
	v_mfma_f32_32x32x16_bf16 v[34:49], v[194:197], v[198:201], v[34:49]
	global_load_lds_dwordx4 v[76:77], off
	s_add_u32 m0, s32, 0xf000
	v_mfma_f32_32x32x16_bf16 v[2:17], v[194:197], v[202:205], v[2:17]
	global_load_lds_dwordx4 v[80:81], off
	s_waitcnt vmcnt(8)
	s_barrier
	ds_read_b128 v[162:165], v91
	ds_read_b128 v[166:169], v92 offset:32768
	ds_read_b128 v[182:185], v91 offset:4096
	ds_read_b128 v[186:189], v92 offset:36864
	ds_read_b128 v[190:193], v93
	ds_read_b128 v[194:197], v90 offset:32768
	ds_read_b128 v[198:201], v93 offset:4096
	ds_read_b128 v[202:205], v90 offset:36864
	s_waitcnt lgkmcnt(6)
	v_mfma_f32_32x32x16_bf16 v[50:65], v[162:165], v[166:169], v[50:65]
	s_waitcnt lgkmcnt(4)
	v_mfma_f32_32x32x16_bf16 v[18:33], v[162:165], v[186:189], v[18:33]
	v_mfma_f32_32x32x16_bf16 v[34:49], v[182:185], v[166:169], v[34:49]
	v_mfma_f32_32x32x16_bf16 v[2:17], v[182:185], v[186:189], v[2:17]
	ds_read_b128 v[162:165], v89
	ds_read_b128 v[166:169], v89 offset:4096
	ds_read_b128 v[182:185], v88 offset:32768
	ds_read_b128 v[186:189], v88 offset:36864
	s_waitcnt lgkmcnt(6)
	v_mfma_f32_32x32x16_bf16 v[50:65], v[190:193], v[194:197], v[50:65]
	s_waitcnt lgkmcnt(4)
	v_mfma_f32_32x32x16_bf16 v[18:33], v[190:193], v[202:205], v[18:33]
	v_mfma_f32_32x32x16_bf16 v[34:49], v[198:201], v[194:197], v[34:49]
	v_mfma_f32_32x32x16_bf16 v[2:17], v[198:201], v[202:205], v[2:17]
	ds_read_b128 v[190:193], v87
	ds_read_b128 v[194:197], v87 offset:4096
	ds_read_b128 v[198:201], v86 offset:32768
	ds_read_b128 v[202:205], v86 offset:36864
	v_lshl_add_u64 v[66:67], v[66:67], 0, s[98:99]
	v_lshl_add_u64 v[70:71], v[70:71], 0, s[98:99]
	v_lshl_add_u64 v[74:75], v[74:75], 0, s[98:99]
	v_lshl_add_u64 v[78:79], v[78:79], 0, s[98:99]
	v_lshl_add_u64 v[68:69], v[68:69], 0, s[98:99]
	v_lshl_add_u64 v[72:73], v[72:73], 0, s[98:99]
	v_lshl_add_u64 v[76:77], v[76:77], 0, s[98:99]
	v_lshl_add_u64 v[80:81], v[80:81], 0, s[98:99]
	s_waitcnt lgkmcnt(0)
	s_barrier
	s_add_u32 m0, s32, 0x0
	v_mfma_f32_32x32x16_bf16 v[50:65], v[162:165], v[182:185], v[50:65]
	global_load_lds_dwordx4 v[66:67], off
	s_add_u32 m0, s32, 0x1000
	v_mfma_f32_32x32x16_bf16 v[18:33], v[162:165], v[186:189], v[18:33]
	global_load_lds_dwordx4 v[70:71], off
	s_add_u32 m0, s32, 0x2000
	v_mfma_f32_32x32x16_bf16 v[34:49], v[166:169], v[182:185], v[34:49]
	global_load_lds_dwordx4 v[74:75], off
	s_add_u32 m0, s32, 0x3000
	v_mfma_f32_32x32x16_bf16 v[2:17], v[166:169], v[186:189], v[2:17]
	global_load_lds_dwordx4 v[78:79], off
	s_add_u32 m0, s32, 0x8000
	v_mfma_f32_32x32x16_bf16 v[50:65], v[190:193], v[198:201], v[50:65]
	global_load_lds_dwordx4 v[68:69], off
	s_add_u32 m0, s32, 0x9000
	v_mfma_f32_32x32x16_bf16 v[18:33], v[190:193], v[202:205], v[18:33]
	global_load_lds_dwordx4 v[72:73], off
	s_add_u32 m0, s32, 0xa000
	v_mfma_f32_32x32x16_bf16 v[34:49], v[194:197], v[198:201], v[34:49]
	global_load_lds_dwordx4 v[76:77], off
	s_add_u32 m0, s32, 0xb000
	v_mfma_f32_32x32x16_bf16 v[2:17], v[194:197], v[202:205], v[2:17]
	global_load_lds_dwordx4 v[80:81], off
	s_waitcnt vmcnt(8)
	s_barrier
	ds_read_b128 v[162:165], v91 offset:16384
	ds_read_b128 v[166:169], v92 offset:49152
	ds_read_b128 v[182:185], v91 offset:20480
	ds_read_b128 v[186:189], v92 offset:53248
	ds_read_b128 v[190:193], v93 offset:16384
	ds_read_b128 v[194:197], v90 offset:49152
	ds_read_b128 v[198:201], v93 offset:20480
	ds_read_b128 v[202:205], v90 offset:53248
	s_waitcnt lgkmcnt(6)
	v_mfma_f32_32x32x16_bf16 v[50:65], v[162:165], v[166:169], v[50:65]
	s_waitcnt lgkmcnt(4)
	v_mfma_f32_32x32x16_bf16 v[18:33], v[162:165], v[186:189], v[18:33]
	v_mfma_f32_32x32x16_bf16 v[34:49], v[182:185], v[166:169], v[34:49]
	v_mfma_f32_32x32x16_bf16 v[2:17], v[182:185], v[186:189], v[2:17]
	ds_read_b128 v[162:165], v89 offset:16384
	ds_read_b128 v[166:169], v89 offset:20480
	ds_read_b128 v[182:185], v88 offset:49152
	ds_read_b128 v[186:189], v88 offset:53248
	s_waitcnt lgkmcnt(6)
	v_mfma_f32_32x32x16_bf16 v[50:65], v[190:193], v[194:197], v[50:65]
	s_waitcnt lgkmcnt(4)
	v_mfma_f32_32x32x16_bf16 v[18:33], v[190:193], v[202:205], v[18:33]
	v_mfma_f32_32x32x16_bf16 v[34:49], v[198:201], v[194:197], v[34:49]
	v_mfma_f32_32x32x16_bf16 v[2:17], v[198:201], v[202:205], v[2:17]
	ds_read_b128 v[190:193], v87 offset:16384
	ds_read_b128 v[194:197], v87 offset:20480
	ds_read_b128 v[198:201], v86 offset:49152
	ds_read_b128 v[202:205], v86 offset:53248
	v_lshl_add_u64 v[66:67], v[66:67], 0, s[98:99]
	v_lshl_add_u64 v[70:71], v[70:71], 0, s[98:99]
	v_lshl_add_u64 v[74:75], v[74:75], 0, s[98:99]
	v_lshl_add_u64 v[78:79], v[78:79], 0, s[98:99]
	v_lshl_add_u64 v[68:69], v[68:69], 0, s[98:99]
	v_lshl_add_u64 v[72:73], v[72:73], 0, s[98:99]
	v_lshl_add_u64 v[76:77], v[76:77], 0, s[98:99]
	v_lshl_add_u64 v[80:81], v[80:81], 0, s[98:99]
	s_waitcnt lgkmcnt(0)
	s_barrier
	s_add_u32 m0, s32, 0x4000
	v_mfma_f32_32x32x16_bf16 v[50:65], v[162:165], v[182:185], v[50:65]
	global_load_lds_dwordx4 v[66:67], off
	s_add_u32 m0, s32, 0x5000
	v_mfma_f32_32x32x16_bf16 v[18:33], v[162:165], v[186:189], v[18:33]
	global_load_lds_dwordx4 v[70:71], off
	s_add_u32 m0, s32, 0x6000
	v_mfma_f32_32x32x16_bf16 v[34:49], v[166:169], v[182:185], v[34:49]
	global_load_lds_dwordx4 v[74:75], off
	s_add_u32 m0, s32, 0x7000
	v_mfma_f32_32x32x16_bf16 v[2:17], v[166:169], v[186:189], v[2:17]
	global_load_lds_dwordx4 v[78:79], off
	s_add_u32 m0, s32, 0xc000
	v_mfma_f32_32x32x16_bf16 v[50:65], v[190:193], v[198:201], v[50:65]
	global_load_lds_dwordx4 v[68:69], off
	s_add_u32 m0, s32, 0xd000
	v_mfma_f32_32x32x16_bf16 v[18:33], v[190:193], v[202:205], v[18:33]
	global_load_lds_dwordx4 v[72:73], off
	s_add_u32 m0, s32, 0xe000
	v_mfma_f32_32x32x16_bf16 v[34:49], v[194:197], v[198:201], v[34:49]
	global_load_lds_dwordx4 v[76:77], off
	s_add_u32 m0, s32, 0xf000
	v_mfma_f32_32x32x16_bf16 v[2:17], v[194:197], v[202:205], v[2:17]
	global_load_lds_dwordx4 v[80:81], off
	s_waitcnt vmcnt(8)
	s_barrier
	ds_read_b128 v[162:165], v91
	ds_read_b128 v[166:169], v92 offset:32768
	ds_read_b128 v[182:185], v91 offset:4096
	ds_read_b128 v[186:189], v92 offset:36864
	ds_read_b128 v[190:193], v93
	ds_read_b128 v[194:197], v90 offset:32768
	ds_read_b128 v[198:201], v93 offset:4096
	ds_read_b128 v[202:205], v90 offset:36864
	s_waitcnt lgkmcnt(6)
	v_mfma_f32_32x32x16_bf16 v[50:65], v[162:165], v[166:169], v[50:65]
	s_waitcnt lgkmcnt(4)
	v_mfma_f32_32x32x16_bf16 v[18:33], v[162:165], v[186:189], v[18:33]
	v_mfma_f32_32x32x16_bf16 v[34:49], v[182:185], v[166:169], v[34:49]
	v_mfma_f32_32x32x16_bf16 v[2:17], v[182:185], v[186:189], v[2:17]
	ds_read_b128 v[162:165], v89
	ds_read_b128 v[166:169], v89 offset:4096
	ds_read_b128 v[182:185], v88 offset:32768
	ds_read_b128 v[186:189], v88 offset:36864
	s_waitcnt lgkmcnt(6)
	v_mfma_f32_32x32x16_bf16 v[50:65], v[190:193], v[194:197], v[50:65]
	s_waitcnt lgkmcnt(4)
	v_mfma_f32_32x32x16_bf16 v[18:33], v[190:193], v[202:205], v[18:33]
	v_mfma_f32_32x32x16_bf16 v[34:49], v[198:201], v[194:197], v[34:49]
	v_mfma_f32_32x32x16_bf16 v[2:17], v[198:201], v[202:205], v[2:17]
	ds_read_b128 v[190:193], v87
	ds_read_b128 v[194:197], v87 offset:4096
	ds_read_b128 v[198:201], v86 offset:32768
	ds_read_b128 v[202:205], v86 offset:36864
	v_lshl_add_u64 v[66:67], v[66:67], 0, s[98:99]
	v_lshl_add_u64 v[70:71], v[70:71], 0, s[98:99]
	v_lshl_add_u64 v[74:75], v[74:75], 0, s[98:99]
	v_lshl_add_u64 v[78:79], v[78:79], 0, s[98:99]
	v_lshl_add_u64 v[68:69], v[68:69], 0, s[98:99]
	v_lshl_add_u64 v[72:73], v[72:73], 0, s[98:99]
	v_lshl_add_u64 v[76:77], v[76:77], 0, s[98:99]
	v_lshl_add_u64 v[80:81], v[80:81], 0, s[98:99]
	s_waitcnt lgkmcnt(0)
	s_barrier
	s_add_u32 m0, s32, 0x0
	v_mfma_f32_32x32x16_bf16 v[50:65], v[162:165], v[182:185], v[50:65]
	global_load_lds_dwordx4 v[66:67], off
	s_add_u32 m0, s32, 0x1000
	v_mfma_f32_32x32x16_bf16 v[18:33], v[162:165], v[186:189], v[18:33]
	global_load_lds_dwordx4 v[70:71], off
	s_add_u32 m0, s32, 0x2000
	v_mfma_f32_32x32x16_bf16 v[34:49], v[166:169], v[182:185], v[34:49]
	global_load_lds_dwordx4 v[74:75], off
	s_add_u32 m0, s32, 0x3000
	v_mfma_f32_32x32x16_bf16 v[2:17], v[166:169], v[186:189], v[2:17]
	global_load_lds_dwordx4 v[78:79], off
	s_add_u32 m0, s32, 0x8000
	v_mfma_f32_32x32x16_bf16 v[50:65], v[190:193], v[198:201], v[50:65]
	global_load_lds_dwordx4 v[68:69], off
	s_add_u32 m0, s32, 0x9000
	v_mfma_f32_32x32x16_bf16 v[18:33], v[190:193], v[202:205], v[18:33]
	global_load_lds_dwordx4 v[72:73], off
	s_add_u32 m0, s32, 0xa000
	v_mfma_f32_32x32x16_bf16 v[34:49], v[194:197], v[198:201], v[34:49]
	global_load_lds_dwordx4 v[76:77], off
	s_add_u32 m0, s32, 0xb000
	v_mfma_f32_32x32x16_bf16 v[2:17], v[194:197], v[202:205], v[2:17]
	global_load_lds_dwordx4 v[80:81], off
	s_waitcnt vmcnt(8)
	s_barrier
	ds_read_b128 v[162:165], v91 offset:16384
	ds_read_b128 v[166:169], v92 offset:49152
	ds_read_b128 v[182:185], v91 offset:20480
	ds_read_b128 v[186:189], v92 offset:53248
	ds_read_b128 v[190:193], v93 offset:16384
	ds_read_b128 v[194:197], v90 offset:49152
	ds_read_b128 v[198:201], v93 offset:20480
	ds_read_b128 v[202:205], v90 offset:53248
	s_waitcnt lgkmcnt(6)
	v_mfma_f32_32x32x16_bf16 v[50:65], v[162:165], v[166:169], v[50:65]
	s_waitcnt lgkmcnt(4)
	v_mfma_f32_32x32x16_bf16 v[18:33], v[162:165], v[186:189], v[18:33]
	v_mfma_f32_32x32x16_bf16 v[34:49], v[182:185], v[166:169], v[34:49]
	v_mfma_f32_32x32x16_bf16 v[2:17], v[182:185], v[186:189], v[2:17]
	ds_read_b128 v[162:165], v89 offset:16384
	ds_read_b128 v[166:169], v89 offset:20480
	ds_read_b128 v[182:185], v88 offset:49152
	ds_read_b128 v[186:189], v88 offset:53248
	s_waitcnt lgkmcnt(6)
	v_mfma_f32_32x32x16_bf16 v[50:65], v[190:193], v[194:197], v[50:65]
	s_waitcnt lgkmcnt(4)
	v_mfma_f32_32x32x16_bf16 v[18:33], v[190:193], v[202:205], v[18:33]
	v_mfma_f32_32x32x16_bf16 v[34:49], v[198:201], v[194:197], v[34:49]
	v_mfma_f32_32x32x16_bf16 v[2:17], v[198:201], v[202:205], v[2:17]
	ds_read_b128 v[190:193], v87 offset:16384
	ds_read_b128 v[194:197], v87 offset:20480
	ds_read_b128 v[198:201], v86 offset:49152
	ds_read_b128 v[202:205], v86 offset:53248
	v_lshl_add_u64 v[66:67], v[66:67], 0, s[98:99]
	v_lshl_add_u64 v[70:71], v[70:71], 0, s[98:99]
	v_lshl_add_u64 v[74:75], v[74:75], 0, s[98:99]
	v_lshl_add_u64 v[78:79], v[78:79], 0, s[98:99]
	v_lshl_add_u64 v[68:69], v[68:69], 0, s[98:99]
	v_lshl_add_u64 v[72:73], v[72:73], 0, s[98:99]
	v_lshl_add_u64 v[76:77], v[76:77], 0, s[98:99]
	v_lshl_add_u64 v[80:81], v[80:81], 0, s[98:99]
	s_waitcnt lgkmcnt(0)
	s_barrier
	s_add_u32 m0, s32, 0x4000
	v_mfma_f32_32x32x16_bf16 v[50:65], v[162:165], v[182:185], v[50:65]
	global_load_lds_dwordx4 v[66:67], off
	s_add_u32 m0, s32, 0x5000
	v_mfma_f32_32x32x16_bf16 v[18:33], v[162:165], v[186:189], v[18:33]
	global_load_lds_dwordx4 v[70:71], off
	s_add_u32 m0, s32, 0x6000
	v_mfma_f32_32x32x16_bf16 v[34:49], v[166:169], v[182:185], v[34:49]
	global_load_lds_dwordx4 v[74:75], off
	s_add_u32 m0, s32, 0x7000
	v_mfma_f32_32x32x16_bf16 v[2:17], v[166:169], v[186:189], v[2:17]
	global_load_lds_dwordx4 v[78:79], off
	s_add_u32 m0, s32, 0xc000
	v_mfma_f32_32x32x16_bf16 v[50:65], v[190:193], v[198:201], v[50:65]
	global_load_lds_dwordx4 v[68:69], off
	s_add_u32 m0, s32, 0xd000
	v_mfma_f32_32x32x16_bf16 v[18:33], v[190:193], v[202:205], v[18:33]
	global_load_lds_dwordx4 v[72:73], off
	s_add_u32 m0, s32, 0xe000
	v_mfma_f32_32x32x16_bf16 v[34:49], v[194:197], v[198:201], v[34:49]
	global_load_lds_dwordx4 v[76:77], off
	s_add_u32 m0, s32, 0xf000
	v_mfma_f32_32x32x16_bf16 v[2:17], v[194:197], v[202:205], v[2:17]
	global_load_lds_dwordx4 v[80:81], off
	s_waitcnt vmcnt(8)
	s_barrier
	ds_read_b128 v[162:165], v91
	ds_read_b128 v[166:169], v92 offset:32768
	ds_read_b128 v[182:185], v91 offset:4096
	ds_read_b128 v[186:189], v92 offset:36864
	ds_read_b128 v[190:193], v93
	ds_read_b128 v[194:197], v90 offset:32768
	ds_read_b128 v[198:201], v93 offset:4096
	ds_read_b128 v[202:205], v90 offset:36864
	s_waitcnt lgkmcnt(6)
	v_mfma_f32_32x32x16_bf16 v[50:65], v[162:165], v[166:169], v[50:65]
	s_waitcnt lgkmcnt(4)
	v_mfma_f32_32x32x16_bf16 v[18:33], v[162:165], v[186:189], v[18:33]
	v_mfma_f32_32x32x16_bf16 v[34:49], v[182:185], v[166:169], v[34:49]
	v_mfma_f32_32x32x16_bf16 v[2:17], v[182:185], v[186:189], v[2:17]
	ds_read_b128 v[162:165], v89
	ds_read_b128 v[166:169], v89 offset:4096
	ds_read_b128 v[182:185], v88 offset:32768
	ds_read_b128 v[186:189], v88 offset:36864
	s_waitcnt lgkmcnt(6)
	v_mfma_f32_32x32x16_bf16 v[50:65], v[190:193], v[194:197], v[50:65]
	s_waitcnt lgkmcnt(4)
	v_mfma_f32_32x32x16_bf16 v[18:33], v[190:193], v[202:205], v[18:33]
	v_mfma_f32_32x32x16_bf16 v[34:49], v[198:201], v[194:197], v[34:49]
	v_mfma_f32_32x32x16_bf16 v[2:17], v[198:201], v[202:205], v[2:17]
	ds_read_b128 v[190:193], v87
	ds_read_b128 v[194:197], v87 offset:4096
	ds_read_b128 v[198:201], v86 offset:32768
	ds_read_b128 v[202:205], v86 offset:36864
	v_lshl_add_u64 v[66:67], v[66:67], 0, s[98:99]
	v_lshl_add_u64 v[70:71], v[70:71], 0, s[98:99]
	v_lshl_add_u64 v[74:75], v[74:75], 0, s[98:99]
	v_lshl_add_u64 v[78:79], v[78:79], 0, s[98:99]
	v_lshl_add_u64 v[68:69], v[68:69], 0, s[98:99]
	v_lshl_add_u64 v[72:73], v[72:73], 0, s[98:99]
	v_lshl_add_u64 v[76:77], v[76:77], 0, s[98:99]
	v_lshl_add_u64 v[80:81], v[80:81], 0, s[98:99]
	s_waitcnt lgkmcnt(0)
	s_barrier
	s_add_u32 m0, s32, 0x0
	s_nop 0
	global_load_lds_dwordx4 v[66:67], off
	s_add_u32 m0, s32, 0x1000
	s_nop 0
	global_load_lds_dwordx4 v[70:71], off
	s_add_u32 m0, s32, 0x2000
	s_nop 0
	global_load_lds_dwordx4 v[74:75], off
	s_add_u32 m0, s32, 0x3000
	s_nop 0
	global_load_lds_dwordx4 v[78:79], off
	s_add_u32 m0, s32, 0x8000
	s_nop 0
	global_load_lds_dwordx4 v[68:69], off
	s_add_u32 m0, s32, 0x9000
	s_nop 0
	global_load_lds_dwordx4 v[72:73], off
	s_add_u32 m0, s32, 0xa000
	s_nop 0
	global_load_lds_dwordx4 v[76:77], off
	s_add_u32 m0, s32, 0xb000
	s_nop 0
	global_load_lds_dwordx4 v[80:81], off
	s_waitcnt vmcnt(8)
	s_barrier
	s_nop 0
	s_nop 0
	s_nop 0
	s_nop 0
	s_nop 0
	s_nop 0
	s_nop 0
	v_mfma_f32_32x32x16_bf16 v[50:65], v[162:165], v[182:185], v[50:65]
	v_mfma_f32_32x32x16_bf16 v[18:33], v[162:165], v[186:189], v[18:33]
	v_mfma_f32_32x32x16_bf16 v[34:49], v[166:169], v[182:185], v[34:49]
	v_mfma_f32_32x32x16_bf16 v[2:17], v[166:169], v[186:189], v[2:17]
	ds_read_b128 v[110:113], v91 offset:16384
	ds_read_b128 v[114:117], v91 offset:20480
	ds_read_b128 v[118:121], v92 offset:49152
	ds_read_b128 v[122:125], v92 offset:53248
	ds_read_b128 v[162:165], v93 offset:16384
	ds_read_b128 v[166:169], v93 offset:20480
	ds_read_b128 v[182:185], v90 offset:49152
	ds_read_b128 v[186:189], v90 offset:53248
	v_mfma_f32_32x32x16_bf16 v[50:65], v[190:193], v[198:201], v[50:65]
	v_mfma_f32_32x32x16_bf16 v[18:33], v[190:193], v[202:205], v[18:33]
	v_mfma_f32_32x32x16_bf16 v[34:49], v[194:197], v[198:201], v[34:49]
	v_mfma_f32_32x32x16_bf16 v[2:17], v[194:197], v[202:205], v[2:17]
	s_waitcnt lgkmcnt(5)
	v_mfma_f32_32x32x16_bf16 v[50:65], v[110:113], v[118:121], v[50:65]
	s_waitcnt lgkmcnt(4)
	v_mfma_f32_32x32x16_bf16 v[18:33], v[110:113], v[122:125], v[18:33]
	v_mfma_f32_32x32x16_bf16 v[34:49], v[114:117], v[118:121], v[34:49]
	v_mfma_f32_32x32x16_bf16 v[2:17], v[114:117], v[122:125], v[2:17]
	ds_read_b128 v[110:113], v89 offset:16384
	ds_read_b128 v[114:117], v89 offset:20480
	ds_read_b128 v[118:121], v88 offset:49152
	ds_read_b128 v[122:125], v88 offset:53248
	s_waitcnt lgkmcnt(5)
	v_mfma_f32_32x32x16_bf16 v[50:65], v[162:165], v[182:185], v[50:65]
	s_waitcnt lgkmcnt(4)
	v_mfma_f32_32x32x16_bf16 v[18:33], v[162:165], v[186:189], v[18:33]
	v_mfma_f32_32x32x16_bf16 v[34:49], v[166:169], v[182:185], v[34:49]
	v_mfma_f32_32x32x16_bf16 v[2:17], v[166:169], v[186:189], v[2:17]
	ds_read_b128 v[162:165], v87 offset:16384
	ds_read_b128 v[166:169], v87 offset:20480
	ds_read_b128 v[182:185], v86 offset:49152
	ds_read_b128 v[186:189], v86 offset:53248
	s_waitcnt lgkmcnt(5)
	v_mfma_f32_32x32x16_bf16 v[50:65], v[110:113], v[118:121], v[50:65]
	v_lshl_add_u64 v[66:67], v[66:67], 0, s[98:99]
	v_lshl_add_u64 v[70:71], v[70:71], 0, s[98:99]
	v_lshl_add_u64 v[74:75], v[74:75], 0, s[98:99]
	v_lshl_add_u64 v[78:79], v[78:79], 0, s[98:99]
	v_lshl_add_u64 v[68:69], v[68:69], 0, s[98:99]
	v_lshl_add_u64 v[72:73], v[72:73], 0, s[98:99]
	v_lshl_add_u64 v[76:77], v[76:77], 0, s[98:99]
	v_lshl_add_u64 v[80:81], v[80:81], 0, s[98:99]
	s_waitcnt lgkmcnt(0)
	s_barrier
	s_add_u32 m0, s32, 0x4000
	s_nop 0
	global_load_lds_dwordx4 v[66:67], off
	s_add_u32 m0, s32, 0x5000
	s_nop 0
	global_load_lds_dwordx4 v[70:71], off
	s_add_u32 m0, s32, 0x6000
	s_nop 0
	global_load_lds_dwordx4 v[74:75], off
	s_add_u32 m0, s32, 0x7000
	s_nop 0
	global_load_lds_dwordx4 v[78:79], off
	s_add_u32 m0, s32, 0xc000
	s_nop 0
	global_load_lds_dwordx4 v[68:69], off
	s_add_u32 m0, s32, 0xd000
	s_nop 0
	global_load_lds_dwordx4 v[72:73], off
	s_add_u32 m0, s32, 0xe000
	s_nop 0
	global_load_lds_dwordx4 v[76:77], off
	s_add_u32 m0, s32, 0xf000
	s_nop 0
	global_load_lds_dwordx4 v[80:81], off
	s_waitcnt vmcnt(8)
	s_barrier
	v_mfma_f32_32x32x16_bf16 v[18:33], v[110:113], v[122:125], v[18:33]
	v_mfma_f32_32x32x16_bf16 v[34:49], v[114:117], v[118:121], v[34:49]
	v_mfma_f32_32x32x16_bf16 v[2:17], v[114:117], v[122:125], v[2:17]
	ds_read_b128 v[110:113], v91
	ds_read_b128 v[114:117], v91 offset:4096
	ds_read_b128 v[118:121], v92 offset:32768
	ds_read_b128 v[122:125], v92 offset:36864
	ds_read_b128 v[126:129], v93
	ds_read_b128 v[134:137], v93 offset:4096
	ds_read_b128 v[138:141], v90 offset:32768
	ds_read_b128 v[142:145], v90 offset:36864
	v_mfma_f32_32x32x16_bf16 v[50:65], v[162:165], v[182:185], v[50:65]
	v_mfma_f32_32x32x16_bf16 v[18:33], v[162:165], v[186:189], v[18:33]
	v_mfma_f32_32x32x16_bf16 v[34:49], v[166:169], v[182:185], v[34:49]
	v_mfma_f32_32x32x16_bf16 v[2:17], v[166:169], v[186:189], v[2:17]
	s_waitcnt lgkmcnt(5)
	v_mfma_f32_32x32x16_bf16 v[50:65], v[110:113], v[118:121], v[50:65]
	s_waitcnt lgkmcnt(4)
	v_mfma_f32_32x32x16_bf16 v[18:33], v[110:113], v[122:125], v[18:33]
	v_mfma_f32_32x32x16_bf16 v[34:49], v[114:117], v[118:121], v[34:49]
	v_mfma_f32_32x32x16_bf16 v[2:17], v[114:117], v[122:125], v[2:17]
	ds_read_b128 v[110:113], v89
	ds_read_b128 v[114:117], v89 offset:4096
	ds_read_b128 v[118:121], v88 offset:32768
	ds_read_b128 v[122:125], v88 offset:36864
	s_waitcnt lgkmcnt(5)
	v_mfma_f32_32x32x16_bf16 v[50:65], v[126:129], v[138:141], v[50:65]
	s_waitcnt lgkmcnt(4)
	v_mfma_f32_32x32x16_bf16 v[18:33], v[126:129], v[142:145], v[18:33]
	v_mfma_f32_32x32x16_bf16 v[34:49], v[134:137], v[138:141], v[34:49]
	v_mfma_f32_32x32x16_bf16 v[2:17], v[134:137], v[142:145], v[2:17]
	ds_read_b128 v[126:129], v87
	ds_read_b128 v[134:137], v87 offset:4096
	ds_read_b128 v[138:141], v86 offset:32768
	ds_read_b128 v[142:145], v86 offset:36864
	s_waitcnt vmcnt(0)
	s_waitcnt lgkmcnt(0)
	s_barrier
	ds_read_b128 v[66:69], v91 offset:16384
	ds_read_b128 v[70:73], v91 offset:20480
	ds_read_b128 v[74:77], v92 offset:49152
	ds_read_b128 v[78:81], v92 offset:53248
	ds_read_b128 v[94:97], v93 offset:16384
	ds_read_b128 v[98:101], v93 offset:20480
	ds_read_b128 v[102:105], v90 offset:49152
	ds_read_b128 v[90:93], v90 offset:53248
	v_mfma_f32_32x32x16_bf16 v[50:65], v[110:113], v[118:121], v[50:65]
	v_mfma_f32_32x32x16_bf16 v[18:33], v[110:113], v[122:125], v[18:33]
	v_mfma_f32_32x32x16_bf16 v[34:49], v[114:117], v[118:121], v[34:49]
	v_mfma_f32_32x32x16_bf16 v[2:17], v[114:117], v[122:125], v[2:17]
	v_mfma_f32_32x32x16_bf16 v[50:65], v[126:129], v[138:141], v[50:65]
	v_mfma_f32_32x32x16_bf16 v[18:33], v[126:129], v[142:145], v[18:33]
	v_mfma_f32_32x32x16_bf16 v[34:49], v[134:137], v[138:141], v[34:49]
	v_mfma_f32_32x32x16_bf16 v[2:17], v[134:137], v[142:145], v[2:17]
	s_waitcnt lgkmcnt(5)
	v_mfma_f32_32x32x16_bf16 v[50:65], v[66:69], v[74:77], v[50:65]
	s_waitcnt lgkmcnt(4)
	v_mfma_f32_32x32x16_bf16 v[18:33], v[66:69], v[78:81], v[18:33]
	v_mfma_f32_32x32x16_bf16 v[34:49], v[70:73], v[74:77], v[34:49]
	v_mfma_f32_32x32x16_bf16 v[2:17], v[70:73], v[78:81], v[2:17]
	ds_read_b128 v[66:69], v89 offset:16384
	ds_read_b128 v[70:73], v89 offset:20480
	ds_read_b128 v[74:77], v88 offset:49152
	ds_read_b128 v[78:81], v88 offset:53248
	s_waitcnt lgkmcnt(5)
	v_mfma_f32_32x32x16_bf16 v[50:65], v[94:97], v[102:105], v[50:65]
	s_waitcnt lgkmcnt(4)
	v_mfma_f32_32x32x16_bf16 v[18:33], v[94:97], v[90:93], v[18:33]
	v_mfma_f32_32x32x16_bf16 v[34:49], v[98:101], v[102:105], v[34:49]
	v_mfma_f32_32x32x16_bf16 v[2:17], v[98:101], v[90:93], v[2:17]
	ds_read_b128 v[88:91], v87 offset:16384
	ds_read_b128 v[92:95], v87 offset:20480
	ds_read_b128 v[96:99], v86 offset:49152
	ds_read_b128 v[100:103], v86 offset:53248
	s_lshl_b32 s6, s34, 7
	v_lshl_add_u32 v0, v84, 6, s6
	s_min_i32 s7, s6, 0x4000
	v_lshl_or_b32 v0, v85, 2, v0
	s_movk_i32 s6, 0x4000
	s_waitcnt lgkmcnt(5)
	v_mfma_f32_32x32x16_bf16 v[50:65], v[66:69], v[74:77], v[50:65]
	v_cmp_gt_i32_e32 vcc, s6, v0
	v_readlane_b32 s36, v210, 2
	v_readlane_b32 s40, v210, 6
	s_ashr_i32 s7, s7, 12
	s_add_i32 s7, s7, s70
	s_mul_hi_i32 s8, s7, 0x6000
	s_mulk_i32 s7, 0x6000
	s_waitcnt lgkmcnt(4)
	v_mfma_f32_32x32x16_bf16 v[18:33], v[66:69], v[78:81], v[18:33]
	v_add_u32_e32 v66, 0xffffc000, v0
	v_ashrrev_i32_e32 v67, 31, v0
	v_cndmask_b32_e32 v66, v66, v0, vcc
	v_mov_b32_e32 v0, s95
	v_mov_b32_e32 v68, s89
	v_cndmask_b32_e32 v69, v0, v68, vcc
	v_mov_b32_e32 v0, s94
	v_mov_b32_e32 v68, s88
	v_mfma_f32_32x32x16_bf16 v[34:49], v[70:73], v[74:77], v[34:49]
	v_cndmask_b32_e32 v67, 0, v67, vcc
	v_cndmask_b32_e32 v68, v0, v68, vcc
	v_mov_b32_e32 v0, s40
	v_lshlrev_b64 v[66:67], 12, v[66:67]
	v_lshl_add_u64 v[134:135], v[68:69], 0, v[66:67]
	v_readlane_b32 s37, v210, 3
	v_readlane_b32 s41, v210, 7
	v_mfma_f32_32x32x16_bf16 v[2:17], v[70:73], v[78:81], v[2:17]
	v_mov_b32_e32 v70, s36
	v_cndmask_b32_e32 v0, v0, v70, vcc
	v_cndmask_b32_e64 v68, v68, v0, s[52:53]
	v_lshl_or_b32 v0, v83, 6, v82
	s_add_u32 s7, s90, s7
	v_mov_b32_e32 v70, s41
	v_mov_b32_e32 v71, s37
	v_subrev_u32_e32 v0, s5, v0
	s_addc_u32 s8, s91, s8
	v_cndmask_b32_e32 v70, v70, v71, vcc
	v_add_u32_e32 v168, s3, v0
	s_add_u32 s34, s7, 0x2000
	v_cndmask_b32_e64 v69, v69, v70, s[52:53]
	v_ashrrev_i32_e32 v169, 31, v168
	s_addc_u32 s35, s8, 0
	v_lshl_add_u64 v[66:67], v[68:69], 0, v[66:67]
	v_lshlrev_b64 v[136:137], 2, v[168:169]
	v_lshl_add_u64 v[68:69], s[34:35], 0, v[136:137]
	v_lshl_add_u64 v[66:67], v[66:67], 0, v[136:137]
	s_movk_i32 s8, 0x1000
	s_waitcnt lgkmcnt(0)
	s_barrier
	global_load_dword v0, v[68:69], off
	v_add_co_u32_e32 v68, vcc, s8, v66
	s_movk_i32 s6, 0x2000
	s_nop 0
	v_addc_co_u32_e32 v69, vcc, 0, v67, vcc
	global_load_dword v138, v[66:67], off
	v_add_co_u32_e32 v70, vcc, s6, v66
	v_readlane_b32 s38, v210, 4
	s_nop 0
	v_addc_co_u32_e32 v71, vcc, 0, v67, vcc
	global_load_dword v139, v[70:71], off offset:-4096
	global_load_dword v140, v[70:71], off
	s_movk_i32 s38, 0x3000
	v_add_co_u32_e32 v72, vcc, s38, v66
	s_mov_b32 s7, 0x8000
	s_nop 0
	v_addc_co_u32_e32 v73, vcc, 0, v67, vcc
	global_load_dword v141, v[72:73], off
	v_add_co_u32_e32 v74, vcc, s7, v66
	s_mov_b32 s36, 0x9000
	s_nop 0
	v_addc_co_u32_e32 v75, vcc, 0, v67, vcc
	v_add_co_u32_e32 v76, vcc, s36, v66
	s_mov_b32 s37, 0xa000
	s_nop 0
	v_addc_co_u32_e32 v77, vcc, 0, v67, vcc
	v_add_co_u32_e32 v78, vcc, s37, v66
	s_mov_b32 s5, 0xb000
	s_nop 0
	v_addc_co_u32_e32 v79, vcc, 0, v67, vcc
	global_load_dword v142, v[76:77], off offset:-4096
	global_load_dword v143, v[76:77], off
	v_add_co_u32_e32 v80, vcc, s5, v66
	v_readlane_b32 s39, v210, 5
	s_nop 0
	v_addc_co_u32_e32 v81, vcc, 0, v67, vcc
	v_add_co_u32_e32 v82, vcc, s10, v66
	s_mov_b32 s39, 0x11000
	s_nop 0
	v_addc_co_u32_e32 v83, vcc, 0, v67, vcc
	global_load_dword v144, v[80:81], off offset:-4096
	global_load_dword v145, v[80:81], off
	v_add_co_u32_e32 v84, vcc, s39, v66
	v_mfma_f32_32x32x16_bf16 v[50:65], v[88:91], v[96:99], v[50:65]
	s_nop 0
	v_addc_co_u32_e32 v85, vcc, 0, v67, vcc
	v_add_co_u32_e32 v86, vcc, s62, v66
	global_load_dword v146, v[84:85], off offset:-4096
	global_load_dword v147, v[84:85], off
	v_addc_co_u32_e32 v87, vcc, 0, v67, vcc
	v_mfma_f32_32x32x16_bf16 v[18:33], v[88:91], v[100:103], v[18:33]
	v_add_co_u32_e32 v88, vcc, s57, v66
	v_lshl_add_u64 v[134:135], v[134:135], 0, v[136:137]
	s_nop 0
	v_addc_co_u32_e32 v89, vcc, 0, v67, vcc
	v_add_co_u32_e32 v90, vcc, s54, v66
	v_mfma_f32_32x32x16_bf16 v[34:49], v[92:95], v[96:99], v[34:49]
	s_nop 0
	v_addc_co_u32_e32 v91, vcc, 0, v67, vcc
	global_load_dword v148, v[88:89], off offset:-4096
	global_load_dword v149, v[88:89], off
	s_add_i32 s4, s4, s66
	s_add_i32 s3, s3, s2
	s_cmp_lt_i32 s4, s59
	v_readlane_b32 s42, v210, 8
	v_mfma_f32_32x32x16_bf16 v[2:17], v[92:95], v[100:103], v[2:17]
	v_add_co_u32_e32 v92, vcc, s55, v66
	v_readlane_b32 s43, v210, 9
	s_nop 0
	v_addc_co_u32_e32 v93, vcc, 0, v67, vcc
	v_add_co_u32_e32 v94, vcc, s72, v66
	global_load_dword v150, v[92:93], off offset:-4096
	global_load_dword v151, v[92:93], off
	v_addc_co_u32_e32 v95, vcc, 0, v67, vcc
	v_add_co_u32_e32 v96, vcc, s73, v66
	s_waitcnt vmcnt(13)
	v_fmac_f32_e32 v138, v50, v0
	v_addc_co_u32_e32 v97, vcc, 0, v67, vcc
	v_add_co_u32_e32 v98, vcc, s63, v66
	global_load_dword v152, v[96:97], off offset:-4096
	global_load_dword v153, v[96:97], off
	v_addc_co_u32_e32 v99, vcc, 0, v67, vcc
	v_add_co_u32_e32 v100, vcc, s74, v66
	s_waitcnt vmcnt(14)
	v_fmac_f32_e32 v139, v51, v0
	v_addc_co_u32_e32 v101, vcc, 0, v67, vcc
	v_add_co_u32_e32 v102, vcc, s75, v66
	global_load_dword v154, v[100:101], off offset:-4096
	global_load_dword v155, v[100:101], off
	v_addc_co_u32_e32 v103, vcc, 0, v67, vcc
	v_add_co_u32_e32 v104, vcc, s76, v66
	s_waitcnt vmcnt(15)
	v_fmac_f32_e32 v140, v52, v0
	v_addc_co_u32_e32 v105, vcc, 0, v67, vcc
	v_add_co_u32_e32 v106, vcc, s77, v66
	global_load_dword v156, v[104:105], off offset:-4096
	global_load_dword v157, v[104:105], off
	v_addc_co_u32_e32 v107, vcc, 0, v67, vcc
	v_add_co_u32_e32 v108, vcc, s78, v66
	s_waitcnt vmcnt(16)
	v_fmac_f32_e32 v141, v53, v0
	v_addc_co_u32_e32 v109, vcc, 0, v67, vcc
	v_add_co_u32_e32 v110, vcc, s79, v66
	global_load_dword v158, v[108:109], off offset:-4096
	global_load_dword v159, v[108:109], off
	v_addc_co_u32_e32 v111, vcc, 0, v67, vcc
	v_add_co_u32_e32 v112, vcc, s58, v66
	s_waitcnt vmcnt(17)
	v_fmac_f32_e32 v142, v54, v0
	v_addc_co_u32_e32 v113, vcc, 0, v67, vcc
	v_add_co_u32_e32 v114, vcc, s61, v66
	global_load_dword v160, v[112:113], off offset:-4096
	global_load_dword v161, v[112:113], off
	v_addc_co_u32_e32 v115, vcc, 0, v67, vcc
	v_add_co_u32_e32 v116, vcc, s56, v66
	s_waitcnt vmcnt(18)
	v_fmac_f32_e32 v143, v55, v0
	v_addc_co_u32_e32 v117, vcc, 0, v67, vcc
	v_add_co_u32_e32 v118, vcc, s97, v66
	global_load_dword v162, v[116:117], off offset:-4096
	global_load_dword v163, v[116:117], off
	v_addc_co_u32_e32 v119, vcc, 0, v67, vcc
	v_add_co_u32_e32 v120, vcc, s9, v66
	s_waitcnt vmcnt(19)
	v_fmac_f32_e32 v144, v56, v0
	v_addc_co_u32_e32 v121, vcc, 0, v67, vcc
	v_add_co_u32_e32 v122, vcc, s69, v66
	global_load_dword v164, v[120:121], off offset:-4096
	global_load_dword v165, v[120:121], off
	v_addc_co_u32_e32 v123, vcc, 0, v67, vcc
	v_add_co_u32_e32 v124, vcc, s67, v66
	s_waitcnt vmcnt(20)
	v_fmac_f32_e32 v145, v57, v0
	v_addc_co_u32_e32 v125, vcc, 0, v67, vcc
	v_add_co_u32_e32 v126, vcc, s60, v66
	global_load_dword v166, v[124:125], off offset:-4096
	global_load_dword v167, v[124:125], off
	v_addc_co_u32_e32 v127, vcc, 0, v67, vcc
	v_add_co_u32_e32 v128, vcc, s33, v66
	s_waitcnt vmcnt(21)
	v_fmac_f32_e32 v146, v58, v0
	v_addc_co_u32_e32 v129, vcc, 0, v67, vcc
	global_load_dword v169, v[128:129], off offset:-4096
	global_load_dword v181, v[128:129], off
	v_add_co_u32_e32 v50, vcc, s8, v134
	global_store_dword v[134:135], v138, off
	s_nop 0
	v_addc_co_u32_e32 v51, vcc, 0, v135, vcc
	v_add_co_u32_e32 v136, vcc, s6, v134
	s_waitcnt vmcnt(23)
	v_fmac_f32_e32 v147, v59, v0
	v_addc_co_u32_e32 v137, vcc, 0, v135, vcc
	v_add_co_u32_e32 v52, vcc, s38, v134
	global_store_dword v[136:137], v139, off offset:-4096
	s_nop 0
	v_addc_co_u32_e32 v53, vcc, 0, v135, vcc
	v_add_co_u32_e32 v138, vcc, s7, v134
	global_store_dword v[136:137], v140, off
	s_nop 0
	v_addc_co_u32_e32 v139, vcc, 0, v135, vcc
	v_add_co_u32_e32 v140, vcc, s36, v134
	global_store_dword v[52:53], v141, off
	s_nop 0
	v_addc_co_u32_e32 v141, vcc, 0, v135, vcc
	v_add_co_u32_e32 v54, vcc, s37, v134
	global_store_dword v[140:141], v142, off offset:-4096
	s_nop 0
	v_addc_co_u32_e32 v55, vcc, 0, v135, vcc
	v_add_co_u32_e32 v142, vcc, s5, v134
	global_store_dword v[140:141], v143, off
	s_nop 0
	v_addc_co_u32_e32 v143, vcc, 0, v135, vcc
	v_add_co_u32_e32 v56, vcc, s10, v134
	global_store_dword v[142:143], v144, off offset:-4096
	s_nop 0
	v_addc_co_u32_e32 v57, vcc, 0, v135, vcc
	v_add_co_u32_e32 v144, vcc, s39, v134
	global_store_dword v[142:143], v145, off
	s_nop 0
	v_addc_co_u32_e32 v145, vcc, 0, v135, vcc
	v_add_co_u32_e32 v58, vcc, s62, v134
	global_store_dword v[144:145], v146, off offset:-4096
	s_nop 0
	v_addc_co_u32_e32 v59, vcc, 0, v135, vcc
	v_add_co_u32_e32 v146, vcc, s57, v134
	global_store_dword v[144:145], v147, off
	s_nop 0
	v_addc_co_u32_e32 v147, vcc, 0, v135, vcc
	s_waitcnt vmcnt(31)
	v_fmac_f32_e32 v148, v60, v0
	v_add_co_u32_e32 v60, vcc, s54, v134
	s_waitcnt vmcnt(30)
	v_fmac_f32_e32 v149, v61, v0
	v_addc_co_u32_e32 v61, vcc, 0, v135, vcc
	global_store_dword v[146:147], v148, off offset:-4096
	v_add_co_u32_e32 v148, vcc, s55, v134
	global_store_dword v[146:147], v149, off
	s_nop 0
	v_addc_co_u32_e32 v149, vcc, 0, v135, vcc
	s_waitcnt vmcnt(31)
	v_fmac_f32_e32 v150, v62, v0
	v_add_co_u32_e32 v62, vcc, s72, v134
	s_waitcnt vmcnt(30)
	v_fmac_f32_e32 v151, v63, v0
	v_addc_co_u32_e32 v63, vcc, 0, v135, vcc
	global_store_dword v[148:149], v150, off offset:-4096
	v_add_co_u32_e32 v150, vcc, s73, v134
	global_store_dword v[148:149], v151, off
	s_nop 0
	v_addc_co_u32_e32 v151, vcc, 0, v135, vcc
	s_waitcnt vmcnt(31)
	v_fmac_f32_e32 v152, v64, v0
	v_add_co_u32_e32 v64, vcc, s63, v134
	s_waitcnt vmcnt(30)
	v_fmac_f32_e32 v153, v65, v0
	v_addc_co_u32_e32 v65, vcc, 0, v135, vcc
	global_store_dword v[150:151], v152, off offset:-4096
	v_add_co_u32_e32 v152, vcc, s74, v134
	global_store_dword v[150:151], v153, off
	s_nop 0
	v_addc_co_u32_e32 v153, vcc, 0, v135, vcc
	s_waitcnt vmcnt(31)
	v_fmac_f32_e32 v154, v34, v0
	v_add_co_u32_e32 v34, vcc, s75, v134
	s_waitcnt vmcnt(30)
	v_fmac_f32_e32 v155, v35, v0
	v_addc_co_u32_e32 v35, vcc, 0, v135, vcc
	global_store_dword v[152:153], v154, off offset:-4096
	v_add_co_u32_e32 v154, vcc, s76, v134
	global_store_dword v[152:153], v155, off
	s_nop 0
	v_addc_co_u32_e32 v155, vcc, 0, v135, vcc
	s_waitcnt vmcnt(31)
	v_fmac_f32_e32 v156, v36, v0
	v_add_co_u32_e32 v36, vcc, s77, v134
	s_waitcnt vmcnt(30)
	v_fmac_f32_e32 v157, v37, v0
	v_addc_co_u32_e32 v37, vcc, 0, v135, vcc
	global_store_dword v[154:155], v156, off offset:-4096
	v_add_co_u32_e32 v156, vcc, s78, v134
	global_store_dword v[154:155], v157, off
	s_nop 0
	v_addc_co_u32_e32 v157, vcc, 0, v135, vcc
	s_waitcnt vmcnt(31)
	v_fmac_f32_e32 v158, v38, v0
	v_add_co_u32_e32 v38, vcc, s79, v134
	s_waitcnt vmcnt(30)
	v_fmac_f32_e32 v159, v39, v0
	v_addc_co_u32_e32 v39, vcc, 0, v135, vcc
	global_store_dword v[156:157], v158, off offset:-4096
	v_add_co_u32_e32 v158, vcc, s58, v134
	global_store_dword v[156:157], v159, off
	s_nop 0
	v_addc_co_u32_e32 v159, vcc, 0, v135, vcc
	s_waitcnt vmcnt(31)
	v_fmac_f32_e32 v160, v40, v0
	v_add_co_u32_e32 v40, vcc, s61, v134
	s_waitcnt vmcnt(30)
	v_fmac_f32_e32 v161, v41, v0
	v_addc_co_u32_e32 v41, vcc, 0, v135, vcc
	global_store_dword v[158:159], v160, off offset:-4096
	v_add_co_u32_e32 v160, vcc, s56, v134
	global_store_dword v[158:159], v161, off
	s_nop 0
	v_addc_co_u32_e32 v161, vcc, 0, v135, vcc
	s_waitcnt vmcnt(31)
	v_fmac_f32_e32 v162, v42, v0
	v_add_co_u32_e32 v42, vcc, s97, v134
	s_waitcnt vmcnt(30)
	v_fmac_f32_e32 v163, v43, v0
	v_addc_co_u32_e32 v43, vcc, 0, v135, vcc
	global_store_dword v[160:161], v162, off offset:-4096
	v_add_co_u32_e32 v162, vcc, s9, v134
	global_store_dword v[160:161], v163, off
	s_nop 0
	v_addc_co_u32_e32 v163, vcc, 0, v135, vcc
	s_waitcnt vmcnt(31)
	v_fmac_f32_e32 v164, v44, v0
	v_add_co_u32_e32 v44, vcc, s69, v134
	s_waitcnt vmcnt(30)
	v_fmac_f32_e32 v165, v45, v0
	v_addc_co_u32_e32 v45, vcc, 0, v135, vcc
	global_store_dword v[162:163], v164, off offset:-4096
	v_add_co_u32_e32 v164, vcc, s67, v134
	global_store_dword v[162:163], v165, off
	s_nop 0
	v_addc_co_u32_e32 v165, vcc, 0, v135, vcc
	s_waitcnt vmcnt(31)
	v_fmac_f32_e32 v166, v46, v0
	v_add_co_u32_e32 v46, vcc, s60, v134
	s_waitcnt vmcnt(30)
	v_fmac_f32_e32 v167, v47, v0
	v_addc_co_u32_e32 v47, vcc, 0, v135, vcc
	global_store_dword v[164:165], v166, off offset:-4096
	s_waitcnt vmcnt(30)
	v_fmac_f32_e32 v169, v48, v0
	v_add_co_u32_e32 v166, vcc, s33, v134
	v_add_u32_e32 v48, 32, v168
	global_store_dword v[164:165], v167, off
	v_addc_co_u32_e32 v167, vcc, 0, v135, vcc
	s_waitcnt vmcnt(30)
	v_fmac_f32_e32 v181, v49, v0
	v_ashrrev_i32_e32 v49, 31, v48
	global_store_dword v[166:167], v169, off offset:-4096
	global_store_dword v[166:167], v181, off
	v_lshl_add_u64 v[48:49], v[48:49], 2, s[34:35]
	global_load_dword v0, v[48:49], off
	s_nop 0
	global_load_dword v48, v[66:67], off offset:128
	global_load_dword v49, v[68:69], off offset:128
	s_nop 0
	global_load_dword v66, v[70:71], off offset:128
	global_load_dword v67, v[72:73], off offset:128
	global_load_dword v68, v[74:75], off offset:128
	global_load_dword v69, v[76:77], off offset:128
	s_nop 0
	global_load_dword v70, v[78:79], off offset:128
	global_load_dword v71, v[80:81], off offset:128
	global_load_dword v72, v[82:83], off offset:128
	global_load_dword v73, v[84:85], off offset:128
	global_load_dword v74, v[86:87], off offset:128
	global_load_dword v75, v[88:89], off offset:128
	global_load_dword v76, v[90:91], off offset:128
	global_load_dword v77, v[92:93], off offset:128
	global_load_dword v78, v[94:95], off offset:128
	global_load_dword v79, v[96:97], off offset:128
	global_load_dword v80, v[98:99], off offset:128
	global_load_dword v81, v[100:101], off offset:128
	global_load_dword v82, v[102:103], off offset:128
	global_load_dword v83, v[104:105], off offset:128
	global_load_dword v84, v[106:107], off offset:128
	global_load_dword v85, v[108:109], off offset:128
	global_load_dword v86, v[110:111], off offset:128
	global_load_dword v87, v[112:113], off offset:128
	global_load_dword v88, v[114:115], off offset:128
	global_load_dword v89, v[116:117], off offset:128
	global_load_dword v90, v[118:119], off offset:128
	global_load_dword v91, v[120:121], off offset:128
	global_load_dword v92, v[122:123], off offset:128
	global_load_dword v93, v[124:125], off offset:128
	global_load_dword v94, v[126:127], off offset:128
	global_load_dword v95, v[128:129], off offset:128
	v_readlane_b32 s44, v210, 10
	v_readlane_b32 s45, v210, 11
	v_readlane_b32 s46, v210, 12
	v_readlane_b32 s47, v210, 13
	v_readlane_b32 s48, v210, 14
	v_readlane_b32 s49, v210, 15
	v_readlane_b32 s50, v210, 16
	v_readlane_b32 s51, v210, 17
	s_waitcnt vmcnt(31)
	v_fmac_f32_e32 v48, v18, v0
	s_waitcnt vmcnt(30)
	v_fmac_f32_e32 v49, v19, v0
	s_waitcnt vmcnt(29)
	v_fmac_f32_e32 v66, v20, v0
	s_waitcnt vmcnt(28)
	v_fmac_f32_e32 v67, v21, v0
	s_waitcnt vmcnt(27)
	v_fmac_f32_e32 v68, v22, v0
	s_waitcnt vmcnt(26)
	v_fmac_f32_e32 v69, v23, v0
	s_waitcnt vmcnt(25)
	v_fmac_f32_e32 v70, v24, v0
	s_waitcnt vmcnt(24)
	v_fmac_f32_e32 v71, v25, v0
	s_waitcnt vmcnt(23)
	v_fmac_f32_e32 v72, v26, v0
	s_waitcnt vmcnt(22)
	v_fmac_f32_e32 v73, v27, v0
	s_waitcnt vmcnt(21)
	v_fmac_f32_e32 v74, v28, v0
	s_waitcnt vmcnt(20)
	v_fmac_f32_e32 v75, v29, v0
	s_waitcnt vmcnt(19)
	v_fmac_f32_e32 v76, v30, v0
	s_waitcnt vmcnt(18)
	v_fmac_f32_e32 v77, v31, v0
	s_waitcnt vmcnt(17)
	v_fmac_f32_e32 v78, v32, v0
	s_waitcnt vmcnt(16)
	v_fmac_f32_e32 v79, v33, v0
	s_waitcnt vmcnt(15)
	v_fmac_f32_e32 v80, v2, v0
	s_waitcnt vmcnt(14)
	v_fmac_f32_e32 v81, v3, v0
	s_waitcnt vmcnt(13)
	v_fmac_f32_e32 v82, v4, v0
	s_waitcnt vmcnt(12)
	v_fmac_f32_e32 v83, v5, v0
	s_waitcnt vmcnt(11)
	v_fmac_f32_e32 v84, v6, v0
	s_waitcnt vmcnt(10)
	v_fmac_f32_e32 v85, v7, v0
	s_waitcnt vmcnt(9)
	v_fmac_f32_e32 v86, v8, v0
	s_waitcnt vmcnt(8)
	v_fmac_f32_e32 v87, v9, v0
	s_waitcnt vmcnt(7)
	v_fmac_f32_e32 v88, v10, v0
	s_waitcnt vmcnt(6)
	v_fmac_f32_e32 v89, v11, v0
	s_waitcnt vmcnt(5)
	v_fmac_f32_e32 v90, v12, v0
	s_waitcnt vmcnt(4)
	v_fmac_f32_e32 v91, v13, v0
	s_waitcnt vmcnt(3)
	v_fmac_f32_e32 v92, v14, v0
	s_waitcnt vmcnt(2)
	v_fmac_f32_e32 v93, v15, v0
	s_waitcnt vmcnt(1)
	v_fmac_f32_e32 v94, v16, v0
	s_waitcnt vmcnt(0)
	v_fmac_f32_e32 v95, v17, v0
	global_store_dword v[134:135], v48, off offset:128
	global_store_dword v[50:51], v49, off offset:128
	global_store_dword v[136:137], v66, off offset:128
	global_store_dword v[52:53], v67, off offset:128
	global_store_dword v[138:139], v68, off offset:128
	global_store_dword v[140:141], v69, off offset:128
	global_store_dword v[54:55], v70, off offset:128
	global_store_dword v[142:143], v71, off offset:128
	global_store_dword v[56:57], v72, off offset:128
	global_store_dword v[144:145], v73, off offset:128
	global_store_dword v[58:59], v74, off offset:128
	global_store_dword v[146:147], v75, off offset:128
	global_store_dword v[60:61], v76, off offset:128
	global_store_dword v[148:149], v77, off offset:128
	global_store_dword v[62:63], v78, off offset:128
	global_store_dword v[150:151], v79, off offset:128
	global_store_dword v[64:65], v80, off offset:128
	global_store_dword v[152:153], v81, off offset:128
	global_store_dword v[34:35], v82, off offset:128
	global_store_dword v[154:155], v83, off offset:128
	global_store_dword v[36:37], v84, off offset:128
	global_store_dword v[156:157], v85, off offset:128
	global_store_dword v[38:39], v86, off offset:128
	global_store_dword v[158:159], v87, off offset:128
	global_store_dword v[40:41], v88, off offset:128
	global_store_dword v[160:161], v89, off offset:128
	global_store_dword v[42:43], v90, off offset:128
	global_store_dword v[162:163], v91, off offset:128
	global_store_dword v[44:45], v92, off offset:128
	global_store_dword v[164:165], v93, off offset:128
	global_store_dword v[46:47], v94, off offset:128
	global_store_dword v[166:167], v95, off offset:128
	s_cmpk_lt_i32 s4, 0x400
	s_cbranch_scc1 .LBB0_1186
	s_cmpk_ge_i32 s4, 0x600
	s_cbranch_scc1 .Lph6_done
	s_cmpk_le_i32 s59, 0x400
	s_cbranch_scc1 .Lph6_done
	v_readlane_b32 s5, v209, 2
	s_cmpk_ge_u32 s5, 0x40
	s_cbranch_scc1 .Lph6_done
	s_add_i32 s4, s5, 0x400
	s_lshl_b32 s3, s4, 7
	s_branch .LBB0_1186

.LBB0_1298:
	s_ashr_i32 s6, s5, 31
	s_lshr_b32 s6, s6, 27
	s_add_i32 s6, s5, s6
	s_ashr_i32 s34, s6, 5
	s_ashr_i32 s35, s34, 31
	v_mov_b32_e32 v36, v133
	s_lshl_b64 s[6:7], s[34:35], 18
	s_add_u32 s6, s38, s6
	v_ashrrev_i32_e32 v34, 3, v36
	v_ashrrev_i32_e32 v35, 31, v34
	s_addc_u32 s7, s39, s7
	v_lshlrev_b64 v[2:3], 11, v[34:35]
	v_lshlrev_b32_e32 v0, 4, v36
	v_lshl_add_u64 v[2:3], s[6:7], 0, v[2:3]
	v_and_b32_e32 v0, 0x70, v0
	s_lshl_b32 s6, s34, 12
	v_lshl_add_u64 v[66:67], v[2:3], 0, v[0:1]
	v_subrev_u32_e32 v2, s6, v34
	v_add_u32_e32 v2, s4, v2
	v_ashrrev_i32_e32 v3, 31, v2
	v_lshlrev_b64 v[2:3], 11, v[2:3]
	v_lshl_add_u64 v[2:3], s[0:1], 0, v[2:3]
	v_add_co_u32_e32 v70, vcc, s56, v66
	v_lshl_add_u64 v[68:69], v[2:3], 0, v[0:1]
	s_nop 0
	v_addc_co_u32_e32 v71, vcc, 0, v67, vcc
	v_add_co_u32_e32 v72, vcc, s56, v68
	v_addc_co_u32_e32 v73, vcc, 0, v69, vcc
	v_add_co_u32_e32 v74, vcc, s57, v66
	s_nop 0
	v_addc_co_u32_e32 v75, vcc, 0, v67, vcc
	v_add_co_u32_e32 v76, vcc, s57, v68
	s_nop 0
	v_addc_co_u32_e32 v77, vcc, 0, v69, vcc
	v_add_co_u32_e32 v78, vcc, s58, v66
	s_nop 0
	v_addc_co_u32_e32 v79, vcc, 0, v67, vcc
	v_add_co_u32_e32 v80, vcc, s58, v68
	v_lshlrev_b32_e32 v0, 7, v34
	s_nop 0
	v_addc_co_u32_e32 v81, vcc, 0, v69, vcc
	v_lshrrev_b32_e32 v216, 4, v133
	v_xor_b32_e32 v216, v216, v133
	v_and_b32_e32 v216, 7, v216
	v_lshlrev_b32_e32 v216, 4, v216
	v_mov_b32_e32 v217, 0x70
	v_lshrrev_b32_e32 v218, 6, v133
	v_lshlrev_b32_e32 v218, 10, v218
	s_nop 0
	v_readfirstlane_b32 s32, v218
	v_bfi_b32 v66, v217, v216, v66
	v_bfi_b32 v70, v217, v216, v70
	v_bfi_b32 v74, v217, v216, v74
	v_bfi_b32 v78, v217, v216, v78
	v_bfi_b32 v68, v217, v216, v68
	v_bfi_b32 v72, v217, v216, v72
	v_bfi_b32 v76, v217, v216, v76
	v_bfi_b32 v80, v217, v216, v80
	s_mov_b64 s[98:99], 0x80
	s_add_u32 m0, s32, 0x0
	s_nop 0
	global_load_lds_dwordx4 v[66:67], off
	s_add_u32 m0, s32, 0x1000
	s_nop 0
	global_load_lds_dwordx4 v[70:71], off
	s_add_u32 m0, s32, 0x2000
	s_nop 0
	global_load_lds_dwordx4 v[74:75], off
	s_add_u32 m0, s32, 0x3000
	s_nop 0
	global_load_lds_dwordx4 v[78:79], off
	s_add_u32 m0, s32, 0x8000
	s_nop 0
	global_load_lds_dwordx4 v[68:69], off
	s_add_u32 m0, s32, 0x9000
	s_nop 0
	global_load_lds_dwordx4 v[72:73], off
	s_add_u32 m0, s32, 0xa000
	s_nop 0
	global_load_lds_dwordx4 v[76:77], off
	s_add_u32 m0, s32, 0xb000
	s_nop 0
	global_load_lds_dwordx4 v[80:81], off
	v_lshl_add_u64 v[66:67], v[66:67], 0, s[98:99]
	v_lshl_add_u64 v[70:71], v[70:71], 0, s[98:99]
	v_lshl_add_u64 v[74:75], v[74:75], 0, s[98:99]
	v_lshl_add_u64 v[78:79], v[78:79], 0, s[98:99]
	v_lshl_add_u64 v[68:69], v[68:69], 0, s[98:99]
	v_lshl_add_u64 v[72:73], v[72:73], 0, s[98:99]
	v_lshl_add_u64 v[76:77], v[76:77], 0, s[98:99]
	v_lshl_add_u64 v[80:81], v[80:81], 0, s[98:99]
	s_add_u32 m0, s32, 0x4000
	s_nop 0
	global_load_lds_dwordx4 v[66:67], off
	s_add_u32 m0, s32, 0x5000
	s_nop 0
	global_load_lds_dwordx4 v[70:71], off
	s_add_u32 m0, s32, 0x6000
	s_nop 0
	global_load_lds_dwordx4 v[74:75], off
	s_add_u32 m0, s32, 0x7000
	s_nop 0
	global_load_lds_dwordx4 v[78:79], off
	s_add_u32 m0, s32, 0xc000
	s_nop 0
	global_load_lds_dwordx4 v[68:69], off
	s_add_u32 m0, s32, 0xd000
	s_nop 0
	global_load_lds_dwordx4 v[72:73], off
	s_add_u32 m0, s32, 0xe000
	s_nop 0
	global_load_lds_dwordx4 v[76:77], off
	s_add_u32 m0, s32, 0xf000
	s_nop 0
	global_load_lds_dwordx4 v[80:81], off
	v_lshrrev_b32_e32 v34, 1, v34
	v_xor_b32_e32 v34, v34, v36
	v_lshlrev_b32_e32 v34, 4, v34
	v_and_or_b32 v0, v34, s59, v0
	s_waitcnt vmcnt(26)
	v_and_b32_e32 v82, 31, v36
	v_bfe_u32 v83, v36, 5, 1
	v_ashrrev_i32_e32 v84, 7, v36
	v_bfe_u32 v85, v36, 6, 1
	v_lshl_add_u64 v[66:67], v[66:67], 0, s[98:99]
	v_lshl_add_u64 v[70:71], v[70:71], 0, s[98:99]
	v_lshl_add_u64 v[74:75], v[74:75], 0, s[98:99]
	v_lshl_add_u64 v[78:79], v[78:79], 0, s[98:99]
	v_lshl_add_u64 v[68:69], v[68:69], 0, s[98:99]
	v_lshl_add_u64 v[72:73], v[72:73], 0, s[98:99]
	v_lshl_add_u64 v[76:77], v[76:77], 0, s[98:99]
	v_lshl_add_u64 v[80:81], v[80:81], 0, s[98:99]
	s_waitcnt vmcnt(8)
	s_waitcnt lgkmcnt(0)
	s_barrier
	v_lshrrev_b32_e32 v4, 1, v36
	v_lshlrev_b32_e32 v2, 7, v82
	v_bitop3_b32 v4, v4, v83, 7 bitop3:0x6c
	v_lshl_or_b32 v3, v84, 13, v2
	v_bfe_u32 v5, v36, 1, 3
	v_lshlrev_b32_e32 v4, 4, v4
	v_lshl_or_b32 v2, v85, 13, v2
	v_or_b32_e32 v91, v3, v4
	v_or_b32_e32 v92, v2, v4
	v_bitop3_b32 v4, v83, v5, 2 bitop3:0x36
	v_lshlrev_b32_e32 v4, 4, v4
	v_or_b32_e32 v93, v3, v4
	v_or_b32_e32 v90, v2, v4
	v_bitop3_b32 v4, v83, v5, 4 bitop3:0x36
	v_lshlrev_b32_e32 v4, 4, v4
	v_or_b32_e32 v89, v3, v4
	v_or_b32_e32 v88, v2, v4
	v_bitop3_b32 v4, v83, v5, 6 bitop3:0x36
	v_lshlrev_b32_e32 v4, 4, v4
	v_or_b32_e32 v87, v3, v4
	v_or_b32_e32 v86, v2, v4
	ds_read_b128 v[2:5], v91
	ds_read_b128 v[6:9], v92 offset:32768
	ds_read_b128 v[10:13], v91 offset:4096
	ds_read_b128 v[14:17], v92 offset:36864
	ds_read_b128 v[162:165], v93
	ds_read_b128 v[166:169], v90 offset:32768
	ds_read_b128 v[182:185], v93 offset:4096
	ds_read_b128 v[186:189], v90 offset:36864
	s_waitcnt lgkmcnt(6)
	v_mfma_f32_32x32x16_bf16 v[50:65], v[2:5], v[6:9], 0
	s_waitcnt lgkmcnt(4)
	v_mfma_f32_32x32x16_bf16 v[34:49], v[2:5], v[14:17], 0
	v_mfma_f32_32x32x16_bf16 v[18:33], v[10:13], v[6:9], 0
	v_mfma_f32_32x32x16_bf16 v[2:17], v[10:13], v[14:17], 0
	ds_read_b128 v[190:193], v89
	ds_read_b128 v[194:197], v89 offset:4096
	ds_read_b128 v[198:201], v88 offset:32768
	ds_read_b128 v[202:205], v88 offset:36864
	s_waitcnt lgkmcnt(6)
	v_mfma_f32_32x32x16_bf16 v[50:65], v[162:165], v[166:169], v[50:65]
	s_waitcnt lgkmcnt(4)
	v_mfma_f32_32x32x16_bf16 v[34:49], v[162:165], v[186:189], v[34:49]
	v_mfma_f32_32x32x16_bf16 v[18:33], v[182:185], v[166:169], v[18:33]
	v_mfma_f32_32x32x16_bf16 v[2:17], v[182:185], v[186:189], v[2:17]
	ds_read_b128 v[162:165], v87
	ds_read_b128 v[166:169], v87 offset:4096
	ds_read_b128 v[182:185], v86 offset:32768
	ds_read_b128 v[186:189], v86 offset:36864
	s_waitcnt lgkmcnt(0)
	s_barrier
	s_add_u32 m0, s32, 0x0
	v_mfma_f32_32x32x16_bf16 v[50:65], v[190:193], v[198:201], v[50:65]
	global_load_lds_dwordx4 v[66:67], off
	s_add_u32 m0, s32, 0x1000
	v_mfma_f32_32x32x16_bf16 v[34:49], v[190:193], v[202:205], v[34:49]
	global_load_lds_dwordx4 v[70:71], off
	s_add_u32 m0, s32, 0x2000
	v_mfma_f32_32x32x16_bf16 v[18:33], v[194:197], v[198:201], v[18:33]
	global_load_lds_dwordx4 v[74:75], off
	s_add_u32 m0, s32, 0x3000
	v_mfma_f32_32x32x16_bf16 v[2:17], v[194:197], v[202:205], v[2:17]
	global_load_lds_dwordx4 v[78:79], off
	s_add_u32 m0, s32, 0x8000
	v_mfma_f32_32x32x16_bf16 v[50:65], v[162:165], v[182:185], v[50:65]
	global_load_lds_dwordx4 v[68:69], off
	s_add_u32 m0, s32, 0x9000
	v_mfma_f32_32x32x16_bf16 v[34:49], v[162:165], v[186:189], v[34:49]
	global_load_lds_dwordx4 v[72:73], off
	s_add_u32 m0, s32, 0xa000
	v_mfma_f32_32x32x16_bf16 v[18:33], v[166:169], v[182:185], v[18:33]
	global_load_lds_dwordx4 v[76:77], off
	s_add_u32 m0, s32, 0xb000
	v_mfma_f32_32x32x16_bf16 v[2:17], v[166:169], v[186:189], v[2:17]
	global_load_lds_dwordx4 v[80:81], off
	s_waitcnt vmcnt(8)
	s_barrier
	ds_read_b128 v[162:165], v91 offset:16384
	ds_read_b128 v[166:169], v92 offset:49152
	ds_read_b128 v[182:185], v91 offset:20480
	ds_read_b128 v[186:189], v92 offset:53248
	ds_read_b128 v[190:193], v93 offset:16384
	ds_read_b128 v[194:197], v90 offset:49152
	ds_read_b128 v[198:201], v93 offset:20480
	ds_read_b128 v[202:205], v90 offset:53248
	s_waitcnt lgkmcnt(6)
	v_mfma_f32_32x32x16_bf16 v[50:65], v[162:165], v[166:169], v[50:65]
	s_waitcnt lgkmcnt(4)
	v_mfma_f32_32x32x16_bf16 v[34:49], v[162:165], v[186:189], v[34:49]
	v_mfma_f32_32x32x16_bf16 v[18:33], v[182:185], v[166:169], v[18:33]
	v_mfma_f32_32x32x16_bf16 v[2:17], v[182:185], v[186:189], v[2:17]
	ds_read_b128 v[162:165], v89 offset:16384
	ds_read_b128 v[166:169], v89 offset:20480
	ds_read_b128 v[182:185], v88 offset:49152
	ds_read_b128 v[186:189], v88 offset:53248
	s_waitcnt lgkmcnt(6)
	v_mfma_f32_32x32x16_bf16 v[50:65], v[190:193], v[194:197], v[50:65]
	s_waitcnt lgkmcnt(4)
	v_mfma_f32_32x32x16_bf16 v[34:49], v[190:193], v[202:205], v[34:49]
	v_mfma_f32_32x32x16_bf16 v[18:33], v[198:201], v[194:197], v[18:33]
	v_mfma_f32_32x32x16_bf16 v[2:17], v[198:201], v[202:205], v[2:17]
	ds_read_b128 v[190:193], v87 offset:16384
	ds_read_b128 v[194:197], v87 offset:20480
	ds_read_b128 v[198:201], v86 offset:49152
	ds_read_b128 v[202:205], v86 offset:53248
	v_lshl_add_u64 v[66:67], v[66:67], 0, s[98:99]
	v_lshl_add_u64 v[70:71], v[70:71], 0, s[98:99]
	v_lshl_add_u64 v[74:75], v[74:75], 0, s[98:99]
	v_lshl_add_u64 v[78:79], v[78:79], 0, s[98:99]
	v_lshl_add_u64 v[68:69], v[68:69], 0, s[98:99]
	v_lshl_add_u64 v[72:73], v[72:73], 0, s[98:99]
	v_lshl_add_u64 v[76:77], v[76:77], 0, s[98:99]
	v_lshl_add_u64 v[80:81], v[80:81], 0, s[98:99]
	s_waitcnt lgkmcnt(0)
	s_barrier
	s_add_u32 m0, s32, 0x4000
	v_mfma_f32_32x32x16_bf16 v[50:65], v[162:165], v[182:185], v[50:65]
	global_load_lds_dwordx4 v[66:67], off
	s_add_u32 m0, s32, 0x5000
	v_mfma_f32_32x32x16_bf16 v[34:49], v[162:165], v[186:189], v[34:49]
	global_load_lds_dwordx4 v[70:71], off
	s_add_u32 m0, s32, 0x6000
	v_mfma_f32_32x32x16_bf16 v[18:33], v[166:169], v[182:185], v[18:33]
	global_load_lds_dwordx4 v[74:75], off
	s_add_u32 m0, s32, 0x7000
	v_mfma_f32_32x32x16_bf16 v[2:17], v[166:169], v[186:189], v[2:17]
	global_load_lds_dwordx4 v[78:79], off
	s_add_u32 m0, s32, 0xc000
	v_mfma_f32_32x32x16_bf16 v[50:65], v[190:193], v[198:201], v[50:65]
	global_load_lds_dwordx4 v[68:69], off
	s_add_u32 m0, s32, 0xd000
	v_mfma_f32_32x32x16_bf16 v[34:49], v[190:193], v[202:205], v[34:49]
	global_load_lds_dwordx4 v[72:73], off
	s_add_u32 m0, s32, 0xe000
	v_mfma_f32_32x32x16_bf16 v[18:33], v[194:197], v[198:201], v[18:33]
	global_load_lds_dwordx4 v[76:77], off
	s_add_u32 m0, s32, 0xf000
	v_mfma_f32_32x32x16_bf16 v[2:17], v[194:197], v[202:205], v[2:17]
	global_load_lds_dwordx4 v[80:81], off
	s_waitcnt vmcnt(8)
	s_barrier
	ds_read_b128 v[162:165], v91
	ds_read_b128 v[166:169], v92 offset:32768
	ds_read_b128 v[182:185], v91 offset:4096
	ds_read_b128 v[186:189], v92 offset:36864
	ds_read_b128 v[190:193], v93
	ds_read_b128 v[194:197], v90 offset:32768
	ds_read_b128 v[198:201], v93 offset:4096
	ds_read_b128 v[202:205], v90 offset:36864
	s_waitcnt lgkmcnt(6)
	v_mfma_f32_32x32x16_bf16 v[50:65], v[162:165], v[166:169], v[50:65]
	s_waitcnt lgkmcnt(4)
	v_mfma_f32_32x32x16_bf16 v[34:49], v[162:165], v[186:189], v[34:49]
	v_mfma_f32_32x32x16_bf16 v[18:33], v[182:185], v[166:169], v[18:33]
	v_mfma_f32_32x32x16_bf16 v[2:17], v[182:185], v[186:189], v[2:17]
	ds_read_b128 v[162:165], v89
	ds_read_b128 v[166:169], v89 offset:4096
	ds_read_b128 v[182:185], v88 offset:32768
	ds_read_b128 v[186:189], v88 offset:36864
	s_waitcnt lgkmcnt(6)
	v_mfma_f32_32x32x16_bf16 v[50:65], v[190:193], v[194:197], v[50:65]
	s_waitcnt lgkmcnt(4)
	v_mfma_f32_32x32x16_bf16 v[34:49], v[190:193], v[202:205], v[34:49]
	v_mfma_f32_32x32x16_bf16 v[18:33], v[198:201], v[194:197], v[18:33]
	v_mfma_f32_32x32x16_bf16 v[2:17], v[198:201], v[202:205], v[2:17]
	ds_read_b128 v[190:193], v87
	ds_read_b128 v[194:197], v87 offset:4096
	ds_read_b128 v[198:201], v86 offset:32768
	ds_read_b128 v[202:205], v86 offset:36864
	v_lshl_add_u64 v[66:67], v[66:67], 0, s[98:99]
	v_lshl_add_u64 v[70:71], v[70:71], 0, s[98:99]
	v_lshl_add_u64 v[74:75], v[74:75], 0, s[98:99]
	v_lshl_add_u64 v[78:79], v[78:79], 0, s[98:99]
	v_lshl_add_u64 v[68:69], v[68:69], 0, s[98:99]
	v_lshl_add_u64 v[72:73], v[72:73], 0, s[98:99]
	v_lshl_add_u64 v[76:77], v[76:77], 0, s[98:99]
	v_lshl_add_u64 v[80:81], v[80:81], 0, s[98:99]
	s_waitcnt lgkmcnt(0)
	s_barrier
	s_add_u32 m0, s32, 0x0
	v_mfma_f32_32x32x16_bf16 v[50:65], v[162:165], v[182:185], v[50:65]
	global_load_lds_dwordx4 v[66:67], off
	s_add_u32 m0, s32, 0x1000
	v_mfma_f32_32x32x16_bf16 v[34:49], v[162:165], v[186:189], v[34:49]
	global_load_lds_dwordx4 v[70:71], off
	s_add_u32 m0, s32, 0x2000
	v_mfma_f32_32x32x16_bf16 v[18:33], v[166:169], v[182:185], v[18:33]
	global_load_lds_dwordx4 v[74:75], off
	s_add_u32 m0, s32, 0x3000
	v_mfma_f32_32x32x16_bf16 v[2:17], v[166:169], v[186:189], v[2:17]
	global_load_lds_dwordx4 v[78:79], off
	s_add_u32 m0, s32, 0x8000
	v_mfma_f32_32x32x16_bf16 v[50:65], v[190:193], v[198:201], v[50:65]
	global_load_lds_dwordx4 v[68:69], off
	s_add_u32 m0, s32, 0x9000
	v_mfma_f32_32x32x16_bf16 v[34:49], v[190:193], v[202:205], v[34:49]
	global_load_lds_dwordx4 v[72:73], off
	s_add_u32 m0, s32, 0xa000
	v_mfma_f32_32x32x16_bf16 v[18:33], v[194:197], v[198:201], v[18:33]
	global_load_lds_dwordx4 v[76:77], off
	s_add_u32 m0, s32, 0xb000
	v_mfma_f32_32x32x16_bf16 v[2:17], v[194:197], v[202:205], v[2:17]
	global_load_lds_dwordx4 v[80:81], off
	s_waitcnt vmcnt(8)
	s_barrier
	ds_read_b128 v[162:165], v91 offset:16384
	ds_read_b128 v[166:169], v92 offset:49152
	ds_read_b128 v[182:185], v91 offset:20480
	ds_read_b128 v[186:189], v92 offset:53248
	ds_read_b128 v[190:193], v93 offset:16384
	ds_read_b128 v[194:197], v90 offset:49152
	ds_read_b128 v[198:201], v93 offset:20480
	ds_read_b128 v[202:205], v90 offset:53248
	s_waitcnt lgkmcnt(6)
	v_mfma_f32_32x32x16_bf16 v[50:65], v[162:165], v[166:169], v[50:65]
	s_waitcnt lgkmcnt(4)
	v_mfma_f32_32x32x16_bf16 v[34:49], v[162:165], v[186:189], v[34:49]
	v_mfma_f32_32x32x16_bf16 v[18:33], v[182:185], v[166:169], v[18:33]
	v_mfma_f32_32x32x16_bf16 v[2:17], v[182:185], v[186:189], v[2:17]
	ds_read_b128 v[162:165], v89 offset:16384
	ds_read_b128 v[166:169], v89 offset:20480
	ds_read_b128 v[182:185], v88 offset:49152
	ds_read_b128 v[186:189], v88 offset:53248
	s_waitcnt lgkmcnt(6)
	v_mfma_f32_32x32x16_bf16 v[50:65], v[190:193], v[194:197], v[50:65]
	s_waitcnt lgkmcnt(4)
	v_mfma_f32_32x32x16_bf16 v[34:49], v[190:193], v[202:205], v[34:49]
	v_mfma_f32_32x32x16_bf16 v[18:33], v[198:201], v[194:197], v[18:33]
	v_mfma_f32_32x32x16_bf16 v[2:17], v[198:201], v[202:205], v[2:17]
	ds_read_b128 v[190:193], v87 offset:16384
	ds_read_b128 v[194:197], v87 offset:20480
	ds_read_b128 v[198:201], v86 offset:49152
	ds_read_b128 v[202:205], v86 offset:53248
	v_lshl_add_u64 v[66:67], v[66:67], 0, s[98:99]
	v_lshl_add_u64 v[70:71], v[70:71], 0, s[98:99]
	v_lshl_add_u64 v[74:75], v[74:75], 0, s[98:99]
	v_lshl_add_u64 v[78:79], v[78:79], 0, s[98:99]
	v_lshl_add_u64 v[68:69], v[68:69], 0, s[98:99]
	v_lshl_add_u64 v[72:73], v[72:73], 0, s[98:99]
	v_lshl_add_u64 v[76:77], v[76:77], 0, s[98:99]
	v_lshl_add_u64 v[80:81], v[80:81], 0, s[98:99]
	s_waitcnt lgkmcnt(0)
	s_barrier
	s_add_u32 m0, s32, 0x4000
	v_mfma_f32_32x32x16_bf16 v[50:65], v[162:165], v[182:185], v[50:65]
	global_load_lds_dwordx4 v[66:67], off
	s_add_u32 m0, s32, 0x5000
	v_mfma_f32_32x32x16_bf16 v[34:49], v[162:165], v[186:189], v[34:49]
	global_load_lds_dwordx4 v[70:71], off
	s_add_u32 m0, s32, 0x6000
	v_mfma_f32_32x32x16_bf16 v[18:33], v[166:169], v[182:185], v[18:33]
	global_load_lds_dwordx4 v[74:75], off
	s_add_u32 m0, s32, 0x7000
	v_mfma_f32_32x32x16_bf16 v[2:17], v[166:169], v[186:189], v[2:17]
	global_load_lds_dwordx4 v[78:79], off
	s_add_u32 m0, s32, 0xc000
	v_mfma_f32_32x32x16_bf16 v[50:65], v[190:193], v[198:201], v[50:65]
	global_load_lds_dwordx4 v[68:69], off
	s_add_u32 m0, s32, 0xd000
	v_mfma_f32_32x32x16_bf16 v[34:49], v[190:193], v[202:205], v[34:49]
	global_load_lds_dwordx4 v[72:73], off
	s_add_u32 m0, s32, 0xe000
	v_mfma_f32_32x32x16_bf16 v[18:33], v[194:197], v[198:201], v[18:33]
	global_load_lds_dwordx4 v[76:77], off
	s_add_u32 m0, s32, 0xf000
	v_mfma_f32_32x32x16_bf16 v[2:17], v[194:197], v[202:205], v[2:17]
	global_load_lds_dwordx4 v[80:81], off
	s_waitcnt vmcnt(8)
	s_barrier
	ds_read_b128 v[162:165], v91
	ds_read_b128 v[166:169], v92 offset:32768
	ds_read_b128 v[182:185], v91 offset:4096
	ds_read_b128 v[186:189], v92 offset:36864
	ds_read_b128 v[190:193], v93
	ds_read_b128 v[194:197], v90 offset:32768
	ds_read_b128 v[198:201], v93 offset:4096
	ds_read_b128 v[202:205], v90 offset:36864
	s_waitcnt lgkmcnt(6)
	v_mfma_f32_32x32x16_bf16 v[50:65], v[162:165], v[166:169], v[50:65]
	s_waitcnt lgkmcnt(4)
	v_mfma_f32_32x32x16_bf16 v[34:49], v[162:165], v[186:189], v[34:49]
	v_mfma_f32_32x32x16_bf16 v[18:33], v[182:185], v[166:169], v[18:33]
	v_mfma_f32_32x32x16_bf16 v[2:17], v[182:185], v[186:189], v[2:17]
	ds_read_b128 v[162:165], v89
	ds_read_b128 v[166:169], v89 offset:4096
	ds_read_b128 v[182:185], v88 offset:32768
	ds_read_b128 v[186:189], v88 offset:36864
	s_waitcnt lgkmcnt(6)
	v_mfma_f32_32x32x16_bf16 v[50:65], v[190:193], v[194:197], v[50:65]
	s_waitcnt lgkmcnt(4)
	v_mfma_f32_32x32x16_bf16 v[34:49], v[190:193], v[202:205], v[34:49]
	v_mfma_f32_32x32x16_bf16 v[18:33], v[198:201], v[194:197], v[18:33]
	v_mfma_f32_32x32x16_bf16 v[2:17], v[198:201], v[202:205], v[2:17]
	ds_read_b128 v[190:193], v87
	ds_read_b128 v[194:197], v87 offset:4096
	ds_read_b128 v[198:201], v86 offset:32768
	ds_read_b128 v[202:205], v86 offset:36864
	v_lshl_add_u64 v[66:67], v[66:67], 0, s[98:99]
	v_lshl_add_u64 v[70:71], v[70:71], 0, s[98:99]
	v_lshl_add_u64 v[74:75], v[74:75], 0, s[98:99]
	v_lshl_add_u64 v[78:79], v[78:79], 0, s[98:99]
	v_lshl_add_u64 v[68:69], v[68:69], 0, s[98:99]
	v_lshl_add_u64 v[72:73], v[72:73], 0, s[98:99]
	v_lshl_add_u64 v[76:77], v[76:77], 0, s[98:99]
	v_lshl_add_u64 v[80:81], v[80:81], 0, s[98:99]
	s_waitcnt lgkmcnt(0)
	s_barrier
	s_add_u32 m0, s32, 0x0
	v_mfma_f32_32x32x16_bf16 v[50:65], v[162:165], v[182:185], v[50:65]
	global_load_lds_dwordx4 v[66:67], off
	s_add_u32 m0, s32, 0x1000
	v_mfma_f32_32x32x16_bf16 v[34:49], v[162:165], v[186:189], v[34:49]
	global_load_lds_dwordx4 v[70:71], off
	s_add_u32 m0, s32, 0x2000
	v_mfma_f32_32x32x16_bf16 v[18:33], v[166:169], v[182:185], v[18:33]
	global_load_lds_dwordx4 v[74:75], off
	s_add_u32 m0, s32, 0x3000
	v_mfma_f32_32x32x16_bf16 v[2:17], v[166:169], v[186:189], v[2:17]
	global_load_lds_dwordx4 v[78:79], off
	s_add_u32 m0, s32, 0x8000
	v_mfma_f32_32x32x16_bf16 v[50:65], v[190:193], v[198:201], v[50:65]
	global_load_lds_dwordx4 v[68:69], off
	s_add_u32 m0, s32, 0x9000
	v_mfma_f32_32x32x16_bf16 v[34:49], v[190:193], v[202:205], v[34:49]
	global_load_lds_dwordx4 v[72:73], off
	s_add_u32 m0, s32, 0xa000
	v_mfma_f32_32x32x16_bf16 v[18:33], v[194:197], v[198:201], v[18:33]
	global_load_lds_dwordx4 v[76:77], off
	s_add_u32 m0, s32, 0xb000
	v_mfma_f32_32x32x16_bf16 v[2:17], v[194:197], v[202:205], v[2:17]
	global_load_lds_dwordx4 v[80:81], off
	s_waitcnt vmcnt(8)
	s_barrier
	ds_read_b128 v[162:165], v91 offset:16384
	ds_read_b128 v[166:169], v92 offset:49152
	ds_read_b128 v[182:185], v91 offset:20480
	ds_read_b128 v[186:189], v92 offset:53248
	ds_read_b128 v[190:193], v93 offset:16384
	ds_read_b128 v[194:197], v90 offset:49152
	ds_read_b128 v[198:201], v93 offset:20480
	ds_read_b128 v[202:205], v90 offset:53248
	s_waitcnt lgkmcnt(6)
	v_mfma_f32_32x32x16_bf16 v[50:65], v[162:165], v[166:169], v[50:65]
	s_waitcnt lgkmcnt(4)
	v_mfma_f32_32x32x16_bf16 v[34:49], v[162:165], v[186:189], v[34:49]
	v_mfma_f32_32x32x16_bf16 v[18:33], v[182:185], v[166:169], v[18:33]
	v_mfma_f32_32x32x16_bf16 v[2:17], v[182:185], v[186:189], v[2:17]
	ds_read_b128 v[162:165], v89 offset:16384
	ds_read_b128 v[166:169], v89 offset:20480
	ds_read_b128 v[182:185], v88 offset:49152
	ds_read_b128 v[186:189], v88 offset:53248
	s_waitcnt lgkmcnt(6)
	v_mfma_f32_32x32x16_bf16 v[50:65], v[190:193], v[194:197], v[50:65]
	s_waitcnt lgkmcnt(4)
	v_mfma_f32_32x32x16_bf16 v[34:49], v[190:193], v[202:205], v[34:49]
	v_mfma_f32_32x32x16_bf16 v[18:33], v[198:201], v[194:197], v[18:33]
	v_mfma_f32_32x32x16_bf16 v[2:17], v[198:201], v[202:205], v[2:17]
	ds_read_b128 v[190:193], v87 offset:16384
	ds_read_b128 v[194:197], v87 offset:20480
	ds_read_b128 v[198:201], v86 offset:49152
	ds_read_b128 v[202:205], v86 offset:53248
	v_lshl_add_u64 v[66:67], v[66:67], 0, s[98:99]
	v_lshl_add_u64 v[70:71], v[70:71], 0, s[98:99]
	v_lshl_add_u64 v[74:75], v[74:75], 0, s[98:99]
	v_lshl_add_u64 v[78:79], v[78:79], 0, s[98:99]
	v_lshl_add_u64 v[68:69], v[68:69], 0, s[98:99]
	v_lshl_add_u64 v[72:73], v[72:73], 0, s[98:99]
	v_lshl_add_u64 v[76:77], v[76:77], 0, s[98:99]
	v_lshl_add_u64 v[80:81], v[80:81], 0, s[98:99]
	s_waitcnt lgkmcnt(0)
	s_barrier
	s_add_u32 m0, s32, 0x4000
	v_mfma_f32_32x32x16_bf16 v[50:65], v[162:165], v[182:185], v[50:65]
	global_load_lds_dwordx4 v[66:67], off
	s_add_u32 m0, s32, 0x5000
	v_mfma_f32_32x32x16_bf16 v[34:49], v[162:165], v[186:189], v[34:49]
	global_load_lds_dwordx4 v[70:71], off
	s_add_u32 m0, s32, 0x6000
	v_mfma_f32_32x32x16_bf16 v[18:33], v[166:169], v[182:185], v[18:33]
	global_load_lds_dwordx4 v[74:75], off
	s_add_u32 m0, s32, 0x7000
	v_mfma_f32_32x32x16_bf16 v[2:17], v[166:169], v[186:189], v[2:17]
	global_load_lds_dwordx4 v[78:79], off
	s_add_u32 m0, s32, 0xc000
	v_mfma_f32_32x32x16_bf16 v[50:65], v[190:193], v[198:201], v[50:65]
	global_load_lds_dwordx4 v[68:69], off
	s_add_u32 m0, s32, 0xd000
	v_mfma_f32_32x32x16_bf16 v[34:49], v[190:193], v[202:205], v[34:49]
	global_load_lds_dwordx4 v[72:73], off
	s_add_u32 m0, s32, 0xe000
	v_mfma_f32_32x32x16_bf16 v[18:33], v[194:197], v[198:201], v[18:33]
	global_load_lds_dwordx4 v[76:77], off
	s_add_u32 m0, s32, 0xf000
	v_mfma_f32_32x32x16_bf16 v[2:17], v[194:197], v[202:205], v[2:17]
	global_load_lds_dwordx4 v[80:81], off
	s_waitcnt vmcnt(8)
	s_barrier
	ds_read_b128 v[162:165], v91
	ds_read_b128 v[166:169], v92 offset:32768
	ds_read_b128 v[182:185], v91 offset:4096
	ds_read_b128 v[186:189], v92 offset:36864
	ds_read_b128 v[190:193], v93
	ds_read_b128 v[194:197], v90 offset:32768
	ds_read_b128 v[198:201], v93 offset:4096
	ds_read_b128 v[202:205], v90 offset:36864
	s_waitcnt lgkmcnt(6)
	v_mfma_f32_32x32x16_bf16 v[50:65], v[162:165], v[166:169], v[50:65]
	s_waitcnt lgkmcnt(4)
	v_mfma_f32_32x32x16_bf16 v[34:49], v[162:165], v[186:189], v[34:49]
	v_mfma_f32_32x32x16_bf16 v[18:33], v[182:185], v[166:169], v[18:33]
	v_mfma_f32_32x32x16_bf16 v[2:17], v[182:185], v[186:189], v[2:17]
	ds_read_b128 v[162:165], v89
	ds_read_b128 v[166:169], v89 offset:4096
	ds_read_b128 v[182:185], v88 offset:32768
	ds_read_b128 v[186:189], v88 offset:36864
	s_waitcnt lgkmcnt(6)
	v_mfma_f32_32x32x16_bf16 v[50:65], v[190:193], v[194:197], v[50:65]
	s_waitcnt lgkmcnt(4)
	v_mfma_f32_32x32x16_bf16 v[34:49], v[190:193], v[202:205], v[34:49]
	v_mfma_f32_32x32x16_bf16 v[18:33], v[198:201], v[194:197], v[18:33]
	v_mfma_f32_32x32x16_bf16 v[2:17], v[198:201], v[202:205], v[2:17]
	ds_read_b128 v[190:193], v87
	ds_read_b128 v[194:197], v87 offset:4096
	ds_read_b128 v[198:201], v86 offset:32768
	ds_read_b128 v[202:205], v86 offset:36864
	v_lshl_add_u64 v[66:67], v[66:67], 0, s[98:99]
	v_lshl_add_u64 v[70:71], v[70:71], 0, s[98:99]
	v_lshl_add_u64 v[74:75], v[74:75], 0, s[98:99]
	v_lshl_add_u64 v[78:79], v[78:79], 0, s[98:99]
	v_lshl_add_u64 v[68:69], v[68:69], 0, s[98:99]
	v_lshl_add_u64 v[72:73], v[72:73], 0, s[98:99]
	v_lshl_add_u64 v[76:77], v[76:77], 0, s[98:99]
	v_lshl_add_u64 v[80:81], v[80:81], 0, s[98:99]
	s_waitcnt lgkmcnt(0)
	s_barrier
	s_add_u32 m0, s32, 0x0
	v_mfma_f32_32x32x16_bf16 v[50:65], v[162:165], v[182:185], v[50:65]
	global_load_lds_dwordx4 v[66:67], off
	s_add_u32 m0, s32, 0x1000
	v_mfma_f32_32x32x16_bf16 v[34:49], v[162:165], v[186:189], v[34:49]
	global_load_lds_dwordx4 v[70:71], off
	s_add_u32 m0, s32, 0x2000
	v_mfma_f32_32x32x16_bf16 v[18:33], v[166:169], v[182:185], v[18:33]
	global_load_lds_dwordx4 v[74:75], off
	s_add_u32 m0, s32, 0x3000
	v_mfma_f32_32x32x16_bf16 v[2:17], v[166:169], v[186:189], v[2:17]
	global_load_lds_dwordx4 v[78:79], off
	s_add_u32 m0, s32, 0x8000
	v_mfma_f32_32x32x16_bf16 v[50:65], v[190:193], v[198:201], v[50:65]
	global_load_lds_dwordx4 v[68:69], off
	s_add_u32 m0, s32, 0x9000
	v_mfma_f32_32x32x16_bf16 v[34:49], v[190:193], v[202:205], v[34:49]
	global_load_lds_dwordx4 v[72:73], off
	s_add_u32 m0, s32, 0xa000
	v_mfma_f32_32x32x16_bf16 v[18:33], v[194:197], v[198:201], v[18:33]
	global_load_lds_dwordx4 v[76:77], off
	s_add_u32 m0, s32, 0xb000
	v_mfma_f32_32x32x16_bf16 v[2:17], v[194:197], v[202:205], v[2:17]
	global_load_lds_dwordx4 v[80:81], off
	s_waitcnt vmcnt(8)
	s_barrier
	ds_read_b128 v[162:165], v91 offset:16384
	ds_read_b128 v[166:169], v92 offset:49152
	ds_read_b128 v[182:185], v91 offset:20480
	ds_read_b128 v[186:189], v92 offset:53248
	ds_read_b128 v[190:193], v93 offset:16384
	ds_read_b128 v[194:197], v90 offset:49152
	ds_read_b128 v[198:201], v93 offset:20480
	ds_read_b128 v[202:205], v90 offset:53248
	s_waitcnt lgkmcnt(6)
	v_mfma_f32_32x32x16_bf16 v[50:65], v[162:165], v[166:169], v[50:65]
	s_waitcnt lgkmcnt(4)
	v_mfma_f32_32x32x16_bf16 v[34:49], v[162:165], v[186:189], v[34:49]
	v_mfma_f32_32x32x16_bf16 v[18:33], v[182:185], v[166:169], v[18:33]
	v_mfma_f32_32x32x16_bf16 v[2:17], v[182:185], v[186:189], v[2:17]
	ds_read_b128 v[162:165], v89 offset:16384
	ds_read_b128 v[166:169], v89 offset:20480
	ds_read_b128 v[182:185], v88 offset:49152
	ds_read_b128 v[186:189], v88 offset:53248
	s_waitcnt lgkmcnt(6)
	v_mfma_f32_32x32x16_bf16 v[50:65], v[190:193], v[194:197], v[50:65]
	s_waitcnt lgkmcnt(4)
	v_mfma_f32_32x32x16_bf16 v[34:49], v[190:193], v[202:205], v[34:49]
	v_mfma_f32_32x32x16_bf16 v[18:33], v[198:201], v[194:197], v[18:33]
	v_mfma_f32_32x32x16_bf16 v[2:17], v[198:201], v[202:205], v[2:17]
	ds_read_b128 v[190:193], v87 offset:16384
	ds_read_b128 v[194:197], v87 offset:20480
	ds_read_b128 v[198:201], v86 offset:49152
	ds_read_b128 v[202:205], v86 offset:53248
	v_lshl_add_u64 v[66:67], v[66:67], 0, s[98:99]
	v_lshl_add_u64 v[70:71], v[70:71], 0, s[98:99]
	v_lshl_add_u64 v[74:75], v[74:75], 0, s[98:99]
	v_lshl_add_u64 v[78:79], v[78:79], 0, s[98:99]
	v_lshl_add_u64 v[68:69], v[68:69], 0, s[98:99]
	v_lshl_add_u64 v[72:73], v[72:73], 0, s[98:99]
	v_lshl_add_u64 v[76:77], v[76:77], 0, s[98:99]
	v_lshl_add_u64 v[80:81], v[80:81], 0, s[98:99]
	s_waitcnt lgkmcnt(0)
	s_barrier
	s_add_u32 m0, s32, 0x4000
	v_mfma_f32_32x32x16_bf16 v[50:65], v[162:165], v[182:185], v[50:65]
	global_load_lds_dwordx4 v[66:67], off
	s_add_u32 m0, s32, 0x5000
	v_mfma_f32_32x32x16_bf16 v[34:49], v[162:165], v[186:189], v[34:49]
	global_load_lds_dwordx4 v[70:71], off
	s_add_u32 m0, s32, 0x6000
	v_mfma_f32_32x32x16_bf16 v[18:33], v[166:169], v[182:185], v[18:33]
	global_load_lds_dwordx4 v[74:75], off
	s_add_u32 m0, s32, 0x7000
	v_mfma_f32_32x32x16_bf16 v[2:17], v[166:169], v[186:189], v[2:17]
	global_load_lds_dwordx4 v[78:79], off
	s_add_u32 m0, s32, 0xc000
	v_mfma_f32_32x32x16_bf16 v[50:65], v[190:193], v[198:201], v[50:65]
	global_load_lds_dwordx4 v[68:69], off
	s_add_u32 m0, s32, 0xd000
	v_mfma_f32_32x32x16_bf16 v[34:49], v[190:193], v[202:205], v[34:49]
	global_load_lds_dwordx4 v[72:73], off
	s_add_u32 m0, s32, 0xe000
	v_mfma_f32_32x32x16_bf16 v[18:33], v[194:197], v[198:201], v[18:33]
	global_load_lds_dwordx4 v[76:77], off
	s_add_u32 m0, s32, 0xf000
	v_mfma_f32_32x32x16_bf16 v[2:17], v[194:197], v[202:205], v[2:17]
	global_load_lds_dwordx4 v[80:81], off
	s_waitcnt vmcnt(8)
	s_barrier
	ds_read_b128 v[162:165], v91
	ds_read_b128 v[166:169], v92 offset:32768
	ds_read_b128 v[182:185], v91 offset:4096
	ds_read_b128 v[186:189], v92 offset:36864
	ds_read_b128 v[190:193], v93
	ds_read_b128 v[194:197], v90 offset:32768
	ds_read_b128 v[198:201], v93 offset:4096
	ds_read_b128 v[202:205], v90 offset:36864
	s_waitcnt lgkmcnt(6)
	v_mfma_f32_32x32x16_bf16 v[50:65], v[162:165], v[166:169], v[50:65]
	s_waitcnt lgkmcnt(4)
	v_mfma_f32_32x32x16_bf16 v[34:49], v[162:165], v[186:189], v[34:49]
	v_mfma_f32_32x32x16_bf16 v[18:33], v[182:185], v[166:169], v[18:33]
	v_mfma_f32_32x32x16_bf16 v[2:17], v[182:185], v[186:189], v[2:17]
	ds_read_b128 v[162:165], v89
	ds_read_b128 v[166:169], v89 offset:4096
	ds_read_b128 v[182:185], v88 offset:32768
	ds_read_b128 v[186:189], v88 offset:36864
	s_waitcnt lgkmcnt(6)
	v_mfma_f32_32x32x16_bf16 v[50:65], v[190:193], v[194:197], v[50:65]
	s_waitcnt lgkmcnt(4)
	v_mfma_f32_32x32x16_bf16 v[34:49], v[190:193], v[202:205], v[34:49]
	v_mfma_f32_32x32x16_bf16 v[18:33], v[198:201], v[194:197], v[18:33]
	v_mfma_f32_32x32x16_bf16 v[2:17], v[198:201], v[202:205], v[2:17]
	ds_read_b128 v[190:193], v87
	ds_read_b128 v[194:197], v87 offset:4096
	ds_read_b128 v[198:201], v86 offset:32768
	ds_read_b128 v[202:205], v86 offset:36864
	v_lshl_add_u64 v[66:67], v[66:67], 0, s[98:99]
	v_lshl_add_u64 v[70:71], v[70:71], 0, s[98:99]
	v_lshl_add_u64 v[74:75], v[74:75], 0, s[98:99]
	v_lshl_add_u64 v[78:79], v[78:79], 0, s[98:99]
	v_lshl_add_u64 v[68:69], v[68:69], 0, s[98:99]
	v_lshl_add_u64 v[72:73], v[72:73], 0, s[98:99]
	v_lshl_add_u64 v[76:77], v[76:77], 0, s[98:99]
	v_lshl_add_u64 v[80:81], v[80:81], 0, s[98:99]
	s_waitcnt lgkmcnt(0)
	s_barrier
	s_add_u32 m0, s32, 0x0
	v_mfma_f32_32x32x16_bf16 v[50:65], v[162:165], v[182:185], v[50:65]
	global_load_lds_dwordx4 v[66:67], off
	s_add_u32 m0, s32, 0x1000
	v_mfma_f32_32x32x16_bf16 v[34:49], v[162:165], v[186:189], v[34:49]
	global_load_lds_dwordx4 v[70:71], off
	s_add_u32 m0, s32, 0x2000
	v_mfma_f32_32x32x16_bf16 v[18:33], v[166:169], v[182:185], v[18:33]
	global_load_lds_dwordx4 v[74:75], off
	s_add_u32 m0, s32, 0x3000
	v_mfma_f32_32x32x16_bf16 v[2:17], v[166:169], v[186:189], v[2:17]
	global_load_lds_dwordx4 v[78:79], off
	s_add_u32 m0, s32, 0x8000
	v_mfma_f32_32x32x16_bf16 v[50:65], v[190:193], v[198:201], v[50:65]
	global_load_lds_dwordx4 v[68:69], off
	s_add_u32 m0, s32, 0x9000
	v_mfma_f32_32x32x16_bf16 v[34:49], v[190:193], v[202:205], v[34:49]
	global_load_lds_dwordx4 v[72:73], off
	s_add_u32 m0, s32, 0xa000
	v_mfma_f32_32x32x16_bf16 v[18:33], v[194:197], v[198:201], v[18:33]
	global_load_lds_dwordx4 v[76:77], off
	s_add_u32 m0, s32, 0xb000
	v_mfma_f32_32x32x16_bf16 v[2:17], v[194:197], v[202:205], v[2:17]
	global_load_lds_dwordx4 v[80:81], off
	s_waitcnt vmcnt(8)
	s_barrier
	ds_read_b128 v[162:165], v91 offset:16384
	ds_read_b128 v[166:169], v92 offset:49152
	ds_read_b128 v[182:185], v91 offset:20480
	ds_read_b128 v[186:189], v92 offset:53248
	ds_read_b128 v[190:193], v93 offset:16384
	ds_read_b128 v[194:197], v90 offset:49152
	ds_read_b128 v[198:201], v93 offset:20480
	ds_read_b128 v[202:205], v90 offset:53248
	s_waitcnt lgkmcnt(6)
	v_mfma_f32_32x32x16_bf16 v[50:65], v[162:165], v[166:169], v[50:65]
	s_waitcnt lgkmcnt(4)
	v_mfma_f32_32x32x16_bf16 v[34:49], v[162:165], v[186:189], v[34:49]
	v_mfma_f32_32x32x16_bf16 v[18:33], v[182:185], v[166:169], v[18:33]
	v_mfma_f32_32x32x16_bf16 v[2:17], v[182:185], v[186:189], v[2:17]
	ds_read_b128 v[162:165], v89 offset:16384
	ds_read_b128 v[166:169], v89 offset:20480
	ds_read_b128 v[182:185], v88 offset:49152
	ds_read_b128 v[186:189], v88 offset:53248
	s_waitcnt lgkmcnt(6)
	v_mfma_f32_32x32x16_bf16 v[50:65], v[190:193], v[194:197], v[50:65]
	s_waitcnt lgkmcnt(4)
	v_mfma_f32_32x32x16_bf16 v[34:49], v[190:193], v[202:205], v[34:49]
	v_mfma_f32_32x32x16_bf16 v[18:33], v[198:201], v[194:197], v[18:33]
	v_mfma_f32_32x32x16_bf16 v[2:17], v[198:201], v[202:205], v[2:17]
	ds_read_b128 v[190:193], v87 offset:16384
	ds_read_b128 v[194:197], v87 offset:20480
	ds_read_b128 v[198:201], v86 offset:49152
	ds_read_b128 v[202:205], v86 offset:53248
	v_lshl_add_u64 v[66:67], v[66:67], 0, s[98:99]
	v_lshl_add_u64 v[70:71], v[70:71], 0, s[98:99]
	v_lshl_add_u64 v[74:75], v[74:75], 0, s[98:99]
	v_lshl_add_u64 v[78:79], v[78:79], 0, s[98:99]
	v_lshl_add_u64 v[68:69], v[68:69], 0, s[98:99]
	v_lshl_add_u64 v[72:73], v[72:73], 0, s[98:99]
	v_lshl_add_u64 v[76:77], v[76:77], 0, s[98:99]
	v_lshl_add_u64 v[80:81], v[80:81], 0, s[98:99]
	s_waitcnt lgkmcnt(0)
	s_barrier
	s_add_u32 m0, s32, 0x4000
	v_mfma_f32_32x32x16_bf16 v[50:65], v[162:165], v[182:185], v[50:65]
	global_load_lds_dwordx4 v[66:67], off
	s_add_u32 m0, s32, 0x5000
	v_mfma_f32_32x32x16_bf16 v[34:49], v[162:165], v[186:189], v[34:49]
	global_load_lds_dwordx4 v[70:71], off
	s_add_u32 m0, s32, 0x6000
	v_mfma_f32_32x32x16_bf16 v[18:33], v[166:169], v[182:185], v[18:33]
	global_load_lds_dwordx4 v[74:75], off
	s_add_u32 m0, s32, 0x7000
	v_mfma_f32_32x32x16_bf16 v[2:17], v[166:169], v[186:189], v[2:17]
	global_load_lds_dwordx4 v[78:79], off
	s_add_u32 m0, s32, 0xc000
	v_mfma_f32_32x32x16_bf16 v[50:65], v[190:193], v[198:201], v[50:65]
	global_load_lds_dwordx4 v[68:69], off
	s_add_u32 m0, s32, 0xd000
	v_mfma_f32_32x32x16_bf16 v[34:49], v[190:193], v[202:205], v[34:49]
	global_load_lds_dwordx4 v[72:73], off
	s_add_u32 m0, s32, 0xe000
	v_mfma_f32_32x32x16_bf16 v[18:33], v[194:197], v[198:201], v[18:33]
	global_load_lds_dwordx4 v[76:77], off
	s_add_u32 m0, s32, 0xf000
	v_mfma_f32_32x32x16_bf16 v[2:17], v[194:197], v[202:205], v[2:17]
	global_load_lds_dwordx4 v[80:81], off
	s_waitcnt vmcnt(8)
	s_barrier
	ds_read_b128 v[162:165], v91
	ds_read_b128 v[166:169], v92 offset:32768
	ds_read_b128 v[182:185], v91 offset:4096
	ds_read_b128 v[186:189], v92 offset:36864
	ds_read_b128 v[190:193], v93
	ds_read_b128 v[194:197], v90 offset:32768
	ds_read_b128 v[198:201], v93 offset:4096
	ds_read_b128 v[202:205], v90 offset:36864
	s_waitcnt lgkmcnt(6)
	v_mfma_f32_32x32x16_bf16 v[50:65], v[162:165], v[166:169], v[50:65]
	s_waitcnt lgkmcnt(4)
	v_mfma_f32_32x32x16_bf16 v[34:49], v[162:165], v[186:189], v[34:49]
	v_mfma_f32_32x32x16_bf16 v[18:33], v[182:185], v[166:169], v[18:33]
	v_mfma_f32_32x32x16_bf16 v[2:17], v[182:185], v[186:189], v[2:17]
	ds_read_b128 v[162:165], v89
	ds_read_b128 v[166:169], v89 offset:4096
	ds_read_b128 v[182:185], v88 offset:32768
	ds_read_b128 v[186:189], v88 offset:36864
	s_waitcnt lgkmcnt(6)
	v_mfma_f32_32x32x16_bf16 v[50:65], v[190:193], v[194:197], v[50:65]
	s_waitcnt lgkmcnt(4)
	v_mfma_f32_32x32x16_bf16 v[34:49], v[190:193], v[202:205], v[34:49]
	v_mfma_f32_32x32x16_bf16 v[18:33], v[198:201], v[194:197], v[18:33]
	v_mfma_f32_32x32x16_bf16 v[2:17], v[198:201], v[202:205], v[2:17]
	ds_read_b128 v[190:193], v87
	ds_read_b128 v[194:197], v87 offset:4096
	ds_read_b128 v[198:201], v86 offset:32768
	ds_read_b128 v[202:205], v86 offset:36864
	v_lshl_add_u64 v[66:67], v[66:67], 0, s[98:99]
	v_lshl_add_u64 v[70:71], v[70:71], 0, s[98:99]
	v_lshl_add_u64 v[74:75], v[74:75], 0, s[98:99]
	v_lshl_add_u64 v[78:79], v[78:79], 0, s[98:99]
	v_lshl_add_u64 v[68:69], v[68:69], 0, s[98:99]
	v_lshl_add_u64 v[72:73], v[72:73], 0, s[98:99]
	v_lshl_add_u64 v[76:77], v[76:77], 0, s[98:99]
	v_lshl_add_u64 v[80:81], v[80:81], 0, s[98:99]
	s_waitcnt lgkmcnt(0)
	s_barrier
	s_add_u32 m0, s32, 0x0
	v_mfma_f32_32x32x16_bf16 v[50:65], v[162:165], v[182:185], v[50:65]
	global_load_lds_dwordx4 v[66:67], off
	s_add_u32 m0, s32, 0x1000
	v_mfma_f32_32x32x16_bf16 v[34:49], v[162:165], v[186:189], v[34:49]
	global_load_lds_dwordx4 v[70:71], off
	s_add_u32 m0, s32, 0x2000
	v_mfma_f32_32x32x16_bf16 v[18:33], v[166:169], v[182:185], v[18:33]
	global_load_lds_dwordx4 v[74:75], off
	s_add_u32 m0, s32, 0x3000
	v_mfma_f32_32x32x16_bf16 v[2:17], v[166:169], v[186:189], v[2:17]
	global_load_lds_dwordx4 v[78:79], off
	s_add_u32 m0, s32, 0x8000
	v_mfma_f32_32x32x16_bf16 v[50:65], v[190:193], v[198:201], v[50:65]
	global_load_lds_dwordx4 v[68:69], off
	s_add_u32 m0, s32, 0x9000
	v_mfma_f32_32x32x16_bf16 v[34:49], v[190:193], v[202:205], v[34:49]
	global_load_lds_dwordx4 v[72:73], off
	s_add_u32 m0, s32, 0xa000
	v_mfma_f32_32x32x16_bf16 v[18:33], v[194:197], v[198:201], v[18:33]
	global_load_lds_dwordx4 v[76:77], off
	s_add_u32 m0, s32, 0xb000
	v_mfma_f32_32x32x16_bf16 v[2:17], v[194:197], v[202:205], v[2:17]
	global_load_lds_dwordx4 v[80:81], off
	s_waitcnt vmcnt(8)
	s_barrier
	ds_read_b128 v[162:165], v91 offset:16384
	ds_read_b128 v[166:169], v92 offset:49152
	ds_read_b128 v[182:185], v91 offset:20480
	ds_read_b128 v[186:189], v92 offset:53248
	ds_read_b128 v[190:193], v93 offset:16384
	ds_read_b128 v[194:197], v90 offset:49152
	ds_read_b128 v[198:201], v93 offset:20480
	ds_read_b128 v[202:205], v90 offset:53248
	s_waitcnt lgkmcnt(6)
	v_mfma_f32_32x32x16_bf16 v[50:65], v[162:165], v[166:169], v[50:65]
	s_waitcnt lgkmcnt(4)
	v_mfma_f32_32x32x16_bf16 v[34:49], v[162:165], v[186:189], v[34:49]
	v_mfma_f32_32x32x16_bf16 v[18:33], v[182:185], v[166:169], v[18:33]
	v_mfma_f32_32x32x16_bf16 v[2:17], v[182:185], v[186:189], v[2:17]
	ds_read_b128 v[162:165], v89 offset:16384
	ds_read_b128 v[166:169], v89 offset:20480
	ds_read_b128 v[182:185], v88 offset:49152
	ds_read_b128 v[186:189], v88 offset:53248
	s_waitcnt lgkmcnt(6)
	v_mfma_f32_32x32x16_bf16 v[50:65], v[190:193], v[194:197], v[50:65]
	s_waitcnt lgkmcnt(4)
	v_mfma_f32_32x32x16_bf16 v[34:49], v[190:193], v[202:205], v[34:49]
	v_mfma_f32_32x32x16_bf16 v[18:33], v[198:201], v[194:197], v[18:33]
	v_mfma_f32_32x32x16_bf16 v[2:17], v[198:201], v[202:205], v[2:17]
	ds_read_b128 v[190:193], v87 offset:16384
	ds_read_b128 v[194:197], v87 offset:20480
	ds_read_b128 v[198:201], v86 offset:49152
	ds_read_b128 v[202:205], v86 offset:53248
	v_lshl_add_u64 v[66:67], v[66:67], 0, s[98:99]
	v_lshl_add_u64 v[70:71], v[70:71], 0, s[98:99]
	v_lshl_add_u64 v[74:75], v[74:75], 0, s[98:99]
	v_lshl_add_u64 v[78:79], v[78:79], 0, s[98:99]
	v_lshl_add_u64 v[68:69], v[68:69], 0, s[98:99]
	v_lshl_add_u64 v[72:73], v[72:73], 0, s[98:99]
	v_lshl_add_u64 v[76:77], v[76:77], 0, s[98:99]
	v_lshl_add_u64 v[80:81], v[80:81], 0, s[98:99]
	s_waitcnt lgkmcnt(0)
	s_barrier
	s_add_u32 m0, s32, 0x4000
	v_mfma_f32_32x32x16_bf16 v[50:65], v[162:165], v[182:185], v[50:65]
	global_load_lds_dwordx4 v[66:67], off
	s_add_u32 m0, s32, 0x5000
	v_mfma_f32_32x32x16_bf16 v[34:49], v[162:165], v[186:189], v[34:49]
	global_load_lds_dwordx4 v[70:71], off
	s_add_u32 m0, s32, 0x6000
	v_mfma_f32_32x32x16_bf16 v[18:33], v[166:169], v[182:185], v[18:33]
	global_load_lds_dwordx4 v[74:75], off
	s_add_u32 m0, s32, 0x7000
	v_mfma_f32_32x32x16_bf16 v[2:17], v[166:169], v[186:189], v[2:17]
	global_load_lds_dwordx4 v[78:79], off
	s_add_u32 m0, s32, 0xc000
	v_mfma_f32_32x32x16_bf16 v[50:65], v[190:193], v[198:201], v[50:65]
	global_load_lds_dwordx4 v[68:69], off
	s_add_u32 m0, s32, 0xd000
	v_mfma_f32_32x32x16_bf16 v[34:49], v[190:193], v[202:205], v[34:49]
	global_load_lds_dwordx4 v[72:73], off
	s_add_u32 m0, s32, 0xe000
	v_mfma_f32_32x32x16_bf16 v[18:33], v[194:197], v[198:201], v[18:33]
	global_load_lds_dwordx4 v[76:77], off
	s_add_u32 m0, s32, 0xf000
	v_mfma_f32_32x32x16_bf16 v[2:17], v[194:197], v[202:205], v[2:17]
	global_load_lds_dwordx4 v[80:81], off
	s_waitcnt vmcnt(8)
	s_barrier
	ds_read_b128 v[162:165], v91
	ds_read_b128 v[166:169], v92 offset:32768
	ds_read_b128 v[182:185], v91 offset:4096
	ds_read_b128 v[186:189], v92 offset:36864
	ds_read_b128 v[190:193], v93
	ds_read_b128 v[194:197], v90 offset:32768
	ds_read_b128 v[198:201], v93 offset:4096
	ds_read_b128 v[202:205], v90 offset:36864
	s_waitcnt lgkmcnt(6)
	v_mfma_f32_32x32x16_bf16 v[50:65], v[162:165], v[166:169], v[50:65]
	s_waitcnt lgkmcnt(4)
	v_mfma_f32_32x32x16_bf16 v[34:49], v[162:165], v[186:189], v[34:49]
	v_mfma_f32_32x32x16_bf16 v[18:33], v[182:185], v[166:169], v[18:33]
	v_mfma_f32_32x32x16_bf16 v[2:17], v[182:185], v[186:189], v[2:17]
	ds_read_b128 v[162:165], v89
	ds_read_b128 v[166:169], v89 offset:4096
	ds_read_b128 v[182:185], v88 offset:32768
	ds_read_b128 v[186:189], v88 offset:36864
	s_waitcnt lgkmcnt(6)
	v_mfma_f32_32x32x16_bf16 v[50:65], v[190:193], v[194:197], v[50:65]
	s_waitcnt lgkmcnt(4)
	v_mfma_f32_32x32x16_bf16 v[34:49], v[190:193], v[202:205], v[34:49]
	v_mfma_f32_32x32x16_bf16 v[18:33], v[198:201], v[194:197], v[18:33]
	v_mfma_f32_32x32x16_bf16 v[2:17], v[198:201], v[202:205], v[2:17]
	ds_read_b128 v[190:193], v87
	ds_read_b128 v[194:197], v87 offset:4096
	ds_read_b128 v[198:201], v86 offset:32768
	ds_read_b128 v[202:205], v86 offset:36864
	v_lshl_add_u64 v[66:67], v[66:67], 0, s[98:99]
	v_lshl_add_u64 v[70:71], v[70:71], 0, s[98:99]
	v_lshl_add_u64 v[74:75], v[74:75], 0, s[98:99]
	v_lshl_add_u64 v[78:79], v[78:79], 0, s[98:99]
	v_lshl_add_u64 v[68:69], v[68:69], 0, s[98:99]
	v_lshl_add_u64 v[72:73], v[72:73], 0, s[98:99]
	v_lshl_add_u64 v[76:77], v[76:77], 0, s[98:99]
	v_lshl_add_u64 v[80:81], v[80:81], 0, s[98:99]
	s_waitcnt lgkmcnt(0)
	s_barrier
	s_add_u32 m0, s32, 0x0
	s_nop 0
	global_load_lds_dwordx4 v[66:67], off
	s_add_u32 m0, s32, 0x1000
	s_nop 0
	global_load_lds_dwordx4 v[70:71], off
	s_add_u32 m0, s32, 0x2000
	s_nop 0
	global_load_lds_dwordx4 v[74:75], off
	s_add_u32 m0, s32, 0x3000
	s_nop 0
	global_load_lds_dwordx4 v[78:79], off
	s_add_u32 m0, s32, 0x8000
	s_nop 0
	global_load_lds_dwordx4 v[68:69], off
	s_add_u32 m0, s32, 0x9000
	s_nop 0
	global_load_lds_dwordx4 v[72:73], off
	s_add_u32 m0, s32, 0xa000
	s_nop 0
	global_load_lds_dwordx4 v[76:77], off
	s_add_u32 m0, s32, 0xb000
	s_nop 0
	global_load_lds_dwordx4 v[80:81], off
	s_waitcnt vmcnt(8)
	s_barrier
	s_nop 0
	s_nop 0
	s_nop 0
	s_nop 0
	s_nop 0
	s_nop 0
	s_nop 0
	v_mfma_f32_32x32x16_bf16 v[50:65], v[162:165], v[182:185], v[50:65]
	v_mfma_f32_32x32x16_bf16 v[34:49], v[162:165], v[186:189], v[34:49]
	v_mfma_f32_32x32x16_bf16 v[18:33], v[166:169], v[182:185], v[18:33]
	v_mfma_f32_32x32x16_bf16 v[2:17], v[166:169], v[186:189], v[2:17]
	ds_read_b128 v[110:113], v91 offset:16384
	ds_read_b128 v[114:117], v91 offset:20480
	ds_read_b128 v[118:121], v92 offset:49152
	ds_read_b128 v[122:125], v92 offset:53248
	ds_read_b128 v[162:165], v93 offset:16384
	ds_read_b128 v[166:169], v93 offset:20480
	ds_read_b128 v[182:185], v90 offset:49152
	ds_read_b128 v[186:189], v90 offset:53248
	v_mfma_f32_32x32x16_bf16 v[50:65], v[190:193], v[198:201], v[50:65]
	v_mfma_f32_32x32x16_bf16 v[34:49], v[190:193], v[202:205], v[34:49]
	v_mfma_f32_32x32x16_bf16 v[18:33], v[194:197], v[198:201], v[18:33]
	v_mfma_f32_32x32x16_bf16 v[2:17], v[194:197], v[202:205], v[2:17]
	s_waitcnt lgkmcnt(5)
	v_mfma_f32_32x32x16_bf16 v[50:65], v[110:113], v[118:121], v[50:65]
	s_waitcnt lgkmcnt(4)
	v_mfma_f32_32x32x16_bf16 v[34:49], v[110:113], v[122:125], v[34:49]
	v_mfma_f32_32x32x16_bf16 v[18:33], v[114:117], v[118:121], v[18:33]
	v_mfma_f32_32x32x16_bf16 v[2:17], v[114:117], v[122:125], v[2:17]
	ds_read_b128 v[110:113], v89 offset:16384
	ds_read_b128 v[114:117], v89 offset:20480
	ds_read_b128 v[118:121], v88 offset:49152
	ds_read_b128 v[122:125], v88 offset:53248
	s_waitcnt lgkmcnt(5)
	v_mfma_f32_32x32x16_bf16 v[50:65], v[162:165], v[182:185], v[50:65]
	s_waitcnt lgkmcnt(4)
	v_mfma_f32_32x32x16_bf16 v[34:49], v[162:165], v[186:189], v[34:49]
	v_mfma_f32_32x32x16_bf16 v[18:33], v[166:169], v[182:185], v[18:33]
	v_mfma_f32_32x32x16_bf16 v[2:17], v[166:169], v[186:189], v[2:17]
	ds_read_b128 v[162:165], v87 offset:16384
	ds_read_b128 v[166:169], v87 offset:20480
	ds_read_b128 v[182:185], v86 offset:49152
	ds_read_b128 v[186:189], v86 offset:53248
	s_waitcnt lgkmcnt(5)
	v_mfma_f32_32x32x16_bf16 v[50:65], v[110:113], v[118:121], v[50:65]
	v_lshl_add_u64 v[66:67], v[66:67], 0, s[98:99]
	v_lshl_add_u64 v[70:71], v[70:71], 0, s[98:99]
	v_lshl_add_u64 v[74:75], v[74:75], 0, s[98:99]
	v_lshl_add_u64 v[78:79], v[78:79], 0, s[98:99]
	v_lshl_add_u64 v[68:69], v[68:69], 0, s[98:99]
	v_lshl_add_u64 v[72:73], v[72:73], 0, s[98:99]
	v_lshl_add_u64 v[76:77], v[76:77], 0, s[98:99]
	v_lshl_add_u64 v[80:81], v[80:81], 0, s[98:99]
	s_waitcnt lgkmcnt(0)
	s_barrier
	s_add_u32 m0, s32, 0x4000
	s_nop 0
	global_load_lds_dwordx4 v[66:67], off
	s_add_u32 m0, s32, 0x5000
	s_nop 0
	global_load_lds_dwordx4 v[70:71], off
	s_add_u32 m0, s32, 0x6000
	s_nop 0
	global_load_lds_dwordx4 v[74:75], off
	s_add_u32 m0, s32, 0x7000
	s_nop 0
	global_load_lds_dwordx4 v[78:79], off
	s_add_u32 m0, s32, 0xc000
	s_nop 0
	global_load_lds_dwordx4 v[68:69], off
	s_add_u32 m0, s32, 0xd000
	s_nop 0
	global_load_lds_dwordx4 v[72:73], off
	s_add_u32 m0, s32, 0xe000
	s_nop 0
	global_load_lds_dwordx4 v[76:77], off
	s_add_u32 m0, s32, 0xf000
	s_nop 0
	global_load_lds_dwordx4 v[80:81], off
	s_waitcnt vmcnt(8)
	s_barrier
	v_mfma_f32_32x32x16_bf16 v[34:49], v[110:113], v[122:125], v[34:49]
	v_mfma_f32_32x32x16_bf16 v[18:33], v[114:117], v[118:121], v[18:33]
	v_mfma_f32_32x32x16_bf16 v[2:17], v[114:117], v[122:125], v[2:17]
	ds_read_b128 v[110:113], v91
	ds_read_b128 v[114:117], v91 offset:4096
	ds_read_b128 v[118:121], v92 offset:32768
	ds_read_b128 v[122:125], v92 offset:36864
	ds_read_b128 v[126:129], v93
	ds_read_b128 v[134:137], v93 offset:4096
	ds_read_b128 v[138:141], v90 offset:32768
	ds_read_b128 v[142:145], v90 offset:36864
	v_mfma_f32_32x32x16_bf16 v[50:65], v[162:165], v[182:185], v[50:65]
	v_mfma_f32_32x32x16_bf16 v[34:49], v[162:165], v[186:189], v[34:49]
	v_mfma_f32_32x32x16_bf16 v[18:33], v[166:169], v[182:185], v[18:33]
	v_mfma_f32_32x32x16_bf16 v[2:17], v[166:169], v[186:189], v[2:17]
	s_waitcnt lgkmcnt(5)
	v_mfma_f32_32x32x16_bf16 v[50:65], v[110:113], v[118:121], v[50:65]
	s_waitcnt lgkmcnt(4)
	v_mfma_f32_32x32x16_bf16 v[34:49], v[110:113], v[122:125], v[34:49]
	v_mfma_f32_32x32x16_bf16 v[18:33], v[114:117], v[118:121], v[18:33]
	v_mfma_f32_32x32x16_bf16 v[2:17], v[114:117], v[122:125], v[2:17]
	ds_read_b128 v[110:113], v89
	ds_read_b128 v[114:117], v89 offset:4096
	ds_read_b128 v[118:121], v88 offset:32768
	ds_read_b128 v[122:125], v88 offset:36864
	s_waitcnt lgkmcnt(5)
	v_mfma_f32_32x32x16_bf16 v[50:65], v[126:129], v[138:141], v[50:65]
	s_waitcnt lgkmcnt(4)
	v_mfma_f32_32x32x16_bf16 v[34:49], v[126:129], v[142:145], v[34:49]
	v_mfma_f32_32x32x16_bf16 v[18:33], v[134:137], v[138:141], v[18:33]
	v_mfma_f32_32x32x16_bf16 v[2:17], v[134:137], v[142:145], v[2:17]
	ds_read_b128 v[126:129], v87
	ds_read_b128 v[134:137], v87 offset:4096
	ds_read_b128 v[138:141], v86 offset:32768
	ds_read_b128 v[142:145], v86 offset:36864
	s_waitcnt vmcnt(0)
	s_waitcnt lgkmcnt(0)
	s_barrier
	ds_read_b128 v[66:69], v91 offset:16384
	ds_read_b128 v[70:73], v91 offset:20480
	ds_read_b128 v[74:77], v92 offset:49152
	ds_read_b128 v[78:81], v92 offset:53248
	ds_read_b128 v[94:97], v93 offset:16384
	ds_read_b128 v[98:101], v93 offset:20480
	ds_read_b128 v[102:105], v90 offset:49152
	ds_read_b128 v[90:93], v90 offset:53248
	v_mfma_f32_32x32x16_bf16 v[50:65], v[110:113], v[118:121], v[50:65]
	v_mfma_f32_32x32x16_bf16 v[34:49], v[110:113], v[122:125], v[34:49]
	v_mfma_f32_32x32x16_bf16 v[18:33], v[114:117], v[118:121], v[18:33]
	v_mfma_f32_32x32x16_bf16 v[2:17], v[114:117], v[122:125], v[2:17]
	v_mfma_f32_32x32x16_bf16 v[50:65], v[126:129], v[138:141], v[50:65]
	v_mfma_f32_32x32x16_bf16 v[34:49], v[126:129], v[142:145], v[34:49]
	v_mfma_f32_32x32x16_bf16 v[18:33], v[134:137], v[138:141], v[18:33]
	v_mfma_f32_32x32x16_bf16 v[2:17], v[134:137], v[142:145], v[2:17]
	s_waitcnt lgkmcnt(5)
	v_mfma_f32_32x32x16_bf16 v[50:65], v[66:69], v[74:77], v[50:65]
	s_waitcnt lgkmcnt(4)
	v_mfma_f32_32x32x16_bf16 v[34:49], v[66:69], v[78:81], v[34:49]
	v_mfma_f32_32x32x16_bf16 v[18:33], v[70:73], v[74:77], v[18:33]
	v_mfma_f32_32x32x16_bf16 v[2:17], v[70:73], v[78:81], v[2:17]
	ds_read_b128 v[66:69], v89 offset:16384
	ds_read_b128 v[70:73], v89 offset:20480
	ds_read_b128 v[74:77], v88 offset:49152
	ds_read_b128 v[78:81], v88 offset:53248
	s_waitcnt lgkmcnt(5)
	v_mfma_f32_32x32x16_bf16 v[50:65], v[94:97], v[102:105], v[50:65]
	s_waitcnt lgkmcnt(4)
	v_mfma_f32_32x32x16_bf16 v[34:49], v[94:97], v[90:93], v[34:49]
	v_mfma_f32_32x32x16_bf16 v[18:33], v[98:101], v[102:105], v[18:33]
	v_mfma_f32_32x32x16_bf16 v[2:17], v[98:101], v[90:93], v[2:17]
	ds_read_b128 v[88:91], v87 offset:16384
	ds_read_b128 v[92:95], v87 offset:20480
	ds_read_b128 v[96:99], v86 offset:49152
	ds_read_b128 v[100:103], v86 offset:53248
	s_waitcnt lgkmcnt(5)
	v_mfma_f32_32x32x16_bf16 v[50:65], v[66:69], v[74:77], v[50:65]
	v_lshlrev_b32_e32 v0, 6, v85
	v_lshlrev_b32_e32 v84, 6, v84
	v_subrev_u32_e32 v0, s6, v0
	v_add_u32_e32 v0, s4, v0
	v_ashrrev_i32_e32 v0, 6, v0
	v_lshlrev_b32_e32 v85, 2, v83
	s_waitcnt lgkmcnt(0)
	v_mfma_f32_32x32x16_bf16 v[50:65], v[88:91], v[96:99], v[50:65]
	s_barrier
	v_or_b32_e32 v83, 2, v84
	v_or_b32_e32 v86, 3, v84
	v_or_b32_e32 v87, 8, v85
	s_add_i32 s5, s5, s66
	s_add_i32 s4, s4, s3
	v_mfma_f32_32x32x16_bf16 v[34:49], v[66:69], v[78:81], v[34:49]
	v_lshl_add_u32 v66, s34, 7, v84
	v_ashrrev_i32_e32 v66, 1, v66
	v_and_b32_e32 v66, 0xffffffc0, v66
	v_add_u32_e32 v66, v66, v0
	v_ashrrev_i32_e32 v67, 31, v66
	v_lshlrev_b64 v[66:67], 14, v[66:67]
	v_lshl_add_u64 v[66:67], s[50:51], 0, v[66:67]
	v_lshlrev_b32_e32 v0, 1, v82
	v_lshl_add_u64 v[66:67], v[66:67], 0, v[0:1]
	v_max_f32_e32 v0, v50, v50
	v_max_f32_e32 v0, 0, v0
	v_or_b32_e32 v68, v85, v84
	v_mul_f32_e32 v0, v0, v0
	v_cvt_pk_bf16_f32 v50, v0, s0
	v_lshlrev_b32_e32 v0, 7, v68
	v_and_b32_e32 v0, 0x2200, v0
	v_lshl_add_u64 v[68:69], v[66:67], 0, v[0:1]
	v_or_b32_e32 v82, 1, v84
	global_store_short v[68:69], v50, off
	v_or_b32_e32 v0, v85, v82
	v_max_f32_e32 v50, v51, v51
	v_max_f32_e32 v50, 0, v50
	v_lshlrev_b32_e32 v0, 7, v0
	v_mul_f32_e32 v50, v50, v50
	v_and_b32_e32 v0, 0x2280, v0
	v_mfma_f32_32x32x16_bf16 v[18:33], v[70:73], v[74:77], v[18:33]
	v_max_f32_e32 v52, v52, v52
	v_max_f32_e32 v52, 0, v52
	v_mul_f32_e32 v52, v52, v52
	v_cvt_pk_bf16_f32 v52, v52, s0
	v_max_f32_e32 v54, v54, v54
	v_max_f32_e32 v54, 0, v54
	v_mul_f32_e32 v54, v54, v54
	v_mfma_f32_32x32x16_bf16 v[2:17], v[70:73], v[78:81], v[2:17]
	v_cvt_pk_bf16_f32 v70, v50, s0
	v_lshl_add_u64 v[50:51], v[66:67], 0, v[0:1]
	v_or_b32_e32 v0, v85, v83
	v_lshlrev_b32_e32 v0, 7, v0
	v_and_b32_e32 v0, 0x2300, v0
	global_store_short v[50:51], v70, off
	v_lshl_add_u64 v[70:71], v[66:67], 0, v[0:1]
	global_store_short v[70:71], v52, off
	v_or_b32_e32 v0, v85, v86
	v_max_f32_e32 v52, v53, v53
	v_max_f32_e32 v52, 0, v52
	v_lshlrev_b32_e32 v0, 7, v0
	v_mul_f32_e32 v52, v52, v52
	v_and_b32_e32 v0, 0x2380, v0
	v_cvt_pk_bf16_f32 v72, v52, s0
	v_lshl_add_u64 v[52:53], v[66:67], 0, v[0:1]
	v_or_b32_e32 v0, v87, v84
	v_lshlrev_b32_e32 v0, 7, v0
	v_and_b32_e32 v0, 0x2600, v0
	global_store_short v[52:53], v72, off
	v_cvt_pk_bf16_f32 v54, v54, s0
	v_lshl_add_u64 v[72:73], v[66:67], 0, v[0:1]
	global_store_short v[72:73], v54, off
	v_or_b32_e32 v0, v87, v82
	v_max_f32_e32 v54, v55, v55
	v_max_f32_e32 v54, 0, v54
	v_lshlrev_b32_e32 v0, 7, v0
	v_mul_f32_e32 v54, v54, v54
	v_and_b32_e32 v0, 0x2680, v0
	v_cvt_pk_bf16_f32 v74, v54, s0
	v_lshl_add_u64 v[54:55], v[66:67], 0, v[0:1]
	v_or_b32_e32 v0, v87, v83
	v_max_f32_e32 v56, v56, v56
	v_max_f32_e32 v56, 0, v56
	v_lshlrev_b32_e32 v0, 7, v0
	v_mul_f32_e32 v56, v56, v56
	v_and_b32_e32 v0, 0x2700, v0
	global_store_short v[54:55], v74, off
	v_cvt_pk_bf16_f32 v56, v56, s0
	v_lshl_add_u64 v[74:75], v[66:67], 0, v[0:1]
	global_store_short v[74:75], v56, off
	v_or_b32_e32 v0, v87, v86
	v_max_f32_e32 v56, v57, v57
	v_max_f32_e32 v56, 0, v56
	v_lshlrev_b32_e32 v0, 7, v0
	v_mfma_f32_32x32x16_bf16 v[34:49], v[88:91], v[100:103], v[34:49]
	v_mul_f32_e32 v56, v56, v56
	v_and_b32_e32 v0, 0x2780, v0
	v_or_b32_e32 v88, 16, v85
	v_cvt_pk_bf16_f32 v76, v56, s0
	v_lshl_add_u64 v[56:57], v[66:67], 0, v[0:1]
	v_or_b32_e32 v0, v88, v84
	v_max_f32_e32 v58, v58, v58
	v_max_f32_e32 v58, 0, v58
	v_lshlrev_b32_e32 v0, 7, v0
	v_mul_f32_e32 v58, v58, v58
	v_and_b32_e32 v0, 0x2a00, v0
	global_store_short v[56:57], v76, off
	v_cvt_pk_bf16_f32 v58, v58, s0
	v_lshl_add_u64 v[76:77], v[66:67], 0, v[0:1]
	global_store_short v[76:77], v58, off
	v_or_b32_e32 v0, v88, v82
	v_max_f32_e32 v58, v59, v59
	v_max_f32_e32 v58, 0, v58
	v_lshlrev_b32_e32 v0, 7, v0
	v_mul_f32_e32 v58, v58, v58
	v_and_b32_e32 v0, 0x2a80, v0
	v_cvt_pk_bf16_f32 v78, v58, s0
	v_lshl_add_u64 v[58:59], v[66:67], 0, v[0:1]
	v_or_b32_e32 v0, v88, v83
	v_max_f32_e32 v60, v60, v60
	v_max_f32_e32 v60, 0, v60
	v_lshlrev_b32_e32 v0, 7, v0
	v_mul_f32_e32 v60, v60, v60
	v_and_b32_e32 v0, 0x2b00, v0
	global_store_short v[58:59], v78, off
	v_cvt_pk_bf16_f32 v60, v60, s0
	v_lshl_add_u64 v[78:79], v[66:67], 0, v[0:1]
	global_store_short v[78:79], v60, off
	v_or_b32_e32 v0, v88, v86
	v_max_f32_e32 v60, v61, v61
	v_max_f32_e32 v60, 0, v60
	v_lshlrev_b32_e32 v0, 7, v0
	v_mul_f32_e32 v60, v60, v60
	v_and_b32_e32 v0, 0x2b80, v0
	v_or_b32_e32 v89, 24, v85
	v_cvt_pk_bf16_f32 v80, v60, s0
	v_lshl_add_u64 v[60:61], v[66:67], 0, v[0:1]
	v_or_b32_e32 v0, v89, v84
	v_max_f32_e32 v62, v62, v62
	v_max_f32_e32 v62, 0, v62
	v_lshlrev_b32_e32 v0, 7, v0
	v_mul_f32_e32 v62, v62, v62
	v_and_b32_e32 v0, 0x2e00, v0
	global_store_short v[60:61], v80, off
	v_cvt_pk_bf16_f32 v62, v62, s0
	v_lshl_add_u64 v[80:81], v[66:67], 0, v[0:1]
	global_store_short v[80:81], v62, off
	v_or_b32_e32 v0, v89, v82
	v_max_f32_e32 v62, v63, v63
	v_max_f32_e32 v62, 0, v62
	v_lshlrev_b32_e32 v0, 7, v0
	v_mul_f32_e32 v62, v62, v62
	v_and_b32_e32 v0, 0x2e80, v0
	v_cvt_pk_bf16_f32 v82, v62, s0
	v_lshl_add_u64 v[62:63], v[66:67], 0, v[0:1]
	v_or_b32_e32 v0, v89, v83
	v_max_f32_e32 v64, v64, v64
	v_max_f32_e32 v64, 0, v64
	v_lshlrev_b32_e32 v0, 7, v0
	v_mul_f32_e32 v64, v64, v64
	v_and_b32_e32 v0, 0x2f00, v0
	global_store_short v[62:63], v82, off
	v_cvt_pk_bf16_f32 v64, v64, s0
	v_lshl_add_u64 v[82:83], v[66:67], 0, v[0:1]
	global_store_short v[82:83], v64, off
	v_or_b32_e32 v0, v89, v86
	v_max_f32_e32 v64, v65, v65
	v_max_f32_e32 v64, 0, v64
	v_lshlrev_b32_e32 v0, 7, v0
	v_mul_f32_e32 v64, v64, v64
	v_and_b32_e32 v0, 0x2f80, v0
	v_cvt_pk_bf16_f32 v86, v64, s0
	v_lshl_add_u64 v[64:65], v[66:67], 0, v[0:1]
	v_max_f32_e32 v0, v34, v34
	v_max_f32_e32 v0, 0, v0
	v_mul_f32_e32 v0, v0, v0
	v_cvt_pk_bf16_f32 v0, v0, s0
	global_store_short v[64:65], v86, off
	global_store_short v[68:69], v0, off offset:64
	v_max_f32_e32 v0, v35, v35
	v_max_f32_e32 v0, 0, v0
	v_mul_f32_e32 v0, v0, v0
	v_cvt_pk_bf16_f32 v0, v0, s0
	global_store_short v[50:51], v0, off offset:64
	v_max_f32_e32 v0, v36, v36
	v_max_f32_e32 v0, 0, v0
	v_mul_f32_e32 v0, v0, v0
	v_cvt_pk_bf16_f32 v0, v0, s0
	global_store_short v[70:71], v0, off offset:64
	v_max_f32_e32 v0, v37, v37
	v_max_f32_e32 v0, 0, v0
	v_mul_f32_e32 v0, v0, v0
	v_cvt_pk_bf16_f32 v0, v0, s0
	global_store_short v[52:53], v0, off offset:64
	v_max_f32_e32 v0, v38, v38
	v_max_f32_e32 v0, 0, v0
	v_mul_f32_e32 v0, v0, v0
	v_cvt_pk_bf16_f32 v0, v0, s0
	global_store_short v[72:73], v0, off offset:64
	v_max_f32_e32 v0, v39, v39
	v_max_f32_e32 v0, 0, v0
	v_mul_f32_e32 v0, v0, v0
	v_cvt_pk_bf16_f32 v0, v0, s0
	global_store_short v[54:55], v0, off offset:64
	v_max_f32_e32 v0, v40, v40
	v_max_f32_e32 v0, 0, v0
	v_mul_f32_e32 v0, v0, v0
	v_cvt_pk_bf16_f32 v0, v0, s0
	global_store_short v[74:75], v0, off offset:64
	v_max_f32_e32 v0, v41, v41
	v_max_f32_e32 v0, 0, v0
	v_mul_f32_e32 v0, v0, v0
	v_cvt_pk_bf16_f32 v0, v0, s0
	global_store_short v[56:57], v0, off offset:64
	v_max_f32_e32 v0, v42, v42
	v_max_f32_e32 v0, 0, v0
	v_mul_f32_e32 v0, v0, v0
	v_cvt_pk_bf16_f32 v0, v0, s0
	global_store_short v[76:77], v0, off offset:64
	v_max_f32_e32 v0, v43, v43
	v_max_f32_e32 v0, 0, v0
	v_mul_f32_e32 v0, v0, v0
	v_cvt_pk_bf16_f32 v0, v0, s0
	global_store_short v[58:59], v0, off offset:64
	v_max_f32_e32 v0, v44, v44
	v_max_f32_e32 v0, 0, v0
	v_mul_f32_e32 v0, v0, v0
	v_cvt_pk_bf16_f32 v0, v0, s0
	global_store_short v[78:79], v0, off offset:64
	v_max_f32_e32 v0, v45, v45
	v_max_f32_e32 v0, 0, v0
	v_mul_f32_e32 v0, v0, v0
	v_cvt_pk_bf16_f32 v0, v0, s0
	global_store_short v[60:61], v0, off offset:64
	v_max_f32_e32 v0, v46, v46
	v_max_f32_e32 v0, 0, v0
	v_mul_f32_e32 v0, v0, v0
	v_cvt_pk_bf16_f32 v0, v0, s0
	global_store_short v[80:81], v0, off offset:64
	v_max_f32_e32 v0, v47, v47
	v_max_f32_e32 v0, 0, v0
	v_mul_f32_e32 v0, v0, v0
	v_cvt_pk_bf16_f32 v0, v0, s0
	v_mfma_f32_32x32x16_bf16 v[18:33], v[92:95], v[96:99], v[18:33]
	global_store_short v[62:63], v0, off offset:64
	v_max_f32_e32 v0, v48, v48
	v_max_f32_e32 v0, 0, v0
	v_mul_f32_e32 v0, v0, v0
	v_cvt_pk_bf16_f32 v0, v0, s0
	global_store_short v[82:83], v0, off offset:64
	v_max_f32_e32 v0, v49, v49
	v_max_f32_e32 v0, 0, v0
	v_mul_f32_e32 v0, v0, v0
	v_cvt_pk_bf16_f32 v0, v0, s0
	v_or_b32_e32 v46, 32, v84
	global_store_short v[64:65], v0, off offset:64
	v_or_b32_e32 v0, v85, v46
	v_max_f32_e32 v18, v18, v18
	v_max_f32_e32 v18, 0, v18
	v_lshlrev_b32_e32 v0, 7, v0
	v_mul_f32_e32 v18, v18, v18
	v_and_b32_e32 v0, 0x3200, v0
	v_cvt_pk_bf16_f32 v18, v18, s0
	v_lshl_add_u64 v[34:35], v[66:67], 0, v[0:1]
	v_or_b32_e32 v48, 33, v84
	global_store_short v[34:35], v18, off
	v_or_b32_e32 v0, v85, v48
	v_max_f32_e32 v18, v19, v19
	v_max_f32_e32 v18, 0, v18
	v_lshlrev_b32_e32 v0, 7, v0
	v_mul_f32_e32 v18, v18, v18
	v_and_b32_e32 v0, 0x3280, v0
	v_or_b32_e32 v49, 34, v84
	v_cvt_pk_bf16_f32 v36, v18, s0
	v_lshl_add_u64 v[18:19], v[66:67], 0, v[0:1]
	v_or_b32_e32 v0, v85, v49
	v_max_f32_e32 v20, v20, v20
	v_max_f32_e32 v20, 0, v20
	v_lshlrev_b32_e32 v0, 7, v0
	v_mul_f32_e32 v20, v20, v20
	v_and_b32_e32 v0, 0x3300, v0
	global_store_short v[18:19], v36, off
	v_cvt_pk_bf16_f32 v20, v20, s0
	v_lshl_add_u64 v[36:37], v[66:67], 0, v[0:1]
	v_or_b32_e32 v50, 35, v84
	global_store_short v[36:37], v20, off
	v_or_b32_e32 v0, v85, v50
	v_max_f32_e32 v20, v21, v21
	v_max_f32_e32 v20, 0, v20
	v_lshlrev_b32_e32 v0, 7, v0
	v_mul_f32_e32 v20, v20, v20
	v_and_b32_e32 v0, 0x3380, v0
	v_cvt_pk_bf16_f32 v38, v20, s0
	v_lshl_add_u64 v[20:21], v[66:67], 0, v[0:1]
	v_or_b32_e32 v0, v87, v46
	v_max_f32_e32 v22, v22, v22
	v_max_f32_e32 v22, 0, v22
	v_lshlrev_b32_e32 v0, 7, v0
	v_mul_f32_e32 v22, v22, v22
	v_and_b32_e32 v0, 0x3600, v0
	global_store_short v[20:21], v38, off
	v_cvt_pk_bf16_f32 v22, v22, s0
	v_lshl_add_u64 v[38:39], v[66:67], 0, v[0:1]
	global_store_short v[38:39], v22, off
	v_or_b32_e32 v0, v87, v48
	v_max_f32_e32 v22, v23, v23
	v_max_f32_e32 v22, 0, v22
	v_lshlrev_b32_e32 v0, 7, v0
	v_mul_f32_e32 v22, v22, v22
	v_and_b32_e32 v0, 0x3680, v0
	v_cvt_pk_bf16_f32 v40, v22, s0
	v_lshl_add_u64 v[22:23], v[66:67], 0, v[0:1]
	v_or_b32_e32 v0, v87, v49
	v_max_f32_e32 v24, v24, v24
	v_max_f32_e32 v24, 0, v24
	v_lshlrev_b32_e32 v0, 7, v0
	v_mul_f32_e32 v24, v24, v24
	v_and_b32_e32 v0, 0x3700, v0
	global_store_short v[22:23], v40, off
	v_cvt_pk_bf16_f32 v24, v24, s0
	v_lshl_add_u64 v[40:41], v[66:67], 0, v[0:1]
	global_store_short v[40:41], v24, off
	v_or_b32_e32 v0, v87, v50
	v_max_f32_e32 v24, v25, v25
	v_max_f32_e32 v24, 0, v24
	v_lshlrev_b32_e32 v0, 7, v0
	v_mul_f32_e32 v24, v24, v24
	v_and_b32_e32 v0, 0x3780, v0
	v_cvt_pk_bf16_f32 v42, v24, s0
	v_lshl_add_u64 v[24:25], v[66:67], 0, v[0:1]
	v_or_b32_e32 v0, v88, v46
	v_max_f32_e32 v26, v26, v26
	v_max_f32_e32 v26, 0, v26
	v_lshlrev_b32_e32 v0, 7, v0
	v_mul_f32_e32 v26, v26, v26
	v_and_b32_e32 v0, 0x3a00, v0
	global_store_short v[24:25], v42, off
	v_cvt_pk_bf16_f32 v26, v26, s0
	v_lshl_add_u64 v[42:43], v[66:67], 0, v[0:1]
	global_store_short v[42:43], v26, off
	v_or_b32_e32 v0, v88, v48
	v_max_f32_e32 v26, v27, v27
	v_max_f32_e32 v26, 0, v26
	v_lshlrev_b32_e32 v0, 7, v0
	v_mul_f32_e32 v26, v26, v26
	v_and_b32_e32 v0, 0x3a80, v0
	v_cvt_pk_bf16_f32 v44, v26, s0
	v_lshl_add_u64 v[26:27], v[66:67], 0, v[0:1]
	v_or_b32_e32 v0, v88, v49
	v_max_f32_e32 v28, v28, v28
	v_max_f32_e32 v28, 0, v28
	v_lshlrev_b32_e32 v0, 7, v0
	v_mul_f32_e32 v28, v28, v28
	v_and_b32_e32 v0, 0x3b00, v0
	global_store_short v[26:27], v44, off
	v_cvt_pk_bf16_f32 v28, v28, s0
	v_lshl_add_u64 v[44:45], v[66:67], 0, v[0:1]
	global_store_short v[44:45], v28, off
	v_or_b32_e32 v0, v88, v50
	v_max_f32_e32 v28, v29, v29
	v_max_f32_e32 v28, 0, v28
	v_lshlrev_b32_e32 v0, 7, v0
	v_mul_f32_e32 v28, v28, v28
	v_and_b32_e32 v0, 0x3b80, v0
	v_cvt_pk_bf16_f32 v47, v28, s0
	v_lshl_add_u64 v[28:29], v[66:67], 0, v[0:1]
	v_or_b32_e32 v0, v89, v46
	v_max_f32_e32 v30, v30, v30
	v_max_f32_e32 v30, 0, v30
	v_lshlrev_b32_e32 v0, 7, v0
	v_mul_f32_e32 v30, v30, v30
	v_and_b32_e32 v0, 0x3e00, v0
	global_store_short v[28:29], v47, off
	v_cvt_pk_bf16_f32 v30, v30, s0
	v_lshl_add_u64 v[46:47], v[66:67], 0, v[0:1]
	global_store_short v[46:47], v30, off
	v_or_b32_e32 v0, v89, v48
	v_max_f32_e32 v30, v31, v31
	v_max_f32_e32 v30, 0, v30
	v_lshlrev_b32_e32 v0, 7, v0
	v_mfma_f32_32x32x16_bf16 v[2:17], v[92:95], v[100:103], v[2:17]
	v_mul_f32_e32 v30, v30, v30
	v_and_b32_e32 v0, 0x3e80, v0
	v_cvt_pk_bf16_f32 v48, v30, s0
	v_lshl_add_u64 v[30:31], v[66:67], 0, v[0:1]
	v_or_b32_e32 v0, v89, v49
	v_max_f32_e32 v32, v32, v32
	v_max_f32_e32 v32, 0, v32
	v_lshlrev_b32_e32 v0, 7, v0
	v_mul_f32_e32 v32, v32, v32
	v_and_b32_e32 v0, 0x3f00, v0
	global_store_short v[30:31], v48, off
	v_cvt_pk_bf16_f32 v32, v32, s0
	v_lshl_add_u64 v[48:49], v[66:67], 0, v[0:1]
	global_store_short v[48:49], v32, off
	v_or_b32_e32 v0, v89, v50
	v_max_f32_e32 v32, v33, v33
	v_max_f32_e32 v32, 0, v32
	v_lshlrev_b32_e32 v0, 7, v0
	v_mul_f32_e32 v32, v32, v32
	v_and_b32_e32 v0, 0x3f80, v0
	v_cvt_pk_bf16_f32 v50, v32, s0
	v_lshl_add_u64 v[32:33], v[66:67], 0, v[0:1]
	v_max_f32_e32 v0, v2, v2
	v_max_f32_e32 v0, 0, v0
	v_mul_f32_e32 v0, v0, v0
	v_cvt_pk_bf16_f32 v0, v0, s0
	global_store_short v[32:33], v50, off
	global_store_short v[34:35], v0, off offset:64
	v_max_f32_e32 v0, v3, v3
	v_max_f32_e32 v0, 0, v0
	v_mul_f32_e32 v0, v0, v0
	v_cvt_pk_bf16_f32 v0, v0, s0
	global_store_short v[18:19], v0, off offset:64
	v_max_f32_e32 v0, v4, v4
	v_max_f32_e32 v0, 0, v0
	v_mul_f32_e32 v0, v0, v0
	v_cvt_pk_bf16_f32 v0, v0, s0
	global_store_short v[36:37], v0, off offset:64
	v_max_f32_e32 v0, v5, v5
	v_max_f32_e32 v0, 0, v0
	v_mul_f32_e32 v0, v0, v0
	v_cvt_pk_bf16_f32 v0, v0, s0
	global_store_short v[20:21], v0, off offset:64
	v_max_f32_e32 v0, v6, v6
	v_max_f32_e32 v0, 0, v0
	v_mul_f32_e32 v0, v0, v0
	v_cvt_pk_bf16_f32 v0, v0, s0
	global_store_short v[38:39], v0, off offset:64
	v_max_f32_e32 v0, v7, v7
	v_max_f32_e32 v0, 0, v0
	v_mul_f32_e32 v0, v0, v0
	v_cvt_pk_bf16_f32 v0, v0, s0
	global_store_short v[22:23], v0, off offset:64
	v_max_f32_e32 v0, v8, v8
	v_max_f32_e32 v0, 0, v0
	v_mul_f32_e32 v0, v0, v0
	v_cvt_pk_bf16_f32 v0, v0, s0
	global_store_short v[40:41], v0, off offset:64
	v_max_f32_e32 v0, v9, v9
	v_max_f32_e32 v0, 0, v0
	v_mul_f32_e32 v0, v0, v0
	v_cvt_pk_bf16_f32 v0, v0, s0
	global_store_short v[24:25], v0, off offset:64
	v_max_f32_e32 v0, v10, v10
	v_max_f32_e32 v0, 0, v0
	v_mul_f32_e32 v0, v0, v0
	v_cvt_pk_bf16_f32 v0, v0, s0
	global_store_short v[42:43], v0, off offset:64
	v_max_f32_e32 v0, v11, v11
	v_max_f32_e32 v0, 0, v0
	v_mul_f32_e32 v0, v0, v0
	v_cvt_pk_bf16_f32 v0, v0, s0
	global_store_short v[26:27], v0, off offset:64
	v_max_f32_e32 v0, v12, v12
	v_max_f32_e32 v0, 0, v0
	v_mul_f32_e32 v0, v0, v0
	v_cvt_pk_bf16_f32 v0, v0, s0
	global_store_short v[44:45], v0, off offset:64
	v_max_f32_e32 v0, v13, v13
	v_max_f32_e32 v0, 0, v0
	v_mul_f32_e32 v0, v0, v0
	v_cvt_pk_bf16_f32 v0, v0, s0
	global_store_short v[28:29], v0, off offset:64
	v_max_f32_e32 v0, v14, v14
	v_max_f32_e32 v0, 0, v0
	v_mul_f32_e32 v0, v0, v0
	v_cvt_pk_bf16_f32 v0, v0, s0
	global_store_short v[46:47], v0, off offset:64
	v_max_f32_e32 v0, v15, v15
	v_max_f32_e32 v0, 0, v0
	v_mul_f32_e32 v0, v0, v0
	v_cvt_pk_bf16_f32 v0, v0, s0
	global_store_short v[30:31], v0, off offset:64
	v_max_f32_e32 v0, v16, v16
	v_max_f32_e32 v0, 0, v0
	v_mul_f32_e32 v0, v0, v0
	v_cvt_pk_bf16_f32 v0, v0, s0
	global_store_short v[48:49], v0, off offset:64
	v_max_f32_e32 v0, v17, v17
	v_max_f32_e32 v0, 0, v0
	v_mul_f32_e32 v0, v0, v0
	v_cvt_pk_bf16_f32 v0, v0, s0
	s_cmp_lt_i32 s5, s2
	global_store_short v[32:33], v0, off offset:64
	s_cmpk_lt_i32 s5, 0x1000
	s_cbranch_scc1 .LBB0_1298
	s_cmpk_ge_i32 s5, 0x1200
	s_cbranch_scc1 .Lph8_done
	s_cmpk_le_i32 s2, 0x1000
	s_cbranch_scc1 .Lph8_done
	v_readlane_b32 s6, v209, 2
	s_cmpk_ge_u32 s6, 0x100
	s_cbranch_scc1 .Lph8_done
	s_and_b32 s7, s6, 7
	s_lshl_b32 s7, s7, 2
	s_lshr_b32 s6, s6, 3
	s_and_b32 s5, s6, 3
	s_or_b32 s7, s7, s5
	s_lshr_b32 s6, s6, 2
	s_lshl_b32 s6, s6, 5
	s_or_b32 s5, s6, s7
	s_addk_i32 s5, 0x1000
	s_lshl_b32 s4, s5, 7
	s_branch .LBB0_1298

.LBB0_1355:
	s_ashr_i32 s2, s7, 31
	s_lshr_b32 s2, s2, 29
	s_add_i32 s8, s7, s2
	s_ashr_i32 s2, s8, 3
	s_ashr_i32 s3, s2, 31
	v_readlane_b32 s36, v210, 50
	s_lshl_b64 s[4:5], s[2:3], 20
	v_readlane_b32 s50, v209, 0
	v_readlane_b32 s51, v209, 1
	s_add_u32 s4, s50, s4
	v_mov_b32_e32 v52, v133
	s_addc_u32 s5, s51, s5
	s_and_b32 s3, s8, 0x1fffff8
	s_sub_i32 s3, s7, s3
	v_ashrrev_i32_e32 v34, 3, v52
	v_ashrrev_i32_e32 v35, 31, v34
	s_lshl_b32 s8, s3, 7
	v_lshlrev_b64 v[2:3], 7, v[34:35]
	v_lshl_add_u64 v[134:135], s[4:5], 0, v[2:3]
	v_lshlrev_b32_e32 v0, 4, v52
	v_add_u32_e32 v2, s8, v34
	v_and_b32_e32 v0, 0x70, v0
	v_ashrrev_i32_e32 v3, 31, v2
	v_lshl_add_u64 v[36:37], v[134:135], 0, v[0:1]
	v_lshlrev_b64 v[2:3], 13, v[2:3]
	v_lshl_add_u64 v[136:137], s[0:1], 0, v[2:3]
	v_add_co_u32_e32 v18, vcc, s53, v36
	v_lshl_add_u64 v[38:39], v[136:137], 0, v[0:1]
	v_lshrrev_b32_e32 v232, 4, v133
	v_xor_b32_e32 v232, v232, v133
	v_and_b32_e32 v232, 7, v232
	v_lshlrev_b32_e32 v232, 4, v232
	v_mov_b32_e32 v233, 0x70
	v_lshrrev_b32_e32 v238, 6, v133
	v_lshlrev_b32_e32 v238, 10, v238
	s_nop 0
	v_readfirstlane_b32 s32, v238
	v_bfi_b32 v216, v233, v232, v36
	v_mov_b32_e32 v217, v37
	v_bfi_b32 v224, v233, v232, v38
	v_mov_b32_e32 v225, v39
	v_mov_b32_e32 v234, 0x1000
	v_mov_b32_e32 v235, 0
	v_mov_b32_e32 v236, 0x40000
	v_mov_b32_e32 v237, 0
	v_lshl_add_u64 v[218:219], v[234:235], 0, v[216:217]
	v_lshl_add_u64 v[220:221], v[234:235], 1, v[216:217]
	v_lshl_add_u64 v[222:223], v[234:235], 1, v[218:219]
	v_lshl_add_u64 v[226:227], v[236:237], 0, v[224:225]
	v_lshl_add_u64 v[228:229], v[236:237], 1, v[224:225]
	v_lshl_add_u64 v[230:231], v[236:237], 1, v[226:227]
	s_add_u32 m0, s32, 0x0
	s_nop 0
	global_load_lds_dwordx4 v[216:217], off
	s_add_u32 m0, s32, 0x1000
	v_lshl_add_u64 v[216:217], v[234:235], 2, v[216:217]
	global_load_lds_dwordx4 v[218:219], off
	s_add_u32 m0, s32, 0x2000
	v_lshl_add_u64 v[218:219], v[234:235], 2, v[218:219]
	global_load_lds_dwordx4 v[220:221], off
	s_add_u32 m0, s32, 0x3000
	v_lshl_add_u64 v[220:221], v[234:235], 2, v[220:221]
	global_load_lds_dwordx4 v[222:223], off
	s_add_u32 m0, s32, 0x8000
	v_lshl_add_u64 v[222:223], v[234:235], 2, v[222:223]
	global_load_lds_dwordx4 v[224:225], off
	s_add_u32 m0, s32, 0x9000
	v_lshl_add_u64 v[224:225], 32, 2, v[224:225]
	global_load_lds_dwordx4 v[226:227], off
	s_add_u32 m0, s32, 0xa000
	v_lshl_add_u64 v[226:227], 32, 2, v[226:227]
	global_load_lds_dwordx4 v[228:229], off
	s_add_u32 m0, s32, 0xb000
	v_lshl_add_u64 v[228:229], 32, 2, v[228:229]
	global_load_lds_dwordx4 v[230:231], off
	v_lshl_add_u64 v[230:231], 32, 2, v[230:231]
	s_add_u32 m0, s32, 0x4000
	s_nop 0
	global_load_lds_dwordx4 v[216:217], off
	s_add_u32 m0, s32, 0x5000
	v_lshl_add_u64 v[216:217], v[234:235], 2, v[216:217]
	global_load_lds_dwordx4 v[218:219], off
	s_add_u32 m0, s32, 0x6000
	v_lshl_add_u64 v[218:219], v[234:235], 2, v[218:219]
	global_load_lds_dwordx4 v[220:221], off
	s_add_u32 m0, s32, 0x7000
	v_lshl_add_u64 v[220:221], v[234:235], 2, v[220:221]
	global_load_lds_dwordx4 v[222:223], off
	s_add_u32 m0, s32, 0xc000
	v_lshl_add_u64 v[222:223], v[234:235], 2, v[222:223]
	global_load_lds_dwordx4 v[224:225], off
	s_add_u32 m0, s32, 0xd000
	v_lshl_add_u64 v[224:225], 32, 2, v[224:225]
	global_load_lds_dwordx4 v[226:227], off
	s_add_u32 m0, s32, 0xe000
	v_lshl_add_u64 v[226:227], 32, 2, v[226:227]
	global_load_lds_dwordx4 v[228:229], off
	s_add_u32 m0, s32, 0xf000
	v_lshl_add_u64 v[228:229], 32, 2, v[228:229]
	global_load_lds_dwordx4 v[230:231], off
	v_lshl_add_u64 v[230:231], 32, 2, v[230:231]
	s_nop 0
	v_addc_co_u32_e32 v19, vcc, 0, v37, vcc
	s_mov_b32 s3, 0x40000
	v_add_co_u32_e32 v40, vcc, s3, v38
	s_mov_b32 s3, 0x80000
	s_nop 0
	v_addc_co_u32_e32 v41, vcc, 0, v39, vcc
	v_add_co_u32_e32 v42, vcc, s3, v38
	s_nop 0
	v_addc_co_u32_e32 v43, vcc, 0, v39, vcc
	v_add_co_u32_e32 v44, vcc, s9, v36
	s_mov_b32 s3, 0xc0000
	s_nop 0
	v_addc_co_u32_e32 v45, vcc, 0, v37, vcc
	v_add_co_u32_e32 v46, vcc, s3, v38
	s_nop 0
	v_addc_co_u32_e32 v47, vcc, 0, v39, vcc
	v_lshlrev_b32_e32 v0, 7, v34
	v_lshrrev_b32_e32 v34, 1, v34
	v_xor_b32_e32 v34, v34, v52
	v_lshlrev_b32_e32 v34, 4, v34
	s_movk_i32 s4, 0x6000
	v_and_or_b32 v146, v34, s59, v0
	v_add_co_u32_e32 v34, vcc, s4, v36
	v_and_b32_e32 v142, 31, v52
	s_nop 0
	v_addc_co_u32_e32 v35, vcc, 0, v37, vcc
	v_add_co_u32_e32 v48, vcc, s10, v36
	v_ashrrev_i32_e32 v144, 7, v52
	s_nop 0
	v_addc_co_u32_e32 v49, vcc, 0, v37, vcc
	v_add_co_u32_e32 v50, vcc, s34, v36
	v_bfe_u32 v145, v52, 5, 1
	s_nop 0
	v_addc_co_u32_e32 v51, vcc, 0, v37, vcc
	v_bfe_u32 v143, v52, 6, 1
	v_lshlrev_b32_e32 v0, 7, v142
	v_lshl_or_b32 v147, v144, 13, v0
	v_lshl_or_b32 v149, v143, 13, v0
	s_mov_b32 s3, 0
	v_readlane_b32 s37, v210, 51
	v_readlane_b32 s38, v210, 52
	v_readlane_b32 s39, v210, 53
	v_readlane_b32 s40, v210, 54
	v_readlane_b32 s41, v210, 55
	v_readlane_b32 s42, v210, 56
	v_readlane_b32 s43, v210, 57
	v_readlane_b32 s44, v210, 58
	v_readlane_b32 s45, v210, 59
	v_readlane_b32 s46, v210, 60
	v_readlane_b32 s47, v210, 61
	v_readlane_b32 s48, v210, 62
	v_readlane_b32 s49, v210, 63
	v_add_co_u32_e32 v2, vcc, s52, v36
	s_waitcnt vmcnt(8)
	s_waitcnt lgkmcnt(0)
	s_barrier
	v_addc_co_u32_e32 v3, vcc, 0, v37, vcc
	v_bfe_u32 v3, v52, 1, 3
	v_bitop3_b32 v0, v145, v3, 2 bitop3:0x36
	v_lshrrev_b32_e32 v2, 1, v52
	v_lshlrev_b32_e32 v150, 4, v0
	v_bitop3_b32 v0, v145, v3, 4 bitop3:0x36
	v_bitop3_b32 v2, v2, v145, 7 bitop3:0x6c
	v_lshlrev_b32_e32 v151, 4, v0
	v_bitop3_b32 v0, v145, v3, 6 bitop3:0x36
	v_lshlrev_b32_e32 v148, 4, v2
	v_lshlrev_b32_e32 v152, 4, v0
	v_and_b32_e32 v0, 7, v52
	v_mov_b32_e32 v2, 0
	v_lshlrev_b32_e32 v0, 4, v0
	v_mov_b32_e32 v3, v2
	v_mov_b32_e32 v4, v2
	v_mov_b32_e32 v5, v2
	v_mov_b32_e32 v6, v2
	v_mov_b32_e32 v7, v2
	v_mov_b32_e32 v8, v2
	v_mov_b32_e32 v9, v2
	v_mov_b32_e32 v10, v2
	v_mov_b32_e32 v11, v2
	v_mov_b32_e32 v12, v2
	v_mov_b32_e32 v13, v2
	v_mov_b32_e32 v14, v2
	v_mov_b32_e32 v15, v2
	v_mov_b32_e32 v16, v2
	v_mov_b32_e32 v17, v2
	v_mov_b32_e32 v34, v2
	v_mov_b32_e32 v35, v2
	v_mov_b32_e32 v36, v2
	v_mov_b32_e32 v37, v2
	v_mov_b32_e32 v38, v2
	v_mov_b32_e32 v39, v2
	v_mov_b32_e32 v40, v2
	v_mov_b32_e32 v41, v2
	v_mov_b32_e32 v42, v2
	v_mov_b32_e32 v43, v2
	v_mov_b32_e32 v44, v2
	v_mov_b32_e32 v45, v2
	v_mov_b32_e32 v46, v2
	v_mov_b32_e32 v47, v2
	v_mov_b32_e32 v48, v2
	v_mov_b32_e32 v49, v2
	v_mov_b32_e32 v18, v2
	v_mov_b32_e32 v19, v2
	v_mov_b32_e32 v20, v2
	v_mov_b32_e32 v21, v2
	v_mov_b32_e32 v22, v2
	v_mov_b32_e32 v23, v2
	v_mov_b32_e32 v24, v2
	v_mov_b32_e32 v25, v2
	v_mov_b32_e32 v26, v2
	v_mov_b32_e32 v27, v2
	v_mov_b32_e32 v28, v2
	v_mov_b32_e32 v29, v2
	v_mov_b32_e32 v30, v2
	v_mov_b32_e32 v31, v2
	v_mov_b32_e32 v32, v2
	v_mov_b32_e32 v33, v2
	v_mov_b32_e32 v50, v2
	v_mov_b32_e32 v51, v2
	v_mov_b32_e32 v52, v2
	v_mov_b32_e32 v53, v2
	v_mov_b32_e32 v54, v2
	v_mov_b32_e32 v55, v2
	v_mov_b32_e32 v56, v2
	v_mov_b32_e32 v57, v2
	v_mov_b32_e32 v58, v2
	v_mov_b32_e32 v59, v2
	v_mov_b32_e32 v60, v2
	v_mov_b32_e32 v61, v2
	v_mov_b32_e32 v62, v2
	v_mov_b32_e32 v63, v2
	v_mov_b32_e32 v64, v2
	v_mov_b32_e32 v65, v2
	s_branch .LBB0_1357
.LBB0_1356:
	v_mfma_f32_32x32x16_bf16 v[50:65], v[186:189], v[194:197], v[50:65]
	v_mfma_f32_32x32x16_bf16 v[18:33], v[186:189], v[158:161], v[18:33]
	v_mfma_f32_32x32x16_bf16 v[34:49], v[190:193], v[194:197], v[34:49]
	v_mfma_f32_32x32x16_bf16 v[2:17], v[190:193], v[158:161], v[2:17]
	s_cmp_gt_u32 s3, 60
	s_cbranch_scc1 .Ldma9_skip_b
	s_add_u32 m0, s32, 0x4000
	s_nop 0
	global_load_lds_dwordx4 v[216:217], off
	s_add_u32 m0, s32, 0x5000
	v_lshl_add_u64 v[216:217], v[234:235], 2, v[216:217]
	global_load_lds_dwordx4 v[218:219], off
	s_add_u32 m0, s32, 0x6000
	v_lshl_add_u64 v[218:219], v[234:235], 2, v[218:219]
	global_load_lds_dwordx4 v[220:221], off
	s_add_u32 m0, s32, 0x7000
	v_lshl_add_u64 v[220:221], v[234:235], 2, v[220:221]
	global_load_lds_dwordx4 v[222:223], off
	s_add_u32 m0, s32, 0xc000
	v_lshl_add_u64 v[222:223], v[234:235], 2, v[222:223]
	global_load_lds_dwordx4 v[224:225], off
	s_add_u32 m0, s32, 0xd000
	v_lshl_add_u64 v[224:225], 32, 2, v[224:225]
	global_load_lds_dwordx4 v[226:227], off
	s_add_u32 m0, s32, 0xe000
	v_lshl_add_u64 v[226:227], 32, 2, v[226:227]
	global_load_lds_dwordx4 v[228:229], off
	s_add_u32 m0, s32, 0xf000
	v_lshl_add_u64 v[228:229], 32, 2, v[228:229]
	global_load_lds_dwordx4 v[230:231], off
	v_lshl_add_u64 v[230:231], 32, 2, v[230:231]
	s_waitcnt vmcnt(8)
	s_branch .Ldma9_join_b

.Ldma9_join_a:
	s_barrier
	ds_read_b128 v[162:165], v153 offset:16384
	ds_read_b128 v[166:169], v153 offset:20480
	ds_read_b128 v[182:185], v154 offset:49152
	ds_read_b128 v[186:189], v154 offset:53248
	ds_read_b128 v[190:193], v155 offset:16384
	ds_read_b128 v[194:197], v155 offset:20480
	ds_read_b128 v[198:201], v156 offset:49152
	ds_read_b128 v[202:205], v156 offset:53248
	s_waitcnt lgkmcnt(5)
	v_mfma_f32_32x32x16_bf16 v[50:65], v[162:165], v[182:185], v[50:65]
	s_waitcnt lgkmcnt(4)
	v_mfma_f32_32x32x16_bf16 v[18:33], v[162:165], v[186:189], v[18:33]
	v_mfma_f32_32x32x16_bf16 v[34:49], v[166:169], v[182:185], v[34:49]
	v_mfma_f32_32x32x16_bf16 v[2:17], v[166:169], v[186:189], v[2:17]
	ds_read_b128 v[162:165], v157 offset:16384
	ds_read_b128 v[154:157], v157 offset:20480
	ds_read_b128 v[166:169], v158 offset:49152
	ds_read_b128 v[182:185], v158 offset:53248
	s_waitcnt lgkmcnt(5)
	v_mfma_f32_32x32x16_bf16 v[50:65], v[190:193], v[198:201], v[50:65]
	s_waitcnt lgkmcnt(4)
	v_mfma_f32_32x32x16_bf16 v[18:33], v[190:193], v[202:205], v[18:33]
	v_mfma_f32_32x32x16_bf16 v[34:49], v[194:197], v[198:201], v[34:49]
	v_mfma_f32_32x32x16_bf16 v[2:17], v[194:197], v[202:205], v[2:17]
	ds_read_b128 v[186:189], v159 offset:16384
	ds_read_b128 v[190:193], v159 offset:20480
	ds_read_b128 v[194:197], v160 offset:49152
	ds_read_b128 v[158:161], v160 offset:53248
	s_waitcnt lgkmcnt(5)
	v_mfma_f32_32x32x16_bf16 v[50:65], v[162:165], v[166:169], v[50:65]
	s_cmp_gt_u32 s3, 61
	s_cselect_b64 s[4:5], -1, 0
	s_and_b64 vcc, exec, s[4:5]
	s_waitcnt lgkmcnt(4)
	v_mfma_f32_32x32x16_bf16 v[18:33], v[162:165], v[182:185], v[18:33]
	v_mfma_f32_32x32x16_bf16 v[34:49], v[154:157], v[166:169], v[34:49]
	v_mfma_f32_32x32x16_bf16 v[2:17], v[154:157], v[182:185], v[2:17]
	s_waitcnt lgkmcnt(1)
	s_waitcnt lgkmcnt(0)
	s_cbranch_vccnz .LBB0_1361
